# code placement: all 11 GEMM k-loop heads aligned to 64 bytes (padding after an unconditional branch, never executed)
# baseline (speedup 1.0000x reference)
.LBB0_504:
	s_mov_b32 s39, 0
	s_mov_b64 s[66:67], -1
	s_mov_b64 s[72:73], 0
	s_add_u32 s20, s62, s39
	s_addc_u32 s21, s63, 0
	s_add_u32 s22, s20, 0x100
	s_addc_u32 s23, s21, 0
	s_and_b64 s[18:19], s[72:73], exec
	s_cselect_b32 vcc_hi, s49, s23
	s_cselect_b32 vcc_lo, s48, s22
	s_add_u32 s18, s60, s39
	s_addc_u32 s19, s61, 0
	s_add_u32 s22, s18, 0x100
	s_addc_u32 s23, s19, 0
	s_add_i32 s24, 0, 0x10000
	s_and_b64 s[18:19], s[72:73], exec
	s_cselect_b32 s51, s59, s23
	s_cselect_b32 s50, s58, s22
	s_add_i32 s22, 0, 0x14000
	s_add_u32 s64, s20, 0x40080
	s_addc_u32 s65, s21, 0
	s_add_i32 s21, s24, s69
	s_add_i32 m0, s4, 0xc000
	s_add_i32 s25, s4, 0xe000
	s_add_i32 s18, s21, 0x2000
	s_add_u32 s78, s50, 0x10000
	v_add_u32_e32 v140, s24, v170
	v_add_u32_e32 v162, s22, v170
	s_addc_u32 s79, s51, 0
	s_add_i32 s19, s22, s69
	ds_read_b128 v[128:131], v140
	ds_read_b128 v[132:135], v140 offset:1024
	ds_read_b128 v[136:139], v140 offset:2048
	ds_read_b128 v[140:143], v140 offset:3072
	ds_read_b128 v[152:155], v162
	ds_read_b128 v[156:159], v162 offset:1024
	ds_read_b128 v[164:167], v162 offset:2048
	ds_read_b128 v[172:175], v162 offset:3072
	s_add_i32 s20, s19, 0x2000
	s_add_i32 s54, 0, 0x18000
	s_add_i32 s43, 0, 0x1c000
	s_add_u32 s74, vcc_lo, 0x40000
	s_addc_u32 s75, vcc_hi, 0
	s_add_i32 s41, s54, s69
	s_add_i32 s39, s41, 0x2000
	s_add_u32 s72, s50, 0x10080
	s_addc_u32 s73, s51, 0
	s_add_i32 s23, s43, s69
	s_add_i32 s22, s23, 0x2000
	v_lshl_add_u64 v[200:201], s[64:65], 0, v[150:151]
	ds_read_b128 v[176:179], v171
	ds_read_b128 v[180:183], v171 offset:1024
	ds_read_b128 v[184:187], v171 offset:2048
	ds_read_b128 v[188:191], v171 offset:3072
	ds_read_b128 v[192:195], v171 offset:4096
	ds_read_b128 v[196:199], v171 offset:5120
	ds_read_b128 v[206:209], v171 offset:6144
	ds_read_b128 v[210:213], v171 offset:7168
	global_load_lds_dwordx4 v[200:201], off
	v_lshl_add_u64 v[200:201], s[64:65], 0, v[146:147]
	s_mov_b32 m0, s25
	s_nop 0
	global_load_lds_dwordx4 v[200:201], off
	s_waitcnt vmcnt(8)
	s_waitcnt lgkmcnt(0)
	s_barrier
	s_setprio 1
	s_waitcnt lgkmcnt(0)
	v_mfma_f32_16x16x32_bf16 v[124:127], v[128:131], v[176:179], 0
	v_mfma_f32_16x16x32_bf16 v[120:123], v[136:139], v[176:179], 0
	v_mfma_f32_16x16x32_bf16 v[112:115], v[128:131], v[184:187], 0
	v_mfma_f32_16x16x32_bf16 v[104:107], v[136:139], v[184:187], 0
	v_mfma_f32_16x16x32_bf16 v[96:99], v[128:131], v[192:195], 0
	v_mfma_f32_16x16x32_bf16 v[88:91], v[136:139], v[192:195], 0
	v_mfma_f32_16x16x32_bf16 v[80:83], v[128:131], v[206:209], 0
	v_mfma_f32_16x16x32_bf16 v[72:75], v[136:139], v[206:209], 0
	v_mfma_f32_16x16x32_bf16 v[124:127], v[132:135], v[180:183], v[124:127]
	v_mfma_f32_16x16x32_bf16 v[120:123], v[140:143], v[180:183], v[120:123]
	v_mfma_f32_16x16x32_bf16 v[112:115], v[132:135], v[188:191], v[112:115]
	v_mfma_f32_16x16x32_bf16 v[104:107], v[140:143], v[188:191], v[104:107]
	v_mfma_f32_16x16x32_bf16 v[96:99], v[132:135], v[196:199], v[96:99]
	v_mfma_f32_16x16x32_bf16 v[88:91], v[140:143], v[196:199], v[88:91]
	v_mfma_f32_16x16x32_bf16 v[80:83], v[132:135], v[210:213], v[80:83]
	v_mfma_f32_16x16x32_bf16 v[72:75], v[140:143], v[210:213], v[72:75]
	s_setprio 0
	s_setprio 1
	v_mfma_f32_16x16x32_bf16 v[116:119], v[152:155], v[176:179], 0
	v_mfma_f32_16x16x32_bf16 v[108:111], v[164:167], v[176:179], 0
	v_mfma_f32_16x16x32_bf16 v[100:103], v[152:155], v[184:187], 0
	v_mfma_f32_16x16x32_bf16 v[92:95], v[164:167], v[184:187], 0
	v_mfma_f32_16x16x32_bf16 v[84:87], v[152:155], v[192:195], 0
	v_mfma_f32_16x16x32_bf16 v[76:79], v[164:167], v[192:195], 0
	v_mfma_f32_16x16x32_bf16 v[68:71], v[152:155], v[206:209], 0
	v_mfma_f32_16x16x32_bf16 v[64:67], v[164:167], v[206:209], 0
	v_mfma_f32_16x16x32_bf16 v[116:119], v[156:159], v[180:183], v[116:119]
	v_mfma_f32_16x16x32_bf16 v[108:111], v[172:175], v[180:183], v[108:111]
	v_mfma_f32_16x16x32_bf16 v[100:103], v[156:159], v[188:191], v[100:103]
	v_mfma_f32_16x16x32_bf16 v[92:95], v[172:175], v[188:191], v[92:95]
	v_mfma_f32_16x16x32_bf16 v[84:87], v[156:159], v[196:199], v[84:87]
	v_mfma_f32_16x16x32_bf16 v[76:79], v[172:175], v[196:199], v[76:79]
	v_mfma_f32_16x16x32_bf16 v[68:71], v[156:159], v[210:213], v[68:71]
	v_mfma_f32_16x16x32_bf16 v[64:67], v[172:175], v[210:213], v[64:67]
	s_setprio 0
	s_barrier
	s_mov_b32 m0, s21
	v_lshl_add_u64 v[200:201], s[50:51], 0, v[148:149]
	ds_read_b128 v[176:179], v171 offset:16384
	ds_read_b128 v[180:183], v171 offset:17408
	ds_read_b128 v[184:187], v171 offset:18432
	ds_read_b128 v[188:191], v171 offset:19456
	ds_read_b128 v[192:195], v171 offset:20480
	ds_read_b128 v[196:199], v171 offset:21504
	ds_read_b128 v[206:209], v171 offset:22528
	ds_read_b128 v[210:213], v171 offset:23552
	global_load_lds_dwordx4 v[200:201], off
	v_lshl_add_u64 v[214:215], s[50:51], 0, v[144:145]
	s_mov_b32 m0, s18
	v_lshl_add_u64 v[216:217], s[78:79], 0, v[148:149]
	global_load_lds_dwordx4 v[214:215], off
	s_mov_b32 m0, s19
	v_lshl_add_u64 v[218:219], vcc, 0, v[146:147]
	global_load_lds_dwordx4 v[216:217], off
	v_lshl_add_u64 v[216:217], s[78:79], 0, v[144:145]
	s_mov_b32 m0, s20
	s_nop 0
	global_load_lds_dwordx4 v[216:217], off
	v_lshl_add_u64 v[216:217], vcc, 0, v[150:151]
	s_mov_b32 m0, s4
	s_nop 0
	global_load_lds_dwordx4 v[216:217], off
	s_mov_b32 m0, s5
	s_nop 0
	global_load_lds_dwordx4 v[218:219], off
	s_waitcnt vmcnt(8)
	s_waitcnt lgkmcnt(0)
	s_barrier
	s_setprio 1
	s_waitcnt lgkmcnt(0)
	v_mfma_f32_16x16x32_bf16 v[60:63], v[128:131], v[176:179], 0
	v_mfma_f32_16x16x32_bf16 v[56:59], v[136:139], v[176:179], 0
	v_mfma_f32_16x16x32_bf16 v[48:51], v[128:131], v[184:187], 0
	v_mfma_f32_16x16x32_bf16 v[40:43], v[136:139], v[184:187], 0
	v_mfma_f32_16x16x32_bf16 v[32:35], v[128:131], v[192:195], 0
	v_mfma_f32_16x16x32_bf16 v[24:27], v[136:139], v[192:195], 0
	v_mfma_f32_16x16x32_bf16 v[16:19], v[128:131], v[206:209], 0
	v_mfma_f32_16x16x32_bf16 v[8:11], v[136:139], v[206:209], 0
	v_mfma_f32_16x16x32_bf16 v[60:63], v[132:135], v[180:183], v[60:63]
	v_mfma_f32_16x16x32_bf16 v[56:59], v[140:143], v[180:183], v[56:59]
	v_mfma_f32_16x16x32_bf16 v[48:51], v[132:135], v[188:191], v[48:51]
	v_mfma_f32_16x16x32_bf16 v[40:43], v[140:143], v[188:191], v[40:43]
	v_mfma_f32_16x16x32_bf16 v[32:35], v[132:135], v[196:199], v[32:35]
	v_mfma_f32_16x16x32_bf16 v[24:27], v[140:143], v[196:199], v[24:27]
	v_mfma_f32_16x16x32_bf16 v[16:19], v[132:135], v[210:213], v[16:19]
	v_mfma_f32_16x16x32_bf16 v[8:11], v[140:143], v[210:213], v[8:11]
	s_setprio 0
	s_setprio 1
	v_mfma_f32_16x16x32_bf16 v[52:55], v[152:155], v[176:179], 0
	v_mfma_f32_16x16x32_bf16 v[44:47], v[164:167], v[176:179], 0
	v_mfma_f32_16x16x32_bf16 v[36:39], v[152:155], v[184:187], 0
	v_mfma_f32_16x16x32_bf16 v[28:31], v[164:167], v[184:187], 0
	v_mfma_f32_16x16x32_bf16 v[20:23], v[152:155], v[192:195], 0
	v_mfma_f32_16x16x32_bf16 v[12:15], v[164:167], v[192:195], 0
	v_mfma_f32_16x16x32_bf16 v[4:7], v[152:155], v[206:209], 0
	v_mfma_f32_16x16x32_bf16 v[0:3], v[164:167], v[206:209], 0
	v_mfma_f32_16x16x32_bf16 v[52:55], v[156:159], v[180:183], v[52:55]
	v_mfma_f32_16x16x32_bf16 v[44:47], v[172:175], v[180:183], v[44:47]
	v_mfma_f32_16x16x32_bf16 v[36:39], v[156:159], v[188:191], v[36:39]
	v_mfma_f32_16x16x32_bf16 v[28:31], v[172:175], v[188:191], v[28:31]
	v_mfma_f32_16x16x32_bf16 v[20:23], v[156:159], v[196:199], v[20:23]
	v_mfma_f32_16x16x32_bf16 v[12:15], v[172:175], v[196:199], v[12:15]
	v_mfma_f32_16x16x32_bf16 v[4:7], v[156:159], v[210:213], v[4:7]
	v_mfma_f32_16x16x32_bf16 v[0:3], v[172:175], v[210:213], v[0:3]
	s_setprio 0
	s_barrier
	v_add_u32_e32 v140, s54, v170
	v_add_u32_e32 v162, s43, v170
	ds_read_b128 v[128:131], v140
	ds_read_b128 v[132:135], v140 offset:1024
	ds_read_b128 v[136:139], v140 offset:2048
	ds_read_b128 v[140:143], v140 offset:3072
	ds_read_b128 v[152:155], v162
	ds_read_b128 v[156:159], v162 offset:1024
	ds_read_b128 v[164:167], v162 offset:2048
	ds_read_b128 v[172:175], v162 offset:3072
	s_mov_b32 m0, s6
	v_lshl_add_u64 v[220:221], s[74:75], 0, v[150:151]
	ds_read_b128 v[176:179], v171 offset:32768
	ds_read_b128 v[180:183], v171 offset:33792
	ds_read_b128 v[184:187], v171 offset:34816
	ds_read_b128 v[188:191], v171 offset:35840
	ds_read_b128 v[192:195], v171 offset:36864
	ds_read_b128 v[196:199], v171 offset:37888
	ds_read_b128 v[206:209], v171 offset:38912
	ds_read_b128 v[210:213], v171 offset:39936
	global_load_lds_dwordx4 v[220:221], off
	v_lshl_add_u64 v[220:221], s[74:75], 0, v[146:147]
	s_mov_b32 m0, s7
	s_nop 0
	global_load_lds_dwordx4 v[220:221], off
	s_waitcnt vmcnt(8)
	s_waitcnt lgkmcnt(0)
	s_barrier
	s_setprio 1
	s_waitcnt lgkmcnt(0)
	v_mfma_f32_16x16x32_bf16 v[124:127], v[128:131], v[176:179], v[124:127]
	v_mfma_f32_16x16x32_bf16 v[120:123], v[136:139], v[176:179], v[120:123]
	v_mfma_f32_16x16x32_bf16 v[112:115], v[128:131], v[184:187], v[112:115]
	v_mfma_f32_16x16x32_bf16 v[104:107], v[136:139], v[184:187], v[104:107]
	v_mfma_f32_16x16x32_bf16 v[96:99], v[128:131], v[192:195], v[96:99]
	v_mfma_f32_16x16x32_bf16 v[88:91], v[136:139], v[192:195], v[88:91]
	v_mfma_f32_16x16x32_bf16 v[80:83], v[128:131], v[206:209], v[80:83]
	v_mfma_f32_16x16x32_bf16 v[72:75], v[136:139], v[206:209], v[72:75]
	v_mfma_f32_16x16x32_bf16 v[124:127], v[132:135], v[180:183], v[124:127]
	v_mfma_f32_16x16x32_bf16 v[120:123], v[140:143], v[180:183], v[120:123]
	v_mfma_f32_16x16x32_bf16 v[112:115], v[132:135], v[188:191], v[112:115]
	v_mfma_f32_16x16x32_bf16 v[104:107], v[140:143], v[188:191], v[104:107]
	v_mfma_f32_16x16x32_bf16 v[96:99], v[132:135], v[196:199], v[96:99]
	v_mfma_f32_16x16x32_bf16 v[88:91], v[140:143], v[196:199], v[88:91]
	v_mfma_f32_16x16x32_bf16 v[80:83], v[132:135], v[210:213], v[80:83]
	v_mfma_f32_16x16x32_bf16 v[72:75], v[140:143], v[210:213], v[72:75]
	s_setprio 0
	s_setprio 1
	v_mfma_f32_16x16x32_bf16 v[116:119], v[152:155], v[176:179], v[116:119]
	v_mfma_f32_16x16x32_bf16 v[108:111], v[164:167], v[176:179], v[108:111]
	v_mfma_f32_16x16x32_bf16 v[100:103], v[152:155], v[184:187], v[100:103]
	v_mfma_f32_16x16x32_bf16 v[92:95], v[164:167], v[184:187], v[92:95]
	v_mfma_f32_16x16x32_bf16 v[84:87], v[152:155], v[192:195], v[84:87]
	v_mfma_f32_16x16x32_bf16 v[76:79], v[164:167], v[192:195], v[76:79]
	v_mfma_f32_16x16x32_bf16 v[68:71], v[152:155], v[206:209], v[68:71]
	v_mfma_f32_16x16x32_bf16 v[64:67], v[164:167], v[206:209], v[64:67]
	v_mfma_f32_16x16x32_bf16 v[116:119], v[156:159], v[180:183], v[116:119]
	v_mfma_f32_16x16x32_bf16 v[108:111], v[172:175], v[180:183], v[108:111]
	v_mfma_f32_16x16x32_bf16 v[100:103], v[156:159], v[188:191], v[100:103]
	v_mfma_f32_16x16x32_bf16 v[92:95], v[172:175], v[188:191], v[92:95]
	v_mfma_f32_16x16x32_bf16 v[84:87], v[156:159], v[196:199], v[84:87]
	v_mfma_f32_16x16x32_bf16 v[76:79], v[172:175], v[196:199], v[76:79]
	v_mfma_f32_16x16x32_bf16 v[68:71], v[156:159], v[210:213], v[68:71]
	v_mfma_f32_16x16x32_bf16 v[64:67], v[172:175], v[210:213], v[64:67]
	s_setprio 0
	s_barrier
	s_mov_b32 m0, s41
	v_lshl_add_u64 v[200:201], v[200:201], 0, s[76:77]
	ds_read_b128 v[176:179], v171 offset:49152
	ds_read_b128 v[180:183], v171 offset:50176
	ds_read_b128 v[184:187], v171 offset:51200
	ds_read_b128 v[188:191], v171 offset:52224
	ds_read_b128 v[192:195], v171 offset:53248
	ds_read_b128 v[196:199], v171 offset:54272
	ds_read_b128 v[206:209], v171 offset:55296
	ds_read_b128 v[210:213], v171 offset:56320
	global_load_lds_dwordx4 v[200:201], off
	v_lshl_add_u64 v[200:201], v[214:215], 0, s[76:77]
	s_mov_b32 m0, s39
	s_nop 0
	global_load_lds_dwordx4 v[200:201], off
	v_lshl_add_u64 v[200:201], s[72:73], 0, v[148:149]
	s_mov_b32 m0, s23
	s_nop 0
	global_load_lds_dwordx4 v[200:201], off
	v_lshl_add_u64 v[200:201], s[72:73], 0, v[144:145]
	s_mov_b32 m0, s22
	s_nop 0
	global_load_lds_dwordx4 v[200:201], off
	v_lshl_add_u64 v[200:201], v[216:217], 0, s[76:77]
	s_mov_b32 m0, s11
	s_nop 0
	global_load_lds_dwordx4 v[200:201], off
	v_lshl_add_u64 v[200:201], v[218:219], 0, s[76:77]
	s_mov_b32 m0, s12
	s_nop 0
	global_load_lds_dwordx4 v[200:201], off
	s_waitcnt vmcnt(8)
	s_waitcnt lgkmcnt(0)
	s_barrier
	s_setprio 1
	s_waitcnt lgkmcnt(0)
	v_mfma_f32_16x16x32_bf16 v[60:63], v[128:131], v[176:179], v[60:63]
	v_mfma_f32_16x16x32_bf16 v[56:59], v[136:139], v[176:179], v[56:59]
	v_mfma_f32_16x16x32_bf16 v[48:51], v[128:131], v[184:187], v[48:51]
	v_mfma_f32_16x16x32_bf16 v[40:43], v[136:139], v[184:187], v[40:43]
	v_mfma_f32_16x16x32_bf16 v[32:35], v[128:131], v[192:195], v[32:35]
	v_mfma_f32_16x16x32_bf16 v[24:27], v[136:139], v[192:195], v[24:27]
	v_mfma_f32_16x16x32_bf16 v[16:19], v[128:131], v[206:209], v[16:19]
	v_mfma_f32_16x16x32_bf16 v[8:11], v[136:139], v[206:209], v[8:11]
	v_mfma_f32_16x16x32_bf16 v[60:63], v[132:135], v[180:183], v[60:63]
	v_mfma_f32_16x16x32_bf16 v[56:59], v[140:143], v[180:183], v[56:59]
	v_mfma_f32_16x16x32_bf16 v[48:51], v[132:135], v[188:191], v[48:51]
	v_mfma_f32_16x16x32_bf16 v[40:43], v[140:143], v[188:191], v[40:43]
	v_mfma_f32_16x16x32_bf16 v[32:35], v[132:135], v[196:199], v[32:35]
	v_mfma_f32_16x16x32_bf16 v[24:27], v[140:143], v[196:199], v[24:27]
	v_mfma_f32_16x16x32_bf16 v[16:19], v[132:135], v[210:213], v[16:19]
	v_mfma_f32_16x16x32_bf16 v[8:11], v[140:143], v[210:213], v[8:11]
	s_setprio 0
	s_setprio 1
	v_mfma_f32_16x16x32_bf16 v[52:55], v[152:155], v[176:179], v[52:55]
	v_mfma_f32_16x16x32_bf16 v[44:47], v[164:167], v[176:179], v[44:47]
	v_mfma_f32_16x16x32_bf16 v[36:39], v[152:155], v[184:187], v[36:39]
	v_mfma_f32_16x16x32_bf16 v[28:31], v[164:167], v[184:187], v[28:31]
	v_mfma_f32_16x16x32_bf16 v[20:23], v[152:155], v[192:195], v[20:23]
	v_mfma_f32_16x16x32_bf16 v[12:15], v[164:167], v[192:195], v[12:15]
	v_mfma_f32_16x16x32_bf16 v[4:7], v[152:155], v[206:209], v[4:7]
	v_mfma_f32_16x16x32_bf16 v[0:3], v[164:167], v[206:209], v[0:3]
	v_mfma_f32_16x16x32_bf16 v[52:55], v[156:159], v[180:183], v[52:55]
	v_mfma_f32_16x16x32_bf16 v[44:47], v[172:175], v[180:183], v[44:47]
	v_mfma_f32_16x16x32_bf16 v[36:39], v[156:159], v[188:191], v[36:39]
	v_mfma_f32_16x16x32_bf16 v[28:31], v[172:175], v[188:191], v[28:31]
	v_mfma_f32_16x16x32_bf16 v[20:23], v[156:159], v[196:199], v[20:23]
	v_mfma_f32_16x16x32_bf16 v[12:15], v[172:175], v[196:199], v[12:15]
	v_mfma_f32_16x16x32_bf16 v[4:7], v[156:159], v[210:213], v[4:7]
	v_mfma_f32_16x16x32_bf16 v[0:3], v[172:175], v[210:213], v[0:3]
	s_setprio 0
	s_barrier
	s_movk_i32 s39, 0x100
	s_andn2_b64 vcc, exec, s[66:67]
	s_mov_b64 s[72:73], -1
	s_mov_b64 s[66:67], 0
	s_cbranch_vccz .LBB0_505
	s_branch .Lpeel_x_505
	.p2align 6

.LBB0_649:
	s_ashr_i32 s59, s58, 31
	s_lshl_b64 s[6:7], s[58:59], 19
	s_add_u32 s62, s96, s6
	s_addc_u32 s63, s97, s7
	s_and_b64 s[6:7], s[72:73], exec
	s_cselect_b32 s6, s63, s39
	s_cselect_b32 s7, s62, s38
	s_ashr_i32 s61, s60, 31
	s_lshl_b64 s[8:9], s[60:61], 19
	s_add_u32 s74, s50, s8
	s_addc_u32 s75, s51, s9
	s_and_b64 s[8:9], s[72:73], exec
	s_cselect_b32 s8, s75, s41
	s_cselect_b32 s9, s74, s40
	s_add_u32 s38, s38, 0x40080
	s_addc_u32 s39, s39, 0
	s_add_u32 s10, s40, 0x100
	s_addc_u32 s11, s41, 0
	s_mov_b32 s12, -2
	s_add_u32 s13, s38, 0xfffc0080
	s_addc_u32 s14, s39, -1
	s_add_i32 s15, 0, 0x10000
	s_cmp_eq_u32 s12, 12
	s_cselect_b32 s43, s6, s14
	s_cselect_b32 s42, s7, s13
	s_cselect_b32 s41, s8, s11
	s_cselect_b32 s40, s9, s10
	s_add_i32 s13, 0, 0x14000
	v_add_u32_e32 v140, s15, v181
	v_add_u32_e32 v156, s13, v181
	ds_read_b128 v[128:131], v140
	ds_read_b128 v[132:135], v140 offset:1024
	ds_read_b128 v[136:139], v140 offset:2048
	ds_read_b128 v[140:143], v140 offset:3072
	ds_read_b128 v[144:147], v156
	ds_read_b128 v[148:151], v156 offset:1024
	ds_read_b128 v[152:155], v156 offset:2048
	ds_read_b128 v[156:159], v156 offset:3072
	v_lshl_add_u64 v[178:179], s[38:39], 0, v[174:175]
	s_add_i32 m0, s66, 0xc000
	ds_read_b128 v[186:189], v185
	ds_read_b128 v[190:193], v185 offset:1024
	ds_read_b128 v[194:197], v185 offset:2048
	ds_read_b128 v[198:201], v185 offset:3072
	ds_read_b128 v[206:209], v185 offset:4096
	ds_read_b128 v[210:213], v185 offset:5120
	ds_read_b128 v[214:217], v185 offset:6144
	ds_read_b128 v[218:221], v185 offset:7168
	global_load_lds_dwordx4 v[178:179], off
	v_lshl_add_u64 v[178:179], s[38:39], 0, v[176:177]
	s_add_i32 m0, s66, 0xe000
	s_nop 0
	global_load_lds_dwordx4 v[178:179], off
	s_waitcnt vmcnt(8)
	s_waitcnt lgkmcnt(0)
	s_barrier
	s_setprio 1
	s_waitcnt lgkmcnt(0)
	v_mfma_f32_16x16x32_bf16 v[120:123], v[128:131], v[186:189], 0
	v_mfma_f32_16x16x32_bf16 v[124:127], v[136:139], v[186:189], 0
	v_mfma_f32_16x16x32_bf16 v[104:107], v[128:131], v[194:197], 0
	v_mfma_f32_16x16x32_bf16 v[108:111], v[136:139], v[194:197], 0
	v_mfma_f32_16x16x32_bf16 v[88:91], v[128:131], v[206:209], 0
	v_mfma_f32_16x16x32_bf16 v[92:95], v[136:139], v[206:209], 0
	v_mfma_f32_16x16x32_bf16 v[72:75], v[128:131], v[214:217], 0
	v_mfma_f32_16x16x32_bf16 v[76:79], v[136:139], v[214:217], 0
	v_mfma_f32_16x16x32_bf16 v[120:123], v[132:135], v[190:193], v[120:123]
	v_mfma_f32_16x16x32_bf16 v[124:127], v[140:143], v[190:193], v[124:127]
	v_mfma_f32_16x16x32_bf16 v[104:107], v[132:135], v[198:201], v[104:107]
	v_mfma_f32_16x16x32_bf16 v[108:111], v[140:143], v[198:201], v[108:111]
	v_mfma_f32_16x16x32_bf16 v[88:91], v[132:135], v[210:213], v[88:91]
	v_mfma_f32_16x16x32_bf16 v[92:95], v[140:143], v[210:213], v[92:95]
	v_mfma_f32_16x16x32_bf16 v[72:75], v[132:135], v[218:221], v[72:75]
	v_mfma_f32_16x16x32_bf16 v[76:79], v[140:143], v[218:221], v[76:79]
	s_setprio 0
	s_setprio 1
	v_mfma_f32_16x16x32_bf16 v[116:119], v[144:147], v[186:189], 0
	v_mfma_f32_16x16x32_bf16 v[112:115], v[152:155], v[186:189], 0
	v_mfma_f32_16x16x32_bf16 v[100:103], v[144:147], v[194:197], 0
	v_mfma_f32_16x16x32_bf16 v[96:99], v[152:155], v[194:197], 0
	v_mfma_f32_16x16x32_bf16 v[84:87], v[144:147], v[206:209], 0
	v_mfma_f32_16x16x32_bf16 v[80:83], v[152:155], v[206:209], 0
	v_mfma_f32_16x16x32_bf16 v[68:71], v[144:147], v[214:217], 0
	v_mfma_f32_16x16x32_bf16 v[64:67], v[152:155], v[214:217], 0
	v_mfma_f32_16x16x32_bf16 v[116:119], v[148:151], v[190:193], v[116:119]
	v_mfma_f32_16x16x32_bf16 v[112:115], v[156:159], v[190:193], v[112:115]
	v_mfma_f32_16x16x32_bf16 v[100:103], v[148:151], v[198:201], v[100:103]
	v_mfma_f32_16x16x32_bf16 v[96:99], v[156:159], v[198:201], v[96:99]
	v_mfma_f32_16x16x32_bf16 v[84:87], v[148:151], v[210:213], v[84:87]
	v_mfma_f32_16x16x32_bf16 v[80:83], v[156:159], v[210:213], v[80:83]
	v_mfma_f32_16x16x32_bf16 v[68:71], v[148:151], v[218:221], v[68:71]
	v_mfma_f32_16x16x32_bf16 v[64:67], v[156:159], v[218:221], v[64:67]
	s_setprio 0
	s_barrier
	s_add_i32 s14, s15, s65
	v_lshl_add_u64 v[178:179], s[40:41], 0, v[168:169]
	s_mov_b32 m0, s14
	ds_read_b128 v[186:189], v185 offset:16384
	ds_read_b128 v[190:193], v185 offset:17408
	ds_read_b128 v[194:197], v185 offset:18432
	ds_read_b128 v[198:201], v185 offset:19456
	ds_read_b128 v[206:209], v185 offset:20480
	ds_read_b128 v[210:213], v185 offset:21504
	ds_read_b128 v[214:217], v185 offset:22528
	ds_read_b128 v[218:221], v185 offset:23552
	global_load_lds_dwordx4 v[178:179], off
	s_add_i32 m0, s14, 0x2000
	s_add_u32 s14, s40, 0x40000
	v_lshl_add_u64 v[222:223], s[40:41], 0, v[164:165]
	s_addc_u32 s15, s41, 0
	s_add_i32 s13, s13, s65
	global_load_lds_dwordx4 v[222:223], off
	v_lshl_add_u64 v[224:225], s[14:15], 0, v[168:169]
	s_mov_b32 m0, s13
	v_lshl_add_u64 v[226:227], s[42:43], 0, v[166:167]
	global_load_lds_dwordx4 v[224:225], off
	v_lshl_add_u64 v[224:225], s[14:15], 0, v[164:165]
	s_add_i32 m0, s13, 0x2000
	s_nop 0
	global_load_lds_dwordx4 v[224:225], off
	v_lshl_add_u64 v[224:225], s[42:43], 0, v[170:171]
	s_mov_b32 m0, s66
	s_nop 0
	global_load_lds_dwordx4 v[224:225], off
	s_mov_b32 m0, s67
	s_nop 0
	global_load_lds_dwordx4 v[226:227], off
	s_waitcnt vmcnt(8)
	s_waitcnt lgkmcnt(0)
	s_barrier
	s_setprio 1
	s_waitcnt lgkmcnt(0)
	v_mfma_f32_16x16x32_bf16 v[56:59], v[128:131], v[186:189], 0
	v_mfma_f32_16x16x32_bf16 v[60:63], v[136:139], v[186:189], 0
	v_mfma_f32_16x16x32_bf16 v[40:43], v[128:131], v[194:197], 0
	v_mfma_f32_16x16x32_bf16 v[44:47], v[136:139], v[194:197], 0
	v_mfma_f32_16x16x32_bf16 v[24:27], v[128:131], v[206:209], 0
	v_mfma_f32_16x16x32_bf16 v[28:31], v[136:139], v[206:209], 0
	v_mfma_f32_16x16x32_bf16 v[8:11], v[128:131], v[214:217], 0
	v_mfma_f32_16x16x32_bf16 v[12:15], v[136:139], v[214:217], 0
	v_mfma_f32_16x16x32_bf16 v[56:59], v[132:135], v[190:193], v[56:59]
	v_mfma_f32_16x16x32_bf16 v[60:63], v[140:143], v[190:193], v[60:63]
	v_mfma_f32_16x16x32_bf16 v[40:43], v[132:135], v[198:201], v[40:43]
	v_mfma_f32_16x16x32_bf16 v[44:47], v[140:143], v[198:201], v[44:47]
	v_mfma_f32_16x16x32_bf16 v[24:27], v[132:135], v[210:213], v[24:27]
	v_mfma_f32_16x16x32_bf16 v[28:31], v[140:143], v[210:213], v[28:31]
	v_mfma_f32_16x16x32_bf16 v[8:11], v[132:135], v[218:221], v[8:11]
	v_mfma_f32_16x16x32_bf16 v[12:15], v[140:143], v[218:221], v[12:15]
	s_setprio 0
	s_setprio 1
	v_mfma_f32_16x16x32_bf16 v[52:55], v[144:147], v[186:189], 0
	v_mfma_f32_16x16x32_bf16 v[48:51], v[152:155], v[186:189], 0
	v_mfma_f32_16x16x32_bf16 v[36:39], v[144:147], v[194:197], 0
	v_mfma_f32_16x16x32_bf16 v[32:35], v[152:155], v[194:197], 0
	v_mfma_f32_16x16x32_bf16 v[20:23], v[144:147], v[206:209], 0
	v_mfma_f32_16x16x32_bf16 v[16:19], v[152:155], v[206:209], 0
	v_mfma_f32_16x16x32_bf16 v[4:7], v[144:147], v[214:217], 0
	v_mfma_f32_16x16x32_bf16 v[0:3], v[152:155], v[214:217], 0
	v_mfma_f32_16x16x32_bf16 v[52:55], v[148:151], v[190:193], v[52:55]
	v_mfma_f32_16x16x32_bf16 v[48:51], v[156:159], v[190:193], v[48:51]
	v_mfma_f32_16x16x32_bf16 v[36:39], v[148:151], v[198:201], v[36:39]
	v_mfma_f32_16x16x32_bf16 v[32:35], v[156:159], v[198:201], v[32:35]
	v_mfma_f32_16x16x32_bf16 v[20:23], v[148:151], v[210:213], v[20:23]
	v_mfma_f32_16x16x32_bf16 v[16:19], v[156:159], v[210:213], v[16:19]
	v_mfma_f32_16x16x32_bf16 v[4:7], v[148:151], v[218:221], v[4:7]
	v_mfma_f32_16x16x32_bf16 v[0:3], v[156:159], v[218:221], v[0:3]
	s_setprio 0
	s_barrier
	s_add_i32 s13, 0, 0x18000
	s_add_i32 s16, 0, 0x1c000
	v_add_u32_e32 v140, s13, v181
	v_add_u32_e32 v156, s16, v181
	ds_read_b128 v[128:131], v140
	ds_read_b128 v[132:135], v140 offset:1024
	ds_read_b128 v[136:139], v140 offset:2048
	ds_read_b128 v[140:143], v140 offset:3072
	ds_read_b128 v[144:147], v156
	ds_read_b128 v[148:151], v156 offset:1024
	ds_read_b128 v[152:155], v156 offset:2048
	ds_read_b128 v[156:159], v156 offset:3072
	s_add_u32 s14, s42, 0x40000
	s_addc_u32 s15, s43, 0
	s_mov_b32 m0, s68
	v_lshl_add_u64 v[228:229], s[14:15], 0, v[170:171]
	ds_read_b128 v[186:189], v185 offset:32768
	ds_read_b128 v[190:193], v185 offset:33792
	ds_read_b128 v[194:197], v185 offset:34816
	ds_read_b128 v[198:201], v185 offset:35840
	ds_read_b128 v[206:209], v185 offset:36864
	ds_read_b128 v[210:213], v185 offset:37888
	ds_read_b128 v[214:217], v185 offset:38912
	ds_read_b128 v[218:221], v185 offset:39936
	global_load_lds_dwordx4 v[228:229], off
	v_lshl_add_u64 v[228:229], s[14:15], 0, v[166:167]
	s_mov_b32 m0, s69
	s_nop 0
	global_load_lds_dwordx4 v[228:229], off
	s_waitcnt vmcnt(8)
	s_waitcnt lgkmcnt(0)
	s_barrier
	s_setprio 1
	s_waitcnt lgkmcnt(0)
	v_mfma_f32_16x16x32_bf16 v[120:123], v[128:131], v[186:189], v[120:123]
	v_mfma_f32_16x16x32_bf16 v[124:127], v[136:139], v[186:189], v[124:127]
	v_mfma_f32_16x16x32_bf16 v[104:107], v[128:131], v[194:197], v[104:107]
	v_mfma_f32_16x16x32_bf16 v[108:111], v[136:139], v[194:197], v[108:111]
	v_mfma_f32_16x16x32_bf16 v[88:91], v[128:131], v[206:209], v[88:91]
	v_mfma_f32_16x16x32_bf16 v[92:95], v[136:139], v[206:209], v[92:95]
	v_mfma_f32_16x16x32_bf16 v[72:75], v[128:131], v[214:217], v[72:75]
	v_mfma_f32_16x16x32_bf16 v[76:79], v[136:139], v[214:217], v[76:79]
	v_mfma_f32_16x16x32_bf16 v[120:123], v[132:135], v[190:193], v[120:123]
	v_mfma_f32_16x16x32_bf16 v[124:127], v[140:143], v[190:193], v[124:127]
	v_mfma_f32_16x16x32_bf16 v[104:107], v[132:135], v[198:201], v[104:107]
	v_mfma_f32_16x16x32_bf16 v[108:111], v[140:143], v[198:201], v[108:111]
	v_mfma_f32_16x16x32_bf16 v[88:91], v[132:135], v[210:213], v[88:91]
	v_mfma_f32_16x16x32_bf16 v[92:95], v[140:143], v[210:213], v[92:95]
	v_mfma_f32_16x16x32_bf16 v[72:75], v[132:135], v[218:221], v[72:75]
	v_mfma_f32_16x16x32_bf16 v[76:79], v[140:143], v[218:221], v[76:79]
	s_setprio 0
	s_setprio 1
	v_mfma_f32_16x16x32_bf16 v[116:119], v[144:147], v[186:189], v[116:119]
	v_mfma_f32_16x16x32_bf16 v[112:115], v[152:155], v[186:189], v[112:115]
	v_mfma_f32_16x16x32_bf16 v[100:103], v[144:147], v[194:197], v[100:103]
	v_mfma_f32_16x16x32_bf16 v[96:99], v[152:155], v[194:197], v[96:99]
	v_mfma_f32_16x16x32_bf16 v[84:87], v[144:147], v[206:209], v[84:87]
	v_mfma_f32_16x16x32_bf16 v[80:83], v[152:155], v[206:209], v[80:83]
	v_mfma_f32_16x16x32_bf16 v[68:71], v[144:147], v[214:217], v[68:71]
	v_mfma_f32_16x16x32_bf16 v[64:67], v[152:155], v[214:217], v[64:67]
	v_mfma_f32_16x16x32_bf16 v[116:119], v[148:151], v[190:193], v[116:119]
	v_mfma_f32_16x16x32_bf16 v[112:115], v[156:159], v[190:193], v[112:115]
	v_mfma_f32_16x16x32_bf16 v[100:103], v[148:151], v[198:201], v[100:103]
	v_mfma_f32_16x16x32_bf16 v[96:99], v[156:159], v[198:201], v[96:99]
	v_mfma_f32_16x16x32_bf16 v[84:87], v[148:151], v[210:213], v[84:87]
	v_mfma_f32_16x16x32_bf16 v[80:83], v[156:159], v[210:213], v[80:83]
	v_mfma_f32_16x16x32_bf16 v[68:71], v[148:151], v[218:221], v[68:71]
	v_mfma_f32_16x16x32_bf16 v[64:67], v[156:159], v[218:221], v[64:67]
	s_setprio 0
	s_barrier
	s_add_i32 s13, s13, s65
	v_lshl_add_u64 v[178:179], v[178:179], 0, s[76:77]
	s_mov_b32 m0, s13
	ds_read_b128 v[186:189], v185 offset:49152
	ds_read_b128 v[190:193], v185 offset:50176
	ds_read_b128 v[194:197], v185 offset:51200
	ds_read_b128 v[198:201], v185 offset:52224
	ds_read_b128 v[206:209], v185 offset:53248
	ds_read_b128 v[210:213], v185 offset:54272
	ds_read_b128 v[214:217], v185 offset:55296
	ds_read_b128 v[218:221], v185 offset:56320
	global_load_lds_dwordx4 v[178:179], off
	s_add_i32 m0, s13, 0x2000
	s_add_u32 s14, s40, 0x40080
	v_lshl_add_u64 v[178:179], v[222:223], 0, s[76:77]
	s_addc_u32 s15, s41, 0
	s_add_i32 s13, s16, s65
	global_load_lds_dwordx4 v[178:179], off
	v_lshl_add_u64 v[178:179], s[14:15], 0, v[168:169]
	s_mov_b32 m0, s13
	s_nop 0
	global_load_lds_dwordx4 v[178:179], off
	v_lshl_add_u64 v[178:179], s[14:15], 0, v[164:165]
	s_add_i32 m0, s13, 0x2000
	s_nop 0
	global_load_lds_dwordx4 v[178:179], off
	v_lshl_add_u64 v[178:179], v[224:225], 0, s[76:77]
	s_mov_b32 m0, s79
	s_nop 0
	global_load_lds_dwordx4 v[178:179], off
	v_lshl_add_u64 v[178:179], v[226:227], 0, s[76:77]
	s_mov_b32 m0, s46
	s_nop 0
	global_load_lds_dwordx4 v[178:179], off
	s_waitcnt vmcnt(8)
	s_waitcnt lgkmcnt(0)
	s_barrier
	s_setprio 1
	s_waitcnt lgkmcnt(0)
	v_mfma_f32_16x16x32_bf16 v[56:59], v[128:131], v[186:189], v[56:59]
	v_mfma_f32_16x16x32_bf16 v[60:63], v[136:139], v[186:189], v[60:63]
	v_mfma_f32_16x16x32_bf16 v[40:43], v[128:131], v[194:197], v[40:43]
	v_mfma_f32_16x16x32_bf16 v[44:47], v[136:139], v[194:197], v[44:47]
	v_mfma_f32_16x16x32_bf16 v[24:27], v[128:131], v[206:209], v[24:27]
	v_mfma_f32_16x16x32_bf16 v[28:31], v[136:139], v[206:209], v[28:31]
	v_mfma_f32_16x16x32_bf16 v[8:11], v[128:131], v[214:217], v[8:11]
	v_mfma_f32_16x16x32_bf16 v[12:15], v[136:139], v[214:217], v[12:15]
	v_mfma_f32_16x16x32_bf16 v[56:59], v[132:135], v[190:193], v[56:59]
	v_mfma_f32_16x16x32_bf16 v[60:63], v[140:143], v[190:193], v[60:63]
	v_mfma_f32_16x16x32_bf16 v[40:43], v[132:135], v[198:201], v[40:43]
	v_mfma_f32_16x16x32_bf16 v[44:47], v[140:143], v[198:201], v[44:47]
	v_mfma_f32_16x16x32_bf16 v[24:27], v[132:135], v[210:213], v[24:27]
	v_mfma_f32_16x16x32_bf16 v[28:31], v[140:143], v[210:213], v[28:31]
	v_mfma_f32_16x16x32_bf16 v[8:11], v[132:135], v[218:221], v[8:11]
	v_mfma_f32_16x16x32_bf16 v[12:15], v[140:143], v[218:221], v[12:15]
	s_setprio 0
	s_setprio 1
	v_mfma_f32_16x16x32_bf16 v[52:55], v[144:147], v[186:189], v[52:55]
	v_mfma_f32_16x16x32_bf16 v[48:51], v[152:155], v[186:189], v[48:51]
	v_mfma_f32_16x16x32_bf16 v[36:39], v[144:147], v[194:197], v[36:39]
	v_mfma_f32_16x16x32_bf16 v[32:35], v[152:155], v[194:197], v[32:35]
	v_mfma_f32_16x16x32_bf16 v[20:23], v[144:147], v[206:209], v[20:23]
	v_mfma_f32_16x16x32_bf16 v[16:19], v[152:155], v[206:209], v[16:19]
	v_mfma_f32_16x16x32_bf16 v[4:7], v[144:147], v[214:217], v[4:7]
	v_mfma_f32_16x16x32_bf16 v[0:3], v[152:155], v[214:217], v[0:3]
	v_mfma_f32_16x16x32_bf16 v[52:55], v[148:151], v[190:193], v[52:55]
	v_mfma_f32_16x16x32_bf16 v[48:51], v[156:159], v[190:193], v[48:51]
	v_mfma_f32_16x16x32_bf16 v[36:39], v[148:151], v[198:201], v[36:39]
	v_mfma_f32_16x16x32_bf16 v[32:35], v[156:159], v[198:201], v[32:35]
	v_mfma_f32_16x16x32_bf16 v[20:23], v[148:151], v[210:213], v[20:23]
	v_mfma_f32_16x16x32_bf16 v[16:19], v[156:159], v[210:213], v[16:19]
	v_mfma_f32_16x16x32_bf16 v[4:7], v[148:151], v[218:221], v[4:7]
	v_mfma_f32_16x16x32_bf16 v[0:3], v[156:159], v[218:221], v[0:3]
	s_setprio 0
	s_barrier
	s_add_i32 s12, s12, 2
	s_add_u32 s38, s38, 0x100
	s_addc_u32 s39, s39, 0
	s_add_u32 s10, s10, 0x100
	s_addc_u32 s11, s11, 0
	s_cmp_gt_u32 s12, 13
	s_cbranch_scc0 .LBB0_650
	s_branch .Lpeel_x_650
	.p2align 6

.LBB0_698:
	s_ashr_i32 s39, s38, 31
	s_lshl_b64 s[16:17], s[38:39], 19
	s_add_u32 s42, s4, s16
	s_addc_u32 s43, s5, s17
	s_and_b64 s[16:17], s[48:49], exec
	s_cselect_b32 s16, s43, s63
	s_cselect_b32 s17, s42, s62
	s_ashr_i32 s41, s40, 31
	s_lshl_b64 s[18:19], s[40:41], 19
	s_add_u32 s58, s96, s18
	s_addc_u32 s59, s97, s19
	s_and_b64 s[18:19], s[48:49], exec
	s_cselect_b32 s39, s59, s67
	s_cselect_b32 s41, s58, s66
	s_add_u32 s62, s62, 0x40080
	s_addc_u32 s63, s63, 0
	s_add_u32 s47, s66, 0x100
	s_addc_u32 s54, s67, 0
	s_mov_b32 s61, -2
	s_add_u32 s18, s62, 0xfffc0080
	s_addc_u32 s19, s63, -1
	s_add_i32 s20, 0, 0x10000
	s_cmp_eq_u32 s61, 12
	s_cselect_b32 s65, s16, s19
	s_cselect_b32 s64, s17, s18
	s_cselect_b32 s51, s39, s54
	s_cselect_b32 s50, s41, s47
	s_add_i32 s21, 0, 0x14000
	v_add_u32_e32 v156, s20, v141
	v_add_u32_e32 v162, s21, v141
	ds_read_b128 v[144:147], v156
	ds_read_b128 v[148:151], v156 offset:1024
	ds_read_b128 v[152:155], v156 offset:2048
	ds_read_b128 v[156:159], v156 offset:3072
	ds_read_b128 v[164:167], v162
	ds_read_b128 v[168:171], v162 offset:1024
	ds_read_b128 v[172:175], v162 offset:2048
	ds_read_b128 v[176:179], v162 offset:3072
	v_lshl_add_u64 v[200:201], s[62:63], 0, v[136:137]
	s_add_i32 m0, s8, 0xc000
	ds_read_b128 v[180:183], v143
	ds_read_b128 v[184:187], v143 offset:1024
	ds_read_b128 v[188:191], v143 offset:2048
	ds_read_b128 v[192:195], v143 offset:3072
	ds_read_b128 v[196:199], v143 offset:4096
	ds_read_b128 v[206:209], v143 offset:5120
	ds_read_b128 v[210:213], v143 offset:6144
	ds_read_b128 v[214:217], v143 offset:7168
	global_load_lds_dwordx4 v[200:201], off
	v_lshl_add_u64 v[200:201], s[62:63], 0, v[138:139]
	s_add_i32 m0, s8, 0xe000
	s_nop 0
	global_load_lds_dwordx4 v[200:201], off
	s_waitcnt vmcnt(8)
	s_waitcnt lgkmcnt(0)
	s_barrier
	s_setprio 1
	s_waitcnt lgkmcnt(0)
	v_mfma_f32_16x16x32_bf16 v[124:127], v[144:147], v[180:183], 0
	v_mfma_f32_16x16x32_bf16 v[120:123], v[152:155], v[180:183], 0
	v_mfma_f32_16x16x32_bf16 v[116:119], v[144:147], v[188:191], 0
	v_mfma_f32_16x16x32_bf16 v[108:111], v[152:155], v[188:191], 0
	v_mfma_f32_16x16x32_bf16 v[100:103], v[144:147], v[196:199], 0
	v_mfma_f32_16x16x32_bf16 v[92:95], v[152:155], v[196:199], 0
	v_mfma_f32_16x16x32_bf16 v[84:87], v[144:147], v[210:213], 0
	v_mfma_f32_16x16x32_bf16 v[76:79], v[152:155], v[210:213], 0
	v_mfma_f32_16x16x32_bf16 v[124:127], v[148:151], v[184:187], v[124:127]
	v_mfma_f32_16x16x32_bf16 v[120:123], v[156:159], v[184:187], v[120:123]
	v_mfma_f32_16x16x32_bf16 v[116:119], v[148:151], v[192:195], v[116:119]
	v_mfma_f32_16x16x32_bf16 v[108:111], v[156:159], v[192:195], v[108:111]
	v_mfma_f32_16x16x32_bf16 v[100:103], v[148:151], v[206:209], v[100:103]
	v_mfma_f32_16x16x32_bf16 v[92:95], v[156:159], v[206:209], v[92:95]
	v_mfma_f32_16x16x32_bf16 v[84:87], v[148:151], v[214:217], v[84:87]
	v_mfma_f32_16x16x32_bf16 v[76:79], v[156:159], v[214:217], v[76:79]
	s_setprio 0
	s_setprio 1
	v_mfma_f32_16x16x32_bf16 v[112:115], v[164:167], v[180:183], 0
	v_mfma_f32_16x16x32_bf16 v[104:107], v[172:175], v[180:183], 0
	v_mfma_f32_16x16x32_bf16 v[96:99], v[164:167], v[188:191], 0
	v_mfma_f32_16x16x32_bf16 v[88:91], v[172:175], v[188:191], 0
	v_mfma_f32_16x16x32_bf16 v[80:83], v[164:167], v[196:199], 0
	v_mfma_f32_16x16x32_bf16 v[72:75], v[172:175], v[196:199], 0
	v_mfma_f32_16x16x32_bf16 v[68:71], v[164:167], v[210:213], 0
	v_mfma_f32_16x16x32_bf16 v[64:67], v[172:175], v[210:213], 0
	v_mfma_f32_16x16x32_bf16 v[112:115], v[168:171], v[184:187], v[112:115]
	v_mfma_f32_16x16x32_bf16 v[104:107], v[176:179], v[184:187], v[104:107]
	v_mfma_f32_16x16x32_bf16 v[96:99], v[168:171], v[192:195], v[96:99]
	v_mfma_f32_16x16x32_bf16 v[88:91], v[176:179], v[192:195], v[88:91]
	v_mfma_f32_16x16x32_bf16 v[80:83], v[168:171], v[206:209], v[80:83]
	v_mfma_f32_16x16x32_bf16 v[72:75], v[176:179], v[206:209], v[72:75]
	v_mfma_f32_16x16x32_bf16 v[68:71], v[168:171], v[214:217], v[68:71]
	v_mfma_f32_16x16x32_bf16 v[64:67], v[176:179], v[214:217], v[64:67]
	s_setprio 0
	s_barrier
	s_add_i32 s18, s20, s7
	v_lshl_add_u64 v[200:201], s[50:51], 0, v[132:133]
	s_mov_b32 m0, s18
	ds_read_b128 v[180:183], v143 offset:16384
	ds_read_b128 v[184:187], v143 offset:17408
	ds_read_b128 v[188:191], v143 offset:18432
	ds_read_b128 v[192:195], v143 offset:19456
	ds_read_b128 v[196:199], v143 offset:20480
	ds_read_b128 v[206:209], v143 offset:21504
	ds_read_b128 v[210:213], v143 offset:22528
	ds_read_b128 v[214:217], v143 offset:23552
	global_load_lds_dwordx4 v[200:201], off
	s_add_i32 m0, s18, 0x2000
	s_add_u32 s18, s50, 0x40000
	v_lshl_add_u64 v[218:219], s[50:51], 0, v[128:129]
	s_addc_u32 s19, s51, 0
	s_add_i32 s20, s21, s7
	global_load_lds_dwordx4 v[218:219], off
	v_lshl_add_u64 v[220:221], s[18:19], 0, v[132:133]
	s_mov_b32 m0, s20
	v_lshl_add_u64 v[222:223], s[64:65], 0, v[130:131]
	global_load_lds_dwordx4 v[220:221], off
	v_lshl_add_u64 v[220:221], s[18:19], 0, v[128:129]
	s_add_i32 m0, s20, 0x2000
	s_nop 0
	global_load_lds_dwordx4 v[220:221], off
	v_lshl_add_u64 v[220:221], s[64:65], 0, v[134:135]
	s_mov_b32 m0, s8
	s_nop 0
	global_load_lds_dwordx4 v[220:221], off
	s_mov_b32 m0, s9
	s_nop 0
	global_load_lds_dwordx4 v[222:223], off
	s_waitcnt vmcnt(8)
	s_waitcnt lgkmcnt(0)
	s_barrier
	s_setprio 1
	s_waitcnt lgkmcnt(0)
	v_mfma_f32_16x16x32_bf16 v[60:63], v[144:147], v[180:183], 0
	v_mfma_f32_16x16x32_bf16 v[56:59], v[152:155], v[180:183], 0
	v_mfma_f32_16x16x32_bf16 v[52:55], v[144:147], v[188:191], 0
	v_mfma_f32_16x16x32_bf16 v[44:47], v[152:155], v[188:191], 0
	v_mfma_f32_16x16x32_bf16 v[36:39], v[144:147], v[196:199], 0
	v_mfma_f32_16x16x32_bf16 v[28:31], v[152:155], v[196:199], 0
	v_mfma_f32_16x16x32_bf16 v[20:23], v[144:147], v[210:213], 0
	v_mfma_f32_16x16x32_bf16 v[12:15], v[152:155], v[210:213], 0
	v_mfma_f32_16x16x32_bf16 v[60:63], v[148:151], v[184:187], v[60:63]
	v_mfma_f32_16x16x32_bf16 v[56:59], v[156:159], v[184:187], v[56:59]
	v_mfma_f32_16x16x32_bf16 v[52:55], v[148:151], v[192:195], v[52:55]
	v_mfma_f32_16x16x32_bf16 v[44:47], v[156:159], v[192:195], v[44:47]
	v_mfma_f32_16x16x32_bf16 v[36:39], v[148:151], v[206:209], v[36:39]
	v_mfma_f32_16x16x32_bf16 v[28:31], v[156:159], v[206:209], v[28:31]
	v_mfma_f32_16x16x32_bf16 v[20:23], v[148:151], v[214:217], v[20:23]
	v_mfma_f32_16x16x32_bf16 v[12:15], v[156:159], v[214:217], v[12:15]
	s_setprio 0
	s_setprio 1
	v_mfma_f32_16x16x32_bf16 v[48:51], v[164:167], v[180:183], 0
	v_mfma_f32_16x16x32_bf16 v[40:43], v[172:175], v[180:183], 0
	v_mfma_f32_16x16x32_bf16 v[32:35], v[164:167], v[188:191], 0
	v_mfma_f32_16x16x32_bf16 v[24:27], v[172:175], v[188:191], 0
	v_mfma_f32_16x16x32_bf16 v[16:19], v[164:167], v[196:199], 0
	v_mfma_f32_16x16x32_bf16 v[8:11], v[172:175], v[196:199], 0
	v_mfma_f32_16x16x32_bf16 v[4:7], v[164:167], v[210:213], 0
	v_mfma_f32_16x16x32_bf16 v[0:3], v[172:175], v[210:213], 0
	v_mfma_f32_16x16x32_bf16 v[48:51], v[168:171], v[184:187], v[48:51]
	v_mfma_f32_16x16x32_bf16 v[40:43], v[176:179], v[184:187], v[40:43]
	v_mfma_f32_16x16x32_bf16 v[32:35], v[168:171], v[192:195], v[32:35]
	v_mfma_f32_16x16x32_bf16 v[24:27], v[176:179], v[192:195], v[24:27]
	v_mfma_f32_16x16x32_bf16 v[16:19], v[168:171], v[206:209], v[16:19]
	v_mfma_f32_16x16x32_bf16 v[8:11], v[176:179], v[206:209], v[8:11]
	v_mfma_f32_16x16x32_bf16 v[4:7], v[168:171], v[214:217], v[4:7]
	v_mfma_f32_16x16x32_bf16 v[0:3], v[176:179], v[214:217], v[0:3]
	s_setprio 0
	s_barrier
	s_add_i32 s20, 0, 0x18000
	s_add_i32 s21, 0, 0x1c000
	v_add_u32_e32 v156, s20, v141
	v_add_u32_e32 v162, s21, v141
	ds_read_b128 v[144:147], v156
	ds_read_b128 v[148:151], v156 offset:1024
	ds_read_b128 v[152:155], v156 offset:2048
	ds_read_b128 v[156:159], v156 offset:3072
	ds_read_b128 v[164:167], v162
	ds_read_b128 v[168:171], v162 offset:1024
	ds_read_b128 v[172:175], v162 offset:2048
	ds_read_b128 v[176:179], v162 offset:3072
	s_add_u32 s18, s64, 0x40000
	s_addc_u32 s19, s65, 0
	s_mov_b32 m0, s10
	v_lshl_add_u64 v[224:225], s[18:19], 0, v[134:135]
	ds_read_b128 v[180:183], v143 offset:32768
	ds_read_b128 v[184:187], v143 offset:33792
	ds_read_b128 v[188:191], v143 offset:34816
	ds_read_b128 v[192:195], v143 offset:35840
	ds_read_b128 v[196:199], v143 offset:36864
	ds_read_b128 v[206:209], v143 offset:37888
	ds_read_b128 v[210:213], v143 offset:38912
	ds_read_b128 v[214:217], v143 offset:39936
	global_load_lds_dwordx4 v[224:225], off
	v_lshl_add_u64 v[224:225], s[18:19], 0, v[130:131]
	s_mov_b32 m0, s11
	s_nop 0
	global_load_lds_dwordx4 v[224:225], off
	s_waitcnt vmcnt(8)
	s_waitcnt lgkmcnt(0)
	s_barrier
	s_setprio 1
	s_waitcnt lgkmcnt(0)
	v_mfma_f32_16x16x32_bf16 v[124:127], v[144:147], v[180:183], v[124:127]
	v_mfma_f32_16x16x32_bf16 v[120:123], v[152:155], v[180:183], v[120:123]
	v_mfma_f32_16x16x32_bf16 v[116:119], v[144:147], v[188:191], v[116:119]
	v_mfma_f32_16x16x32_bf16 v[108:111], v[152:155], v[188:191], v[108:111]
	v_mfma_f32_16x16x32_bf16 v[100:103], v[144:147], v[196:199], v[100:103]
	v_mfma_f32_16x16x32_bf16 v[92:95], v[152:155], v[196:199], v[92:95]
	v_mfma_f32_16x16x32_bf16 v[84:87], v[144:147], v[210:213], v[84:87]
	v_mfma_f32_16x16x32_bf16 v[76:79], v[152:155], v[210:213], v[76:79]
	v_mfma_f32_16x16x32_bf16 v[124:127], v[148:151], v[184:187], v[124:127]
	v_mfma_f32_16x16x32_bf16 v[120:123], v[156:159], v[184:187], v[120:123]
	v_mfma_f32_16x16x32_bf16 v[116:119], v[148:151], v[192:195], v[116:119]
	v_mfma_f32_16x16x32_bf16 v[108:111], v[156:159], v[192:195], v[108:111]
	v_mfma_f32_16x16x32_bf16 v[100:103], v[148:151], v[206:209], v[100:103]
	v_mfma_f32_16x16x32_bf16 v[92:95], v[156:159], v[206:209], v[92:95]
	v_mfma_f32_16x16x32_bf16 v[84:87], v[148:151], v[214:217], v[84:87]
	v_mfma_f32_16x16x32_bf16 v[76:79], v[156:159], v[214:217], v[76:79]
	s_setprio 0
	s_setprio 1
	v_mfma_f32_16x16x32_bf16 v[112:115], v[164:167], v[180:183], v[112:115]
	v_mfma_f32_16x16x32_bf16 v[104:107], v[172:175], v[180:183], v[104:107]
	v_mfma_f32_16x16x32_bf16 v[96:99], v[164:167], v[188:191], v[96:99]
	v_mfma_f32_16x16x32_bf16 v[88:91], v[172:175], v[188:191], v[88:91]
	v_mfma_f32_16x16x32_bf16 v[80:83], v[164:167], v[196:199], v[80:83]
	v_mfma_f32_16x16x32_bf16 v[72:75], v[172:175], v[196:199], v[72:75]
	v_mfma_f32_16x16x32_bf16 v[68:71], v[164:167], v[210:213], v[68:71]
	v_mfma_f32_16x16x32_bf16 v[64:67], v[172:175], v[210:213], v[64:67]
	v_mfma_f32_16x16x32_bf16 v[112:115], v[168:171], v[184:187], v[112:115]
	v_mfma_f32_16x16x32_bf16 v[104:107], v[176:179], v[184:187], v[104:107]
	v_mfma_f32_16x16x32_bf16 v[96:99], v[168:171], v[192:195], v[96:99]
	v_mfma_f32_16x16x32_bf16 v[88:91], v[176:179], v[192:195], v[88:91]
	v_mfma_f32_16x16x32_bf16 v[80:83], v[168:171], v[206:209], v[80:83]
	v_mfma_f32_16x16x32_bf16 v[72:75], v[176:179], v[206:209], v[72:75]
	v_mfma_f32_16x16x32_bf16 v[68:71], v[168:171], v[214:217], v[68:71]
	v_mfma_f32_16x16x32_bf16 v[64:67], v[176:179], v[214:217], v[64:67]
	s_setprio 0
	s_barrier
	s_add_i32 s18, s20, s7
	v_lshl_add_u64 v[200:201], v[200:201], 0, s[76:77]
	s_mov_b32 m0, s18
	ds_read_b128 v[180:183], v143 offset:49152
	ds_read_b128 v[184:187], v143 offset:50176
	ds_read_b128 v[188:191], v143 offset:51200
	ds_read_b128 v[192:195], v143 offset:52224
	ds_read_b128 v[196:199], v143 offset:53248
	ds_read_b128 v[206:209], v143 offset:54272
	ds_read_b128 v[210:213], v143 offset:55296
	ds_read_b128 v[214:217], v143 offset:56320
	global_load_lds_dwordx4 v[200:201], off
	s_add_i32 m0, s18, 0x2000
	s_add_u32 s18, s50, 0x40080
	v_lshl_add_u64 v[200:201], v[218:219], 0, s[76:77]
	s_addc_u32 s19, s51, 0
	s_add_i32 s20, s21, s7
	global_load_lds_dwordx4 v[200:201], off
	v_lshl_add_u64 v[200:201], s[18:19], 0, v[132:133]
	s_mov_b32 m0, s20
	s_nop 0
	global_load_lds_dwordx4 v[200:201], off
	v_lshl_add_u64 v[200:201], s[18:19], 0, v[128:129]
	s_add_i32 m0, s20, 0x2000
	s_nop 0
	global_load_lds_dwordx4 v[200:201], off
	v_lshl_add_u64 v[200:201], v[220:221], 0, s[76:77]
	s_mov_b32 m0, s13
	s_nop 0
	global_load_lds_dwordx4 v[200:201], off
	v_lshl_add_u64 v[200:201], v[222:223], 0, s[76:77]
	s_mov_b32 m0, s14
	s_nop 0
	global_load_lds_dwordx4 v[200:201], off
	s_waitcnt vmcnt(8)
	s_waitcnt lgkmcnt(0)
	s_barrier
	s_setprio 1
	s_waitcnt lgkmcnt(0)
	v_mfma_f32_16x16x32_bf16 v[60:63], v[144:147], v[180:183], v[60:63]
	v_mfma_f32_16x16x32_bf16 v[56:59], v[152:155], v[180:183], v[56:59]
	v_mfma_f32_16x16x32_bf16 v[52:55], v[144:147], v[188:191], v[52:55]
	v_mfma_f32_16x16x32_bf16 v[44:47], v[152:155], v[188:191], v[44:47]
	v_mfma_f32_16x16x32_bf16 v[36:39], v[144:147], v[196:199], v[36:39]
	v_mfma_f32_16x16x32_bf16 v[28:31], v[152:155], v[196:199], v[28:31]
	v_mfma_f32_16x16x32_bf16 v[20:23], v[144:147], v[210:213], v[20:23]
	v_mfma_f32_16x16x32_bf16 v[12:15], v[152:155], v[210:213], v[12:15]
	v_mfma_f32_16x16x32_bf16 v[60:63], v[148:151], v[184:187], v[60:63]
	v_mfma_f32_16x16x32_bf16 v[56:59], v[156:159], v[184:187], v[56:59]
	v_mfma_f32_16x16x32_bf16 v[52:55], v[148:151], v[192:195], v[52:55]
	v_mfma_f32_16x16x32_bf16 v[44:47], v[156:159], v[192:195], v[44:47]
	v_mfma_f32_16x16x32_bf16 v[36:39], v[148:151], v[206:209], v[36:39]
	v_mfma_f32_16x16x32_bf16 v[28:31], v[156:159], v[206:209], v[28:31]
	v_mfma_f32_16x16x32_bf16 v[20:23], v[148:151], v[214:217], v[20:23]
	v_mfma_f32_16x16x32_bf16 v[12:15], v[156:159], v[214:217], v[12:15]
	s_setprio 0
	s_setprio 1
	v_mfma_f32_16x16x32_bf16 v[48:51], v[164:167], v[180:183], v[48:51]
	v_mfma_f32_16x16x32_bf16 v[40:43], v[172:175], v[180:183], v[40:43]
	v_mfma_f32_16x16x32_bf16 v[32:35], v[164:167], v[188:191], v[32:35]
	v_mfma_f32_16x16x32_bf16 v[24:27], v[172:175], v[188:191], v[24:27]
	v_mfma_f32_16x16x32_bf16 v[16:19], v[164:167], v[196:199], v[16:19]
	v_mfma_f32_16x16x32_bf16 v[8:11], v[172:175], v[196:199], v[8:11]
	v_mfma_f32_16x16x32_bf16 v[4:7], v[164:167], v[210:213], v[4:7]
	v_mfma_f32_16x16x32_bf16 v[0:3], v[172:175], v[210:213], v[0:3]
	v_mfma_f32_16x16x32_bf16 v[48:51], v[168:171], v[184:187], v[48:51]
	v_mfma_f32_16x16x32_bf16 v[40:43], v[176:179], v[184:187], v[40:43]
	v_mfma_f32_16x16x32_bf16 v[32:35], v[168:171], v[192:195], v[32:35]
	v_mfma_f32_16x16x32_bf16 v[24:27], v[176:179], v[192:195], v[24:27]
	v_mfma_f32_16x16x32_bf16 v[16:19], v[168:171], v[206:209], v[16:19]
	v_mfma_f32_16x16x32_bf16 v[8:11], v[176:179], v[206:209], v[8:11]
	v_mfma_f32_16x16x32_bf16 v[4:7], v[168:171], v[214:217], v[4:7]
	v_mfma_f32_16x16x32_bf16 v[0:3], v[176:179], v[214:217], v[0:3]
	s_setprio 0
	s_barrier
	s_add_i32 s61, s61, 2
	s_add_u32 s62, s62, 0x100
	s_addc_u32 s63, s63, 0
	s_add_u32 s47, s47, 0x100
	s_addc_u32 s54, s54, 0
	s_cmp_gt_u32 s61, 13
	s_cbranch_scc0 .LBB0_699
	s_branch .Lpeel_x_699
	.p2align 6

.LBB0_778:
	s_add_i32 s11, s11, 1
	s_mov_b32 s14, s12
	s_mul_i32 s12, s11, s86
	v_readlane_b32 s15, v245, 26
	s_add_i32 s12, s12, s15
	s_cmp_lt_u32 s12, 16
	s_mov_b32 s26, s40
	s_cselect_b64 s[48:49], -1, 0
	s_lshr_b32 s40, s12, 1
	s_and_b32 s12, s12, 1
	s_and_b64 s[16:17], s[48:49], exec
	s_mov_b32 s41, s27
	s_cselect_b32 s15, s89, s51
	s_cselect_b32 s16, s88, s50
	s_lshl_b64 s[20:21], s[40:41], 19
	v_readlane_b32 s17, v244, 0
	s_add_u32 s17, s17, s20
	v_readlane_b32 s20, v244, 1
	s_addc_u32 s20, s20, s21
	s_lshl_b32 s21, s12, 18
	s_add_u32 s17, s17, s21
	s_addc_u32 s22, s20, 0
	s_mov_b64 s[18:19], s[42:43]
	s_and_b64 s[20:21], s[48:49], exec
	s_cselect_b32 s43, s22, s19
	s_cselect_b32 s42, s17, s18
	s_add_u32 s58, s50, 0x20080
	s_addc_u32 s59, s51, 0
	s_add_u32 s17, s18, 0x100
	s_addc_u32 s39, s19, 0
	s_mov_b32 s41, -2
	s_add_u32 s18, s58, 0xfffe0080
	s_addc_u32 s19, s59, -1
	s_add_i32 s20, 0, 0x10000
	s_cmp_eq_u32 s41, 4
	s_cselect_b32 s61, s15, s19
	s_cselect_b32 s60, s16, s18
	v_add_u32_e32 v140, s20, v143
	s_cselect_b32 s51, s43, s39
	s_cselect_b32 s50, s42, s17
	s_add_i32 s21, 0, 0x14000
	ds_read_b128 v[146:149], v140
	ds_read_b128 v[150:153], v140 offset:1024
	ds_read_b128 v[154:157], v140 offset:2048
	ds_read_b128 v[164:167], v140 offset:3072
	v_add_u32_e32 v140, s21, v143
	ds_read_b128 v[168:171], v140
	ds_read_b128 v[172:175], v140 offset:1024
	ds_read_b128 v[176:179], v140 offset:2048
	ds_read_b128 v[180:183], v140 offset:3072
	v_lshl_add_u64 v[140:141], s[58:59], 0, v[136:137]
	s_add_i32 m0, s5, 0xc000
	ds_read_b128 v[184:187], v144
	ds_read_b128 v[188:191], v144 offset:1024
	ds_read_b128 v[192:195], v144 offset:2048
	ds_read_b128 v[196:199], v144 offset:3072
	ds_read_b128 v[206:209], v144 offset:4096
	ds_read_b128 v[210:213], v144 offset:5120
	ds_read_b128 v[214:217], v144 offset:6144
	ds_read_b128 v[218:221], v144 offset:7168
	global_load_lds_dwordx4 v[140:141], off
	v_lshl_add_u64 v[140:141], s[58:59], 0, v[138:139]
	s_add_i32 m0, s5, 0xe000
	s_nop 0
	global_load_lds_dwordx4 v[140:141], off
	s_waitcnt vmcnt(8)
	s_waitcnt lgkmcnt(0)
	s_barrier
	s_setprio 1
	s_waitcnt lgkmcnt(0)
	v_mfma_f32_16x16x32_bf16 v[124:127], v[146:149], v[184:187], 0
	v_mfma_f32_16x16x32_bf16 v[120:123], v[154:157], v[184:187], 0
	v_mfma_f32_16x16x32_bf16 v[116:119], v[146:149], v[192:195], 0
	v_mfma_f32_16x16x32_bf16 v[108:111], v[154:157], v[192:195], 0
	v_mfma_f32_16x16x32_bf16 v[100:103], v[146:149], v[206:209], 0
	v_mfma_f32_16x16x32_bf16 v[92:95], v[154:157], v[206:209], 0
	v_mfma_f32_16x16x32_bf16 v[84:87], v[146:149], v[214:217], 0
	v_mfma_f32_16x16x32_bf16 v[76:79], v[154:157], v[214:217], 0
	v_mfma_f32_16x16x32_bf16 v[124:127], v[150:153], v[188:191], v[124:127]
	v_mfma_f32_16x16x32_bf16 v[120:123], v[164:167], v[188:191], v[120:123]
	v_mfma_f32_16x16x32_bf16 v[116:119], v[150:153], v[196:199], v[116:119]
	v_mfma_f32_16x16x32_bf16 v[108:111], v[164:167], v[196:199], v[108:111]
	v_mfma_f32_16x16x32_bf16 v[100:103], v[150:153], v[210:213], v[100:103]
	v_mfma_f32_16x16x32_bf16 v[92:95], v[164:167], v[210:213], v[92:95]
	v_mfma_f32_16x16x32_bf16 v[84:87], v[150:153], v[218:221], v[84:87]
	v_mfma_f32_16x16x32_bf16 v[76:79], v[164:167], v[218:221], v[76:79]
	s_setprio 0
	s_setprio 1
	v_mfma_f32_16x16x32_bf16 v[112:115], v[168:171], v[184:187], 0
	v_mfma_f32_16x16x32_bf16 v[104:107], v[176:179], v[184:187], 0
	v_mfma_f32_16x16x32_bf16 v[96:99], v[168:171], v[192:195], 0
	v_mfma_f32_16x16x32_bf16 v[88:91], v[176:179], v[192:195], 0
	v_mfma_f32_16x16x32_bf16 v[80:83], v[168:171], v[206:209], 0
	v_mfma_f32_16x16x32_bf16 v[72:75], v[176:179], v[206:209], 0
	v_mfma_f32_16x16x32_bf16 v[68:71], v[168:171], v[214:217], 0
	v_mfma_f32_16x16x32_bf16 v[64:67], v[176:179], v[214:217], 0
	v_mfma_f32_16x16x32_bf16 v[112:115], v[172:175], v[188:191], v[112:115]
	v_mfma_f32_16x16x32_bf16 v[104:107], v[180:183], v[188:191], v[104:107]
	v_mfma_f32_16x16x32_bf16 v[96:99], v[172:175], v[196:199], v[96:99]
	v_mfma_f32_16x16x32_bf16 v[88:91], v[180:183], v[196:199], v[88:91]
	v_mfma_f32_16x16x32_bf16 v[80:83], v[172:175], v[210:213], v[80:83]
	v_mfma_f32_16x16x32_bf16 v[72:75], v[180:183], v[210:213], v[72:75]
	v_mfma_f32_16x16x32_bf16 v[68:71], v[172:175], v[218:221], v[68:71]
	v_mfma_f32_16x16x32_bf16 v[64:67], v[180:183], v[218:221], v[64:67]
	s_setprio 0
	s_barrier
	s_add_i32 s18, s20, s4
	v_lshl_add_u64 v[140:141], s[50:51], 0, v[130:131]
	s_mov_b32 m0, s18
	ds_read_b128 v[184:187], v144 offset:16384
	ds_read_b128 v[188:191], v144 offset:17408
	ds_read_b128 v[192:195], v144 offset:18432
	ds_read_b128 v[196:199], v144 offset:19456
	ds_read_b128 v[206:209], v144 offset:20480
	ds_read_b128 v[210:213], v144 offset:21504
	ds_read_b128 v[214:217], v144 offset:22528
	ds_read_b128 v[218:221], v144 offset:23552
	global_load_lds_dwordx4 v[140:141], off
	s_add_i32 m0, s18, 0x2000
	s_add_u32 s18, s50, 0x20000
	v_lshl_add_u64 v[158:159], s[50:51], 0, v[134:135]
	s_addc_u32 s19, s51, 0
	s_add_i32 s20, s21, s4
	global_load_lds_dwordx4 v[158:159], off
	v_lshl_add_u64 v[200:201], s[18:19], 0, v[130:131]
	s_mov_b32 m0, s20
	v_lshl_add_u64 v[222:223], s[60:61], 0, v[132:133]
	global_load_lds_dwordx4 v[200:201], off
	v_lshl_add_u64 v[200:201], s[18:19], 0, v[134:135]
	s_add_i32 m0, s20, 0x2000
	s_nop 0
	global_load_lds_dwordx4 v[200:201], off
	v_lshl_add_u64 v[200:201], s[60:61], 0, v[128:129]
	s_mov_b32 m0, s5
	s_nop 0
	global_load_lds_dwordx4 v[200:201], off
	s_mov_b32 m0, s6
	s_nop 0
	global_load_lds_dwordx4 v[222:223], off
	s_waitcnt vmcnt(8)
	s_waitcnt lgkmcnt(0)
	s_barrier
	s_setprio 1
	s_waitcnt lgkmcnt(0)
	v_mfma_f32_16x16x32_bf16 v[60:63], v[146:149], v[184:187], 0
	v_mfma_f32_16x16x32_bf16 v[56:59], v[154:157], v[184:187], 0
	v_mfma_f32_16x16x32_bf16 v[52:55], v[146:149], v[192:195], 0
	v_mfma_f32_16x16x32_bf16 v[44:47], v[154:157], v[192:195], 0
	v_mfma_f32_16x16x32_bf16 v[36:39], v[146:149], v[206:209], 0
	v_mfma_f32_16x16x32_bf16 v[28:31], v[154:157], v[206:209], 0
	v_mfma_f32_16x16x32_bf16 v[20:23], v[146:149], v[214:217], 0
	v_mfma_f32_16x16x32_bf16 v[12:15], v[154:157], v[214:217], 0
	v_mfma_f32_16x16x32_bf16 v[60:63], v[150:153], v[188:191], v[60:63]
	v_mfma_f32_16x16x32_bf16 v[56:59], v[164:167], v[188:191], v[56:59]
	v_mfma_f32_16x16x32_bf16 v[52:55], v[150:153], v[196:199], v[52:55]
	v_mfma_f32_16x16x32_bf16 v[44:47], v[164:167], v[196:199], v[44:47]
	v_mfma_f32_16x16x32_bf16 v[36:39], v[150:153], v[210:213], v[36:39]
	v_mfma_f32_16x16x32_bf16 v[28:31], v[164:167], v[210:213], v[28:31]
	v_mfma_f32_16x16x32_bf16 v[20:23], v[150:153], v[218:221], v[20:23]
	v_mfma_f32_16x16x32_bf16 v[12:15], v[164:167], v[218:221], v[12:15]
	s_setprio 0
	s_setprio 1
	v_mfma_f32_16x16x32_bf16 v[48:51], v[168:171], v[184:187], 0
	v_mfma_f32_16x16x32_bf16 v[40:43], v[176:179], v[184:187], 0
	v_mfma_f32_16x16x32_bf16 v[32:35], v[168:171], v[192:195], 0
	v_mfma_f32_16x16x32_bf16 v[24:27], v[176:179], v[192:195], 0
	v_mfma_f32_16x16x32_bf16 v[16:19], v[168:171], v[206:209], 0
	v_mfma_f32_16x16x32_bf16 v[8:11], v[176:179], v[206:209], 0
	v_mfma_f32_16x16x32_bf16 v[4:7], v[168:171], v[214:217], 0
	v_mfma_f32_16x16x32_bf16 v[0:3], v[176:179], v[214:217], 0
	v_mfma_f32_16x16x32_bf16 v[48:51], v[172:175], v[188:191], v[48:51]
	v_mfma_f32_16x16x32_bf16 v[40:43], v[180:183], v[188:191], v[40:43]
	v_mfma_f32_16x16x32_bf16 v[32:35], v[172:175], v[196:199], v[32:35]
	v_mfma_f32_16x16x32_bf16 v[24:27], v[180:183], v[196:199], v[24:27]
	v_mfma_f32_16x16x32_bf16 v[16:19], v[172:175], v[210:213], v[16:19]
	v_mfma_f32_16x16x32_bf16 v[8:11], v[180:183], v[210:213], v[8:11]
	v_mfma_f32_16x16x32_bf16 v[4:7], v[172:175], v[218:221], v[4:7]
	v_mfma_f32_16x16x32_bf16 v[0:3], v[180:183], v[218:221], v[0:3]
	s_setprio 0
	s_barrier
	s_add_i32 s20, 0, 0x18000
	v_add_u32_e32 v145, s20, v143
	s_add_i32 s21, 0, 0x1c000
	ds_read_b128 v[146:149], v145
	ds_read_b128 v[150:153], v145 offset:1024
	ds_read_b128 v[154:157], v145 offset:2048
	ds_read_b128 v[164:167], v145 offset:3072
	v_add_u32_e32 v145, s21, v143
	ds_read_b128 v[168:171], v145
	ds_read_b128 v[172:175], v145 offset:1024
	ds_read_b128 v[176:179], v145 offset:2048
	ds_read_b128 v[180:183], v145 offset:3072
	s_add_u32 s18, s60, 0x20000
	s_addc_u32 s19, s61, 0
	s_mov_b32 m0, s7
	v_lshl_add_u64 v[224:225], s[18:19], 0, v[128:129]
	ds_read_b128 v[184:187], v144 offset:32768
	ds_read_b128 v[188:191], v144 offset:33792
	ds_read_b128 v[192:195], v144 offset:34816
	ds_read_b128 v[196:199], v144 offset:35840
	ds_read_b128 v[206:209], v144 offset:36864
	ds_read_b128 v[210:213], v144 offset:37888
	ds_read_b128 v[214:217], v144 offset:38912
	ds_read_b128 v[218:221], v144 offset:39936
	global_load_lds_dwordx4 v[224:225], off
	v_lshl_add_u64 v[224:225], s[18:19], 0, v[132:133]
	s_mov_b32 m0, s8
	s_nop 0
	global_load_lds_dwordx4 v[224:225], off
	s_waitcnt vmcnt(8)
	s_waitcnt lgkmcnt(0)
	s_barrier
	s_setprio 1
	s_waitcnt lgkmcnt(0)
	v_mfma_f32_16x16x32_bf16 v[124:127], v[146:149], v[184:187], v[124:127]
	v_mfma_f32_16x16x32_bf16 v[120:123], v[154:157], v[184:187], v[120:123]
	v_mfma_f32_16x16x32_bf16 v[116:119], v[146:149], v[192:195], v[116:119]
	v_mfma_f32_16x16x32_bf16 v[108:111], v[154:157], v[192:195], v[108:111]
	v_mfma_f32_16x16x32_bf16 v[100:103], v[146:149], v[206:209], v[100:103]
	v_mfma_f32_16x16x32_bf16 v[92:95], v[154:157], v[206:209], v[92:95]
	v_mfma_f32_16x16x32_bf16 v[84:87], v[146:149], v[214:217], v[84:87]
	v_mfma_f32_16x16x32_bf16 v[76:79], v[154:157], v[214:217], v[76:79]
	v_mfma_f32_16x16x32_bf16 v[124:127], v[150:153], v[188:191], v[124:127]
	v_mfma_f32_16x16x32_bf16 v[120:123], v[164:167], v[188:191], v[120:123]
	v_mfma_f32_16x16x32_bf16 v[116:119], v[150:153], v[196:199], v[116:119]
	v_mfma_f32_16x16x32_bf16 v[108:111], v[164:167], v[196:199], v[108:111]
	v_mfma_f32_16x16x32_bf16 v[100:103], v[150:153], v[210:213], v[100:103]
	v_mfma_f32_16x16x32_bf16 v[92:95], v[164:167], v[210:213], v[92:95]
	v_mfma_f32_16x16x32_bf16 v[84:87], v[150:153], v[218:221], v[84:87]
	v_mfma_f32_16x16x32_bf16 v[76:79], v[164:167], v[218:221], v[76:79]
	s_setprio 0
	s_setprio 1
	v_mfma_f32_16x16x32_bf16 v[112:115], v[168:171], v[184:187], v[112:115]
	v_mfma_f32_16x16x32_bf16 v[104:107], v[176:179], v[184:187], v[104:107]
	v_mfma_f32_16x16x32_bf16 v[96:99], v[168:171], v[192:195], v[96:99]
	v_mfma_f32_16x16x32_bf16 v[88:91], v[176:179], v[192:195], v[88:91]
	v_mfma_f32_16x16x32_bf16 v[80:83], v[168:171], v[206:209], v[80:83]
	v_mfma_f32_16x16x32_bf16 v[72:75], v[176:179], v[206:209], v[72:75]
	v_mfma_f32_16x16x32_bf16 v[68:71], v[168:171], v[214:217], v[68:71]
	v_mfma_f32_16x16x32_bf16 v[64:67], v[176:179], v[214:217], v[64:67]
	v_mfma_f32_16x16x32_bf16 v[112:115], v[172:175], v[188:191], v[112:115]
	v_mfma_f32_16x16x32_bf16 v[104:107], v[180:183], v[188:191], v[104:107]
	v_mfma_f32_16x16x32_bf16 v[96:99], v[172:175], v[196:199], v[96:99]
	v_mfma_f32_16x16x32_bf16 v[88:91], v[180:183], v[196:199], v[88:91]
	v_mfma_f32_16x16x32_bf16 v[80:83], v[172:175], v[210:213], v[80:83]
	v_mfma_f32_16x16x32_bf16 v[72:75], v[180:183], v[210:213], v[72:75]
	v_mfma_f32_16x16x32_bf16 v[68:71], v[172:175], v[218:221], v[68:71]
	v_mfma_f32_16x16x32_bf16 v[64:67], v[180:183], v[218:221], v[64:67]
	s_setprio 0
	s_barrier
	s_add_i32 s18, s20, s4
	v_lshl_add_u64 v[140:141], v[140:141], 0, s[76:77]
	s_mov_b32 m0, s18
	ds_read_b128 v[184:187], v144 offset:49152
	ds_read_b128 v[188:191], v144 offset:50176
	ds_read_b128 v[192:195], v144 offset:51200
	ds_read_b128 v[196:199], v144 offset:52224
	ds_read_b128 v[206:209], v144 offset:53248
	ds_read_b128 v[210:213], v144 offset:54272
	ds_read_b128 v[214:217], v144 offset:55296
	ds_read_b128 v[218:221], v144 offset:56320
	global_load_lds_dwordx4 v[140:141], off
	s_add_i32 m0, s18, 0x2000
	s_add_u32 s18, s50, 0x20080
	v_lshl_add_u64 v[140:141], v[158:159], 0, s[76:77]
	s_addc_u32 s19, s51, 0
	s_add_i32 s20, s21, s4
	global_load_lds_dwordx4 v[140:141], off
	v_lshl_add_u64 v[140:141], s[18:19], 0, v[130:131]
	s_mov_b32 m0, s20
	s_nop 0
	global_load_lds_dwordx4 v[140:141], off
	v_lshl_add_u64 v[140:141], s[18:19], 0, v[134:135]
	s_add_i32 m0, s20, 0x2000
	s_nop 0
	global_load_lds_dwordx4 v[140:141], off
	v_lshl_add_u64 v[140:141], v[200:201], 0, s[76:77]
	s_mov_b32 m0, s9
	s_nop 0
	global_load_lds_dwordx4 v[140:141], off
	v_lshl_add_u64 v[140:141], v[222:223], 0, s[76:77]
	s_mov_b32 m0, s10
	s_nop 0
	global_load_lds_dwordx4 v[140:141], off
	s_waitcnt vmcnt(8)
	s_waitcnt lgkmcnt(0)
	s_barrier
	s_setprio 1
	s_waitcnt lgkmcnt(0)
	v_mfma_f32_16x16x32_bf16 v[60:63], v[146:149], v[184:187], v[60:63]
	v_mfma_f32_16x16x32_bf16 v[56:59], v[154:157], v[184:187], v[56:59]
	v_mfma_f32_16x16x32_bf16 v[52:55], v[146:149], v[192:195], v[52:55]
	v_mfma_f32_16x16x32_bf16 v[44:47], v[154:157], v[192:195], v[44:47]
	v_mfma_f32_16x16x32_bf16 v[36:39], v[146:149], v[206:209], v[36:39]
	v_mfma_f32_16x16x32_bf16 v[28:31], v[154:157], v[206:209], v[28:31]
	v_mfma_f32_16x16x32_bf16 v[20:23], v[146:149], v[214:217], v[20:23]
	v_mfma_f32_16x16x32_bf16 v[12:15], v[154:157], v[214:217], v[12:15]
	v_mfma_f32_16x16x32_bf16 v[60:63], v[150:153], v[188:191], v[60:63]
	v_mfma_f32_16x16x32_bf16 v[56:59], v[164:167], v[188:191], v[56:59]
	v_mfma_f32_16x16x32_bf16 v[52:55], v[150:153], v[196:199], v[52:55]
	v_mfma_f32_16x16x32_bf16 v[44:47], v[164:167], v[196:199], v[44:47]
	v_mfma_f32_16x16x32_bf16 v[36:39], v[150:153], v[210:213], v[36:39]
	v_mfma_f32_16x16x32_bf16 v[28:31], v[164:167], v[210:213], v[28:31]
	v_mfma_f32_16x16x32_bf16 v[20:23], v[150:153], v[218:221], v[20:23]
	v_mfma_f32_16x16x32_bf16 v[12:15], v[164:167], v[218:221], v[12:15]
	s_setprio 0
	s_setprio 1
	v_mfma_f32_16x16x32_bf16 v[48:51], v[168:171], v[184:187], v[48:51]
	v_mfma_f32_16x16x32_bf16 v[40:43], v[176:179], v[184:187], v[40:43]
	v_mfma_f32_16x16x32_bf16 v[32:35], v[168:171], v[192:195], v[32:35]
	v_mfma_f32_16x16x32_bf16 v[24:27], v[176:179], v[192:195], v[24:27]
	v_mfma_f32_16x16x32_bf16 v[16:19], v[168:171], v[206:209], v[16:19]
	v_mfma_f32_16x16x32_bf16 v[8:11], v[176:179], v[206:209], v[8:11]
	v_mfma_f32_16x16x32_bf16 v[4:7], v[168:171], v[214:217], v[4:7]
	v_mfma_f32_16x16x32_bf16 v[0:3], v[176:179], v[214:217], v[0:3]
	v_mfma_f32_16x16x32_bf16 v[48:51], v[172:175], v[188:191], v[48:51]
	v_mfma_f32_16x16x32_bf16 v[40:43], v[180:183], v[188:191], v[40:43]
	v_mfma_f32_16x16x32_bf16 v[32:35], v[172:175], v[196:199], v[32:35]
	v_mfma_f32_16x16x32_bf16 v[24:27], v[180:183], v[196:199], v[24:27]
	v_mfma_f32_16x16x32_bf16 v[16:19], v[172:175], v[210:213], v[16:19]
	v_mfma_f32_16x16x32_bf16 v[8:11], v[180:183], v[210:213], v[8:11]
	v_mfma_f32_16x16x32_bf16 v[4:7], v[172:175], v[218:221], v[4:7]
	v_mfma_f32_16x16x32_bf16 v[0:3], v[180:183], v[218:221], v[0:3]
	s_setprio 0
	s_barrier
	s_add_i32 s41, s41, 2
	s_add_u32 s58, s58, 0x100
	s_addc_u32 s59, s59, 0
	s_add_u32 s17, s17, 0x100
	s_addc_u32 s39, s39, 0
	s_cmp_gt_u32 s41, 5
	s_cbranch_scc0 .LBB0_779
	s_branch .Lpeel_x_779
	.p2align 6

.LBB0_890:
	s_ashr_i32 s49, s48, 31
	s_lshl_b64 s[16:17], s[48:49], 20
	s_add_u32 s60, s24, s16
	s_addc_u32 s61, s25, s17
	s_and_b64 s[16:17], s[66:67], exec
	s_cselect_b32 s16, s61, s65
	s_cselect_b32 s17, s60, s64
	s_add_u32 s66, s64, 0x1080
	s_addc_u32 s67, s65, 0
	s_add_u32 s41, s50, 0x100
	s_addc_u32 s43, s51, 0
	s_mov_b32 s46, -2
	s_add_u32 s18, s66, 0xfffff080
	s_addc_u32 s19, s67, -1
	s_add_i32 s20, 0, 0x10000
	s_cmp_eq_u32 s46, 28
	s_cselect_b32 s65, s16, s19
	s_cselect_b32 s64, s17, s18
	s_cselect_b32 s51, s59, s43
	s_cselect_b32 s50, s58, s41
	s_add_i32 s21, 0, 0x14000
	v_add_u32_e32 v90, s20, v88
	v_add_u32_e32 v106, s21, v88
	ds_read_b128 v[74:77], v90
	ds_read_b128 v[78:81], v90 offset:1024
	ds_read_b128 v[82:85], v90 offset:2048
	ds_read_b128 v[90:93], v90 offset:3072
	ds_read_b128 v[94:97], v106
	ds_read_b128 v[98:101], v106 offset:1024
	ds_read_b128 v[102:105], v106 offset:2048
	ds_read_b128 v[106:109], v106 offset:3072
	v_lshl_add_u64 v[142:143], s[66:67], 0, v[70:71]
	s_add_i32 m0, s5, 0xc000
	ds_read_b128 v[110:113], v89
	ds_read_b128 v[114:117], v89 offset:1024
	ds_read_b128 v[118:121], v89 offset:2048
	ds_read_b128 v[122:125], v89 offset:3072
	ds_read_b128 v[126:129], v89 offset:4096
	ds_read_b128 v[130:133], v89 offset:5120
	ds_read_b128 v[134:137], v89 offset:6144
	ds_read_b128 v[138:141], v89 offset:7168
	global_load_lds_dwordx4 v[142:143], off
	v_lshl_add_u64 v[142:143], s[66:67], 0, v[72:73]
	s_add_i32 m0, s5, 0xe000
	s_nop 0
	global_load_lds_dwordx4 v[142:143], off
	s_waitcnt vmcnt(8)
	s_waitcnt lgkmcnt(0)
	s_barrier
	s_setprio 1
	s_waitcnt lgkmcnt(0)
	v_mfma_f32_16x16x32_bf16 v[60:63], v[74:77], v[110:113], 0
	v_mfma_f32_16x16x32_bf16 v[56:59], v[82:85], v[110:113], 0
	v_mfma_f32_16x16x32_bf16 v[44:47], v[74:77], v[118:121], 0
	v_mfma_f32_16x16x32_bf16 v[40:43], v[82:85], v[118:121], 0
	v_mfma_f32_16x16x32_bf16 v[28:31], v[74:77], v[126:129], 0
	v_mfma_f32_16x16x32_bf16 v[24:27], v[82:85], v[126:129], 0
	v_mfma_f32_16x16x32_bf16 v[12:15], v[74:77], v[134:137], 0
	v_mfma_f32_16x16x32_bf16 v[8:11], v[82:85], v[134:137], 0
	v_mfma_f32_16x16x32_bf16 v[60:63], v[78:81], v[114:117], v[60:63]
	v_mfma_f32_16x16x32_bf16 v[56:59], v[90:93], v[114:117], v[56:59]
	v_mfma_f32_16x16x32_bf16 v[44:47], v[78:81], v[122:125], v[44:47]
	v_mfma_f32_16x16x32_bf16 v[40:43], v[90:93], v[122:125], v[40:43]
	v_mfma_f32_16x16x32_bf16 v[28:31], v[78:81], v[130:133], v[28:31]
	v_mfma_f32_16x16x32_bf16 v[24:27], v[90:93], v[130:133], v[24:27]
	v_mfma_f32_16x16x32_bf16 v[12:15], v[78:81], v[138:141], v[12:15]
	v_mfma_f32_16x16x32_bf16 v[8:11], v[90:93], v[138:141], v[8:11]
	s_setprio 0
	s_barrier
	s_add_i32 s18, s20, s4
	v_lshl_add_u64 v[142:143], s[50:51], 0, v[162:163]
	s_mov_b32 m0, s18
	ds_read_b128 v[74:77], v89 offset:16384
	ds_read_b128 v[78:81], v89 offset:17408
	ds_read_b128 v[82:85], v89 offset:18432
	ds_read_b128 v[90:93], v89 offset:19456
	ds_read_b128 v[110:113], v89 offset:20480
	ds_read_b128 v[114:117], v89 offset:21504
	ds_read_b128 v[118:121], v89 offset:22528
	ds_read_b128 v[122:125], v89 offset:23552
	global_load_lds_dwordx4 v[142:143], off
	s_add_i32 m0, s18, 0x2000
	s_add_u32 s18, s50, 0x1000
	v_lshl_add_u64 v[144:145], s[50:51], 0, v[64:65]
	s_addc_u32 s19, s51, 0
	s_add_i32 s20, s21, s4
	global_load_lds_dwordx4 v[144:145], off
	v_lshl_add_u64 v[126:127], s[18:19], 0, v[162:163]
	s_mov_b32 m0, s20
	v_lshl_add_u64 v[146:147], s[64:65], 0, v[68:69]
	global_load_lds_dwordx4 v[126:127], off
	v_lshl_add_u64 v[126:127], s[18:19], 0, v[64:65]
	s_add_i32 m0, s20, 0x2000
	v_lshl_add_u64 v[148:149], s[64:65], 0, v[66:67]
	global_load_lds_dwordx4 v[126:127], off
	s_mov_b32 m0, s5
	s_nop 0
	global_load_lds_dwordx4 v[146:147], off
	s_mov_b32 m0, s6
	s_nop 0
	global_load_lds_dwordx4 v[148:149], off
	s_waitcnt vmcnt(8)
	s_waitcnt lgkmcnt(0)
	s_barrier
	s_setprio 1
	s_waitcnt lgkmcnt(0)
	v_mfma_f32_16x16x32_bf16 v[52:55], v[94:97], v[74:77], 0
	v_mfma_f32_16x16x32_bf16 v[48:51], v[102:105], v[74:77], 0
	v_mfma_f32_16x16x32_bf16 v[36:39], v[94:97], v[82:85], 0
	v_mfma_f32_16x16x32_bf16 v[32:35], v[102:105], v[82:85], 0
	v_mfma_f32_16x16x32_bf16 v[20:23], v[94:97], v[110:113], 0
	v_mfma_f32_16x16x32_bf16 v[16:19], v[102:105], v[110:113], 0
	v_mfma_f32_16x16x32_bf16 v[4:7], v[94:97], v[118:121], 0
	v_mfma_f32_16x16x32_bf16 v[0:3], v[102:105], v[118:121], 0
	v_mfma_f32_16x16x32_bf16 v[52:55], v[98:101], v[78:81], v[52:55]
	v_mfma_f32_16x16x32_bf16 v[48:51], v[106:109], v[78:81], v[48:51]
	v_mfma_f32_16x16x32_bf16 v[36:39], v[98:101], v[90:93], v[36:39]
	v_mfma_f32_16x16x32_bf16 v[32:35], v[106:109], v[90:93], v[32:35]
	v_mfma_f32_16x16x32_bf16 v[20:23], v[98:101], v[114:117], v[20:23]
	v_mfma_f32_16x16x32_bf16 v[16:19], v[106:109], v[114:117], v[16:19]
	v_mfma_f32_16x16x32_bf16 v[4:7], v[98:101], v[122:125], v[4:7]
	v_mfma_f32_16x16x32_bf16 v[0:3], v[106:109], v[122:125], v[0:3]
	s_setprio 0
	s_barrier
	s_add_i32 s20, 0, 0x18000
	s_add_i32 s21, 0, 0x1c000
	v_add_u32_e32 v90, s20, v88
	v_add_u32_e32 v106, s21, v88
	ds_read_b128 v[74:77], v90
	ds_read_b128 v[78:81], v90 offset:1024
	ds_read_b128 v[82:85], v90 offset:2048
	ds_read_b128 v[90:93], v90 offset:3072
	ds_read_b128 v[94:97], v106
	ds_read_b128 v[98:101], v106 offset:1024
	ds_read_b128 v[102:105], v106 offset:2048
	ds_read_b128 v[106:109], v106 offset:3072
	s_add_u32 s18, s64, 0x1000
	s_addc_u32 s19, s65, 0
	s_mov_b32 m0, s7
	v_lshl_add_u64 v[150:151], s[18:19], 0, v[68:69]
	ds_read_b128 v[110:113], v89 offset:32768
	ds_read_b128 v[114:117], v89 offset:33792
	ds_read_b128 v[118:121], v89 offset:34816
	ds_read_b128 v[122:125], v89 offset:35840
	ds_read_b128 v[126:129], v89 offset:36864
	ds_read_b128 v[130:133], v89 offset:37888
	ds_read_b128 v[134:137], v89 offset:38912
	ds_read_b128 v[138:141], v89 offset:39936
	global_load_lds_dwordx4 v[150:151], off
	v_lshl_add_u64 v[150:151], s[18:19], 0, v[66:67]
	s_mov_b32 m0, s8
	s_nop 0
	global_load_lds_dwordx4 v[150:151], off
	s_waitcnt vmcnt(8)
	s_waitcnt lgkmcnt(0)
	s_barrier
	s_setprio 1
	s_waitcnt lgkmcnt(0)
	v_mfma_f32_16x16x32_bf16 v[60:63], v[74:77], v[110:113], v[60:63]
	v_mfma_f32_16x16x32_bf16 v[56:59], v[82:85], v[110:113], v[56:59]
	v_mfma_f32_16x16x32_bf16 v[44:47], v[74:77], v[118:121], v[44:47]
	v_mfma_f32_16x16x32_bf16 v[40:43], v[82:85], v[118:121], v[40:43]
	v_mfma_f32_16x16x32_bf16 v[28:31], v[74:77], v[126:129], v[28:31]
	v_mfma_f32_16x16x32_bf16 v[24:27], v[82:85], v[126:129], v[24:27]
	v_mfma_f32_16x16x32_bf16 v[12:15], v[74:77], v[134:137], v[12:15]
	v_mfma_f32_16x16x32_bf16 v[8:11], v[82:85], v[134:137], v[8:11]
	v_mfma_f32_16x16x32_bf16 v[60:63], v[78:81], v[114:117], v[60:63]
	v_mfma_f32_16x16x32_bf16 v[56:59], v[90:93], v[114:117], v[56:59]
	v_mfma_f32_16x16x32_bf16 v[44:47], v[78:81], v[122:125], v[44:47]
	v_mfma_f32_16x16x32_bf16 v[40:43], v[90:93], v[122:125], v[40:43]
	v_mfma_f32_16x16x32_bf16 v[28:31], v[78:81], v[130:133], v[28:31]
	v_mfma_f32_16x16x32_bf16 v[24:27], v[90:93], v[130:133], v[24:27]
	v_mfma_f32_16x16x32_bf16 v[12:15], v[78:81], v[138:141], v[12:15]
	v_mfma_f32_16x16x32_bf16 v[8:11], v[90:93], v[138:141], v[8:11]
	s_setprio 0
	s_barrier
	s_add_i32 s18, s20, s4
	v_lshl_add_u64 v[126:127], v[142:143], 0, s[76:77]
	s_mov_b32 m0, s18
	ds_read_b128 v[74:77], v89 offset:49152
	ds_read_b128 v[78:81], v89 offset:50176
	ds_read_b128 v[82:85], v89 offset:51200
	ds_read_b128 v[90:93], v89 offset:52224
	ds_read_b128 v[110:113], v89 offset:53248
	ds_read_b128 v[114:117], v89 offset:54272
	ds_read_b128 v[118:121], v89 offset:55296
	ds_read_b128 v[122:125], v89 offset:56320
	global_load_lds_dwordx4 v[126:127], off
	s_add_i32 m0, s18, 0x2000
	s_add_u32 s18, s50, 0x1080
	v_lshl_add_u64 v[126:127], v[144:145], 0, s[76:77]
	s_addc_u32 s19, s51, 0
	s_add_i32 s20, s21, s4
	global_load_lds_dwordx4 v[126:127], off
	v_lshl_add_u64 v[126:127], s[18:19], 0, v[162:163]
	s_mov_b32 m0, s20
	s_nop 0
	global_load_lds_dwordx4 v[126:127], off
	v_lshl_add_u64 v[126:127], s[18:19], 0, v[64:65]
	s_add_i32 m0, s20, 0x2000
	s_nop 0
	global_load_lds_dwordx4 v[126:127], off
	v_lshl_add_u64 v[126:127], v[146:147], 0, s[76:77]
	s_mov_b32 m0, s11
	s_nop 0
	global_load_lds_dwordx4 v[126:127], off
	v_lshl_add_u64 v[126:127], v[148:149], 0, s[76:77]
	s_mov_b32 m0, s12
	s_nop 0
	global_load_lds_dwordx4 v[126:127], off
	s_waitcnt vmcnt(8)
	s_waitcnt lgkmcnt(0)
	s_barrier
	s_setprio 1
	s_waitcnt lgkmcnt(0)
	v_mfma_f32_16x16x32_bf16 v[52:55], v[94:97], v[74:77], v[52:55]
	v_mfma_f32_16x16x32_bf16 v[48:51], v[102:105], v[74:77], v[48:51]
	v_mfma_f32_16x16x32_bf16 v[36:39], v[94:97], v[82:85], v[36:39]
	v_mfma_f32_16x16x32_bf16 v[32:35], v[102:105], v[82:85], v[32:35]
	v_mfma_f32_16x16x32_bf16 v[20:23], v[94:97], v[110:113], v[20:23]
	v_mfma_f32_16x16x32_bf16 v[16:19], v[102:105], v[110:113], v[16:19]
	v_mfma_f32_16x16x32_bf16 v[4:7], v[94:97], v[118:121], v[4:7]
	v_mfma_f32_16x16x32_bf16 v[0:3], v[102:105], v[118:121], v[0:3]
	v_mfma_f32_16x16x32_bf16 v[52:55], v[98:101], v[78:81], v[52:55]
	v_mfma_f32_16x16x32_bf16 v[48:51], v[106:109], v[78:81], v[48:51]
	v_mfma_f32_16x16x32_bf16 v[36:39], v[98:101], v[90:93], v[36:39]
	v_mfma_f32_16x16x32_bf16 v[32:35], v[106:109], v[90:93], v[32:35]
	v_mfma_f32_16x16x32_bf16 v[20:23], v[98:101], v[114:117], v[20:23]
	v_mfma_f32_16x16x32_bf16 v[16:19], v[106:109], v[114:117], v[16:19]
	v_mfma_f32_16x16x32_bf16 v[4:7], v[98:101], v[122:125], v[4:7]
	v_mfma_f32_16x16x32_bf16 v[0:3], v[106:109], v[122:125], v[0:3]
	s_setprio 0
	s_barrier
	s_add_i32 s46, s46, 2
	s_add_u32 s66, s66, 0x100
	s_addc_u32 s67, s67, 0
	s_add_u32 s41, s41, 0x100
	s_addc_u32 s43, s43, 0
	s_cmp_gt_u32 s46, 29
	s_cbranch_scc0 .LBB0_891
	s_branch .Lpeel_x_891
	.p2align 6

.LBB0_913:
	s_add_i32 s11, s11, 1
	s_mov_b32 s13, s12
	s_mul_i32 s12, s11, s86
	s_add_i32 s12, s12, s45
	s_cmp_lt_u32 s12, 16
	s_mov_b32 s26, s40
	s_cselect_b64 s[48:49], -1, 0
	s_lshr_b32 s40, s12, 1
	s_mov_b32 s41, s27
	s_and_b32 s12, s12, 1
	s_lshl_b64 s[16:17], s[40:41], 19
	s_add_u32 s16, s21, s16
	s_addc_u32 s17, s22, s17
	s_lshl_b32 s18, s12, 18
	s_add_u32 s18, s16, s18
	s_addc_u32 s19, s17, 0
	s_mov_b64 s[14:15], s[42:43]
	s_and_b64 s[16:17], s[48:49], exec
	s_cselect_b32 s43, s19, s15
	s_cselect_b32 s42, s18, s14
	s_add_u32 s14, s14, 0x100
	s_addc_u32 s15, s15, 0
	s_mov_b32 s16, -2
	s_mov_b64 s[58:59], 0
	s_add_u32 s60, s58, 0x100
	s_addc_u32 s61, s59, 0
	s_add_u32 s17, s14, s58
	s_addc_u32 s18, s15, s59
	s_cmp_eq_u32 s16, 4
	s_cselect_b32 s20, 0, s60
	s_cselect_b32 s19, 0, s61
	s_cselect_b32 s50, s42, s17
	s_cselect_b32 s51, s43, s18
	s_add_u32 s62, s88, s20
	s_addc_u32 s63, s89, s19
	s_add_i32 s17, 0, 0x10000
	v_add_u32_e32 v142, s17, v144
	s_add_i32 s20, 0, 0x14000
	ds_read_b128 v[146:149], v142
	ds_read_b128 v[150:153], v142 offset:1024
	ds_read_b128 v[154:157], v142 offset:2048
	ds_read_b128 v[164:167], v142 offset:3072
	v_add_u32_e32 v142, s20, v144
	ds_read_b128 v[168:171], v142
	ds_read_b128 v[172:175], v142 offset:1024
	ds_read_b128 v[176:179], v142 offset:2048
	ds_read_b128 v[180:183], v142 offset:3072
	v_lshl_add_u64 v[142:143], v[138:139], 0, s[58:59]
	s_add_i32 m0, s5, 0xc000
	ds_read_b128 v[184:187], v145
	ds_read_b128 v[188:191], v145 offset:1024
	ds_read_b128 v[192:195], v145 offset:2048
	ds_read_b128 v[196:199], v145 offset:3072
	ds_read_b128 v[206:209], v145 offset:4096
	ds_read_b128 v[210:213], v145 offset:5120
	ds_read_b128 v[214:217], v145 offset:6144
	ds_read_b128 v[218:221], v145 offset:7168
	global_load_lds_dwordx4 v[142:143], off
	v_lshl_add_u64 v[142:143], v[140:141], 0, s[58:59]
	s_add_i32 m0, s5, 0xe000
	s_nop 0
	global_load_lds_dwordx4 v[142:143], off
	s_waitcnt vmcnt(8)
	s_waitcnt lgkmcnt(0)
	s_barrier
	s_setprio 1
	s_waitcnt lgkmcnt(0)
	v_mfma_f32_16x16x32_bf16 v[124:127], v[146:149], v[184:187], 0
	v_mfma_f32_16x16x32_bf16 v[120:123], v[154:157], v[184:187], 0
	v_mfma_f32_16x16x32_bf16 v[116:119], v[146:149], v[192:195], 0
	v_mfma_f32_16x16x32_bf16 v[108:111], v[154:157], v[192:195], 0
	v_mfma_f32_16x16x32_bf16 v[100:103], v[146:149], v[206:209], 0
	v_mfma_f32_16x16x32_bf16 v[92:95], v[154:157], v[206:209], 0
	v_mfma_f32_16x16x32_bf16 v[84:87], v[146:149], v[214:217], 0
	v_mfma_f32_16x16x32_bf16 v[76:79], v[154:157], v[214:217], 0
	v_mfma_f32_16x16x32_bf16 v[124:127], v[150:153], v[188:191], v[124:127]
	v_mfma_f32_16x16x32_bf16 v[120:123], v[164:167], v[188:191], v[120:123]
	v_mfma_f32_16x16x32_bf16 v[116:119], v[150:153], v[196:199], v[116:119]
	v_mfma_f32_16x16x32_bf16 v[108:111], v[164:167], v[196:199], v[108:111]
	v_mfma_f32_16x16x32_bf16 v[100:103], v[150:153], v[210:213], v[100:103]
	v_mfma_f32_16x16x32_bf16 v[92:95], v[164:167], v[210:213], v[92:95]
	v_mfma_f32_16x16x32_bf16 v[84:87], v[150:153], v[218:221], v[84:87]
	v_mfma_f32_16x16x32_bf16 v[76:79], v[164:167], v[218:221], v[76:79]
	s_setprio 0
	s_setprio 1
	v_mfma_f32_16x16x32_bf16 v[112:115], v[168:171], v[184:187], 0
	v_mfma_f32_16x16x32_bf16 v[104:107], v[176:179], v[184:187], 0
	v_mfma_f32_16x16x32_bf16 v[96:99], v[168:171], v[192:195], 0
	v_mfma_f32_16x16x32_bf16 v[88:91], v[176:179], v[192:195], 0
	v_mfma_f32_16x16x32_bf16 v[80:83], v[168:171], v[206:209], 0
	v_mfma_f32_16x16x32_bf16 v[72:75], v[176:179], v[206:209], 0
	v_mfma_f32_16x16x32_bf16 v[68:71], v[168:171], v[214:217], 0
	v_mfma_f32_16x16x32_bf16 v[64:67], v[176:179], v[214:217], 0
	v_mfma_f32_16x16x32_bf16 v[112:115], v[172:175], v[188:191], v[112:115]
	v_mfma_f32_16x16x32_bf16 v[104:107], v[180:183], v[188:191], v[104:107]
	v_mfma_f32_16x16x32_bf16 v[96:99], v[172:175], v[196:199], v[96:99]
	v_mfma_f32_16x16x32_bf16 v[88:91], v[180:183], v[196:199], v[88:91]
	v_mfma_f32_16x16x32_bf16 v[80:83], v[172:175], v[210:213], v[80:83]
	v_mfma_f32_16x16x32_bf16 v[72:75], v[180:183], v[210:213], v[72:75]
	v_mfma_f32_16x16x32_bf16 v[68:71], v[172:175], v[218:221], v[68:71]
	v_mfma_f32_16x16x32_bf16 v[64:67], v[180:183], v[218:221], v[64:67]
	s_setprio 0
	s_barrier
	s_add_i32 s17, s17, s4
	v_lshl_add_u64 v[142:143], s[50:51], 0, v[132:133]
	s_mov_b32 m0, s17
	ds_read_b128 v[184:187], v145 offset:16384
	ds_read_b128 v[188:191], v145 offset:17408
	ds_read_b128 v[192:195], v145 offset:18432
	ds_read_b128 v[196:199], v145 offset:19456
	ds_read_b128 v[206:209], v145 offset:20480
	ds_read_b128 v[210:213], v145 offset:21504
	ds_read_b128 v[214:217], v145 offset:22528
	ds_read_b128 v[218:221], v145 offset:23552
	global_load_lds_dwordx4 v[142:143], off
	s_add_i32 m0, s17, 0x2000
	s_add_u32 s18, s50, 0x20000
	v_lshl_add_u64 v[158:159], s[50:51], 0, v[128:129]
	s_addc_u32 s19, s51, 0
	s_add_i32 s17, s20, s4
	global_load_lds_dwordx4 v[158:159], off
	v_lshl_add_u64 v[200:201], s[18:19], 0, v[132:133]
	s_mov_b32 m0, s17
	v_lshl_add_u64 v[222:223], s[62:63], 0, v[130:131]
	global_load_lds_dwordx4 v[200:201], off
	v_lshl_add_u64 v[200:201], s[18:19], 0, v[128:129]
	s_add_i32 m0, s17, 0x2000
	s_nop 0
	global_load_lds_dwordx4 v[200:201], off
	v_lshl_add_u64 v[200:201], s[62:63], 0, v[134:135]
	s_mov_b32 m0, s5
	s_nop 0
	global_load_lds_dwordx4 v[200:201], off
	s_mov_b32 m0, s6
	s_nop 0
	global_load_lds_dwordx4 v[222:223], off
	s_waitcnt vmcnt(8)
	s_waitcnt lgkmcnt(0)
	s_barrier
	s_setprio 1
	s_waitcnt lgkmcnt(0)
	v_mfma_f32_16x16x32_bf16 v[60:63], v[146:149], v[184:187], 0
	v_mfma_f32_16x16x32_bf16 v[56:59], v[154:157], v[184:187], 0
	v_mfma_f32_16x16x32_bf16 v[52:55], v[146:149], v[192:195], 0
	v_mfma_f32_16x16x32_bf16 v[44:47], v[154:157], v[192:195], 0
	v_mfma_f32_16x16x32_bf16 v[36:39], v[146:149], v[206:209], 0
	v_mfma_f32_16x16x32_bf16 v[28:31], v[154:157], v[206:209], 0
	v_mfma_f32_16x16x32_bf16 v[20:23], v[146:149], v[214:217], 0
	v_mfma_f32_16x16x32_bf16 v[12:15], v[154:157], v[214:217], 0
	v_mfma_f32_16x16x32_bf16 v[60:63], v[150:153], v[188:191], v[60:63]
	v_mfma_f32_16x16x32_bf16 v[56:59], v[164:167], v[188:191], v[56:59]
	v_mfma_f32_16x16x32_bf16 v[52:55], v[150:153], v[196:199], v[52:55]
	v_mfma_f32_16x16x32_bf16 v[44:47], v[164:167], v[196:199], v[44:47]
	v_mfma_f32_16x16x32_bf16 v[36:39], v[150:153], v[210:213], v[36:39]
	v_mfma_f32_16x16x32_bf16 v[28:31], v[164:167], v[210:213], v[28:31]
	v_mfma_f32_16x16x32_bf16 v[20:23], v[150:153], v[218:221], v[20:23]
	v_mfma_f32_16x16x32_bf16 v[12:15], v[164:167], v[218:221], v[12:15]
	s_setprio 0
	s_setprio 1
	v_mfma_f32_16x16x32_bf16 v[48:51], v[168:171], v[184:187], 0
	v_mfma_f32_16x16x32_bf16 v[40:43], v[176:179], v[184:187], 0
	v_mfma_f32_16x16x32_bf16 v[32:35], v[168:171], v[192:195], 0
	v_mfma_f32_16x16x32_bf16 v[24:27], v[176:179], v[192:195], 0
	v_mfma_f32_16x16x32_bf16 v[16:19], v[168:171], v[206:209], 0
	v_mfma_f32_16x16x32_bf16 v[8:11], v[176:179], v[206:209], 0
	v_mfma_f32_16x16x32_bf16 v[4:7], v[168:171], v[214:217], 0
	v_mfma_f32_16x16x32_bf16 v[0:3], v[176:179], v[214:217], 0
	v_mfma_f32_16x16x32_bf16 v[48:51], v[172:175], v[188:191], v[48:51]
	v_mfma_f32_16x16x32_bf16 v[40:43], v[180:183], v[188:191], v[40:43]
	v_mfma_f32_16x16x32_bf16 v[32:35], v[172:175], v[196:199], v[32:35]
	v_mfma_f32_16x16x32_bf16 v[24:27], v[180:183], v[196:199], v[24:27]
	v_mfma_f32_16x16x32_bf16 v[16:19], v[172:175], v[210:213], v[16:19]
	v_mfma_f32_16x16x32_bf16 v[8:11], v[180:183], v[210:213], v[8:11]
	v_mfma_f32_16x16x32_bf16 v[4:7], v[172:175], v[218:221], v[4:7]
	v_mfma_f32_16x16x32_bf16 v[0:3], v[180:183], v[218:221], v[0:3]
	s_setprio 0
	s_barrier
	s_add_i32 s17, 0, 0x18000
	s_add_i32 s20, 0, 0x1c000
	v_add_u32_e32 v164, s17, v144
	v_add_u32_e32 v180, s20, v144
	ds_read_b128 v[146:149], v164
	ds_read_b128 v[150:153], v164 offset:1024
	ds_read_b128 v[154:157], v164 offset:2048
	ds_read_b128 v[164:167], v164 offset:3072
	ds_read_b128 v[168:171], v180
	ds_read_b128 v[172:175], v180 offset:1024
	ds_read_b128 v[176:179], v180 offset:2048
	ds_read_b128 v[180:183], v180 offset:3072
	s_add_u32 s18, s62, 0x20000
	s_addc_u32 s19, s63, 0
	s_mov_b32 m0, s7
	v_lshl_add_u64 v[224:225], s[18:19], 0, v[134:135]
	ds_read_b128 v[184:187], v145 offset:32768
	ds_read_b128 v[188:191], v145 offset:33792
	ds_read_b128 v[192:195], v145 offset:34816
	ds_read_b128 v[196:199], v145 offset:35840
	ds_read_b128 v[206:209], v145 offset:36864
	ds_read_b128 v[210:213], v145 offset:37888
	ds_read_b128 v[214:217], v145 offset:38912
	ds_read_b128 v[218:221], v145 offset:39936
	global_load_lds_dwordx4 v[224:225], off
	v_lshl_add_u64 v[224:225], s[18:19], 0, v[130:131]
	s_mov_b32 m0, s8
	s_nop 0
	global_load_lds_dwordx4 v[224:225], off
	s_waitcnt vmcnt(8)
	s_waitcnt lgkmcnt(0)
	s_barrier
	s_setprio 1
	s_waitcnt lgkmcnt(0)
	v_mfma_f32_16x16x32_bf16 v[124:127], v[146:149], v[184:187], v[124:127]
	v_mfma_f32_16x16x32_bf16 v[120:123], v[154:157], v[184:187], v[120:123]
	v_mfma_f32_16x16x32_bf16 v[116:119], v[146:149], v[192:195], v[116:119]
	v_mfma_f32_16x16x32_bf16 v[108:111], v[154:157], v[192:195], v[108:111]
	v_mfma_f32_16x16x32_bf16 v[100:103], v[146:149], v[206:209], v[100:103]
	v_mfma_f32_16x16x32_bf16 v[92:95], v[154:157], v[206:209], v[92:95]
	v_mfma_f32_16x16x32_bf16 v[84:87], v[146:149], v[214:217], v[84:87]
	v_mfma_f32_16x16x32_bf16 v[76:79], v[154:157], v[214:217], v[76:79]
	v_mfma_f32_16x16x32_bf16 v[124:127], v[150:153], v[188:191], v[124:127]
	v_mfma_f32_16x16x32_bf16 v[120:123], v[164:167], v[188:191], v[120:123]
	v_mfma_f32_16x16x32_bf16 v[116:119], v[150:153], v[196:199], v[116:119]
	v_mfma_f32_16x16x32_bf16 v[108:111], v[164:167], v[196:199], v[108:111]
	v_mfma_f32_16x16x32_bf16 v[100:103], v[150:153], v[210:213], v[100:103]
	v_mfma_f32_16x16x32_bf16 v[92:95], v[164:167], v[210:213], v[92:95]
	v_mfma_f32_16x16x32_bf16 v[84:87], v[150:153], v[218:221], v[84:87]
	v_mfma_f32_16x16x32_bf16 v[76:79], v[164:167], v[218:221], v[76:79]
	s_setprio 0
	s_setprio 1
	v_mfma_f32_16x16x32_bf16 v[112:115], v[168:171], v[184:187], v[112:115]
	v_mfma_f32_16x16x32_bf16 v[104:107], v[176:179], v[184:187], v[104:107]
	v_mfma_f32_16x16x32_bf16 v[96:99], v[168:171], v[192:195], v[96:99]
	v_mfma_f32_16x16x32_bf16 v[88:91], v[176:179], v[192:195], v[88:91]
	v_mfma_f32_16x16x32_bf16 v[80:83], v[168:171], v[206:209], v[80:83]
	v_mfma_f32_16x16x32_bf16 v[72:75], v[176:179], v[206:209], v[72:75]
	v_mfma_f32_16x16x32_bf16 v[68:71], v[168:171], v[214:217], v[68:71]
	v_mfma_f32_16x16x32_bf16 v[64:67], v[176:179], v[214:217], v[64:67]
	v_mfma_f32_16x16x32_bf16 v[112:115], v[172:175], v[188:191], v[112:115]
	v_mfma_f32_16x16x32_bf16 v[104:107], v[180:183], v[188:191], v[104:107]
	v_mfma_f32_16x16x32_bf16 v[96:99], v[172:175], v[196:199], v[96:99]
	v_mfma_f32_16x16x32_bf16 v[88:91], v[180:183], v[196:199], v[88:91]
	v_mfma_f32_16x16x32_bf16 v[80:83], v[172:175], v[210:213], v[80:83]
	v_mfma_f32_16x16x32_bf16 v[72:75], v[180:183], v[210:213], v[72:75]
	v_mfma_f32_16x16x32_bf16 v[68:71], v[172:175], v[218:221], v[68:71]
	v_mfma_f32_16x16x32_bf16 v[64:67], v[180:183], v[218:221], v[64:67]
	s_setprio 0
	s_barrier
	s_add_i32 s17, s17, s4
	v_lshl_add_u64 v[142:143], v[142:143], 0, s[76:77]
	s_mov_b32 m0, s17
	ds_read_b128 v[184:187], v145 offset:49152
	ds_read_b128 v[188:191], v145 offset:50176
	ds_read_b128 v[192:195], v145 offset:51200
	ds_read_b128 v[196:199], v145 offset:52224
	ds_read_b128 v[206:209], v145 offset:53248
	ds_read_b128 v[210:213], v145 offset:54272
	ds_read_b128 v[214:217], v145 offset:55296
	ds_read_b128 v[218:221], v145 offset:56320
	global_load_lds_dwordx4 v[142:143], off
	s_add_i32 m0, s17, 0x2000
	s_add_u32 s18, s50, 0x20080
	v_lshl_add_u64 v[142:143], v[158:159], 0, s[76:77]
	s_addc_u32 s19, s51, 0
	s_add_i32 s17, s20, s4
	global_load_lds_dwordx4 v[142:143], off
	v_lshl_add_u64 v[142:143], s[18:19], 0, v[132:133]
	s_mov_b32 m0, s17
	s_nop 0
	global_load_lds_dwordx4 v[142:143], off
	v_lshl_add_u64 v[142:143], s[18:19], 0, v[128:129]
	s_add_i32 m0, s17, 0x2000
	s_nop 0
	global_load_lds_dwordx4 v[142:143], off
	v_lshl_add_u64 v[142:143], v[200:201], 0, s[76:77]
	s_mov_b32 m0, s9
	s_nop 0
	global_load_lds_dwordx4 v[142:143], off
	v_lshl_add_u64 v[142:143], v[222:223], 0, s[76:77]
	s_mov_b32 m0, s10
	s_nop 0
	global_load_lds_dwordx4 v[142:143], off
	s_waitcnt vmcnt(8)
	s_waitcnt lgkmcnt(0)
	s_barrier
	s_setprio 1
	s_waitcnt lgkmcnt(0)
	v_mfma_f32_16x16x32_bf16 v[60:63], v[146:149], v[184:187], v[60:63]
	v_mfma_f32_16x16x32_bf16 v[56:59], v[154:157], v[184:187], v[56:59]
	v_mfma_f32_16x16x32_bf16 v[52:55], v[146:149], v[192:195], v[52:55]
	v_mfma_f32_16x16x32_bf16 v[44:47], v[154:157], v[192:195], v[44:47]
	v_mfma_f32_16x16x32_bf16 v[36:39], v[146:149], v[206:209], v[36:39]
	v_mfma_f32_16x16x32_bf16 v[28:31], v[154:157], v[206:209], v[28:31]
	v_mfma_f32_16x16x32_bf16 v[20:23], v[146:149], v[214:217], v[20:23]
	v_mfma_f32_16x16x32_bf16 v[12:15], v[154:157], v[214:217], v[12:15]
	v_mfma_f32_16x16x32_bf16 v[60:63], v[150:153], v[188:191], v[60:63]
	v_mfma_f32_16x16x32_bf16 v[56:59], v[164:167], v[188:191], v[56:59]
	v_mfma_f32_16x16x32_bf16 v[52:55], v[150:153], v[196:199], v[52:55]
	v_mfma_f32_16x16x32_bf16 v[44:47], v[164:167], v[196:199], v[44:47]
	v_mfma_f32_16x16x32_bf16 v[36:39], v[150:153], v[210:213], v[36:39]
	v_mfma_f32_16x16x32_bf16 v[28:31], v[164:167], v[210:213], v[28:31]
	v_mfma_f32_16x16x32_bf16 v[20:23], v[150:153], v[218:221], v[20:23]
	v_mfma_f32_16x16x32_bf16 v[12:15], v[164:167], v[218:221], v[12:15]
	s_setprio 0
	s_setprio 1
	v_mfma_f32_16x16x32_bf16 v[48:51], v[168:171], v[184:187], v[48:51]
	v_mfma_f32_16x16x32_bf16 v[40:43], v[176:179], v[184:187], v[40:43]
	v_mfma_f32_16x16x32_bf16 v[32:35], v[168:171], v[192:195], v[32:35]
	v_mfma_f32_16x16x32_bf16 v[24:27], v[176:179], v[192:195], v[24:27]
	v_mfma_f32_16x16x32_bf16 v[16:19], v[168:171], v[206:209], v[16:19]
	v_mfma_f32_16x16x32_bf16 v[8:11], v[176:179], v[206:209], v[8:11]
	v_mfma_f32_16x16x32_bf16 v[4:7], v[168:171], v[214:217], v[4:7]
	v_mfma_f32_16x16x32_bf16 v[0:3], v[176:179], v[214:217], v[0:3]
	v_mfma_f32_16x16x32_bf16 v[48:51], v[172:175], v[188:191], v[48:51]
	v_mfma_f32_16x16x32_bf16 v[40:43], v[180:183], v[188:191], v[40:43]
	v_mfma_f32_16x16x32_bf16 v[32:35], v[172:175], v[196:199], v[32:35]
	v_mfma_f32_16x16x32_bf16 v[24:27], v[180:183], v[196:199], v[24:27]
	v_mfma_f32_16x16x32_bf16 v[16:19], v[172:175], v[210:213], v[16:19]
	v_mfma_f32_16x16x32_bf16 v[8:11], v[180:183], v[210:213], v[8:11]
	v_mfma_f32_16x16x32_bf16 v[4:7], v[172:175], v[218:221], v[4:7]
	v_mfma_f32_16x16x32_bf16 v[0:3], v[180:183], v[218:221], v[0:3]
	s_setprio 0
	s_barrier
	s_add_i32 s16, s16, 2
	s_cmp_gt_u32 s16, 5
	s_mov_b64 s[58:59], s[60:61]
	s_cbranch_scc0 .LBB0_914
	s_branch .Lpeel_x_914
	.p2align 6

.LBB0_982:
	s_ashr_i32 s37, s36, 31
	s_lshl_b64 s[16:17], s[36:37], 19
	s_add_u32 s40, s94, s16
	s_addc_u32 s41, s95, s17
	s_and_b64 s[16:17], s[42:43], exec
	s_cselect_b32 s15, s41, s51
	s_cselect_b32 s16, s40, s50
	s_ashr_i32 s39, s38, 31
	s_lshl_b64 s[18:19], s[38:39], 19
	s_add_u32 s48, s22, s18
	s_addc_u32 s49, s23, s19
	s_and_b64 s[18:19], s[42:43], exec
	s_cselect_b32 s17, s49, s61
	s_cselect_b32 s37, s48, s60
	s_add_u32 s58, s50, 0x40080
	s_addc_u32 s59, s51, 0
	s_add_u32 s39, s60, 0x100
	s_addc_u32 s47, s61, 0
	s_mov_b32 s54, -2
	s_add_u32 s18, s58, 0xfffc0080
	s_addc_u32 s19, s59, -1
	s_add_i32 s20, 0, 0x10000
	s_cmp_eq_u32 s54, 12
	s_cselect_b32 s61, s15, s19
	s_cselect_b32 s60, s16, s18
	s_cselect_b32 s51, s17, s47
	s_cselect_b32 s50, s37, s39
	s_add_i32 s21, 0, 0x14000
	v_add_u32_e32 v140, s20, v174
	v_add_u32_e32 v162, s21, v174
	ds_read_b128 v[128:131], v140
	ds_read_b128 v[132:135], v140 offset:1024
	ds_read_b128 v[136:139], v140 offset:2048
	ds_read_b128 v[140:143], v140 offset:3072
	ds_read_b128 v[156:159], v162
	ds_read_b128 v[164:167], v162 offset:1024
	ds_read_b128 v[168:171], v162 offset:2048
	ds_read_b128 v[176:179], v162 offset:3072
	v_lshl_add_u64 v[200:201], s[58:59], 0, v[152:153]
	s_add_i32 m0, s4, 0xc000
	ds_read_b128 v[180:183], v175
	ds_read_b128 v[184:187], v175 offset:1024
	ds_read_b128 v[188:191], v175 offset:2048
	ds_read_b128 v[192:195], v175 offset:3072
	ds_read_b128 v[196:199], v175 offset:4096
	ds_read_b128 v[206:209], v175 offset:5120
	ds_read_b128 v[210:213], v175 offset:6144
	ds_read_b128 v[214:217], v175 offset:7168
	global_load_lds_dwordx4 v[200:201], off
	v_lshl_add_u64 v[200:201], s[58:59], 0, v[154:155]
	s_add_i32 m0, s4, 0xe000
	s_nop 0
	global_load_lds_dwordx4 v[200:201], off
	s_waitcnt vmcnt(8)
	s_waitcnt lgkmcnt(0)
	s_barrier
	s_setprio 1
	s_waitcnt lgkmcnt(0)
	v_mfma_f32_16x16x32_bf16 v[124:127], v[128:131], v[180:183], 0
	v_mfma_f32_16x16x32_bf16 v[120:123], v[136:139], v[180:183], 0
	v_mfma_f32_16x16x32_bf16 v[112:115], v[128:131], v[188:191], 0
	v_mfma_f32_16x16x32_bf16 v[104:107], v[136:139], v[188:191], 0
	v_mfma_f32_16x16x32_bf16 v[96:99], v[128:131], v[196:199], 0
	v_mfma_f32_16x16x32_bf16 v[88:91], v[136:139], v[196:199], 0
	v_mfma_f32_16x16x32_bf16 v[80:83], v[128:131], v[210:213], 0
	v_mfma_f32_16x16x32_bf16 v[72:75], v[136:139], v[210:213], 0
	v_mfma_f32_16x16x32_bf16 v[124:127], v[132:135], v[184:187], v[124:127]
	v_mfma_f32_16x16x32_bf16 v[120:123], v[140:143], v[184:187], v[120:123]
	v_mfma_f32_16x16x32_bf16 v[112:115], v[132:135], v[192:195], v[112:115]
	v_mfma_f32_16x16x32_bf16 v[104:107], v[140:143], v[192:195], v[104:107]
	v_mfma_f32_16x16x32_bf16 v[96:99], v[132:135], v[206:209], v[96:99]
	v_mfma_f32_16x16x32_bf16 v[88:91], v[140:143], v[206:209], v[88:91]
	v_mfma_f32_16x16x32_bf16 v[80:83], v[132:135], v[214:217], v[80:83]
	v_mfma_f32_16x16x32_bf16 v[72:75], v[140:143], v[214:217], v[72:75]
	s_setprio 0
	s_setprio 1
	v_mfma_f32_16x16x32_bf16 v[116:119], v[156:159], v[180:183], 0
	v_mfma_f32_16x16x32_bf16 v[108:111], v[168:171], v[180:183], 0
	v_mfma_f32_16x16x32_bf16 v[100:103], v[156:159], v[188:191], 0
	v_mfma_f32_16x16x32_bf16 v[92:95], v[168:171], v[188:191], 0
	v_mfma_f32_16x16x32_bf16 v[84:87], v[156:159], v[196:199], 0
	v_mfma_f32_16x16x32_bf16 v[76:79], v[168:171], v[196:199], 0
	v_mfma_f32_16x16x32_bf16 v[68:71], v[156:159], v[210:213], 0
	v_mfma_f32_16x16x32_bf16 v[64:67], v[168:171], v[210:213], 0
	v_mfma_f32_16x16x32_bf16 v[116:119], v[164:167], v[184:187], v[116:119]
	v_mfma_f32_16x16x32_bf16 v[108:111], v[176:179], v[184:187], v[108:111]
	v_mfma_f32_16x16x32_bf16 v[100:103], v[164:167], v[192:195], v[100:103]
	v_mfma_f32_16x16x32_bf16 v[92:95], v[176:179], v[192:195], v[92:95]
	v_mfma_f32_16x16x32_bf16 v[84:87], v[164:167], v[206:209], v[84:87]
	v_mfma_f32_16x16x32_bf16 v[76:79], v[176:179], v[206:209], v[76:79]
	v_mfma_f32_16x16x32_bf16 v[68:71], v[164:167], v[214:217], v[68:71]
	v_mfma_f32_16x16x32_bf16 v[64:67], v[176:179], v[214:217], v[64:67]
	s_setprio 0
	s_barrier
	s_add_i32 s18, s20, s46
	v_lshl_add_u64 v[200:201], s[50:51], 0, v[148:149]
	s_mov_b32 m0, s18
	ds_read_b128 v[180:183], v175 offset:16384
	ds_read_b128 v[184:187], v175 offset:17408
	ds_read_b128 v[188:191], v175 offset:18432
	ds_read_b128 v[192:195], v175 offset:19456
	ds_read_b128 v[196:199], v175 offset:20480
	ds_read_b128 v[206:209], v175 offset:21504
	ds_read_b128 v[210:213], v175 offset:22528
	ds_read_b128 v[214:217], v175 offset:23552
	global_load_lds_dwordx4 v[200:201], off
	s_add_i32 m0, s18, 0x2000
	s_add_u32 s18, s50, 0x40000
	v_lshl_add_u64 v[218:219], s[50:51], 0, v[144:145]
	s_addc_u32 s19, s51, 0
	s_add_i32 s20, s21, s46
	global_load_lds_dwordx4 v[218:219], off
	v_lshl_add_u64 v[220:221], s[18:19], 0, v[148:149]
	s_mov_b32 m0, s20
	v_lshl_add_u64 v[222:223], s[60:61], 0, v[146:147]
	global_load_lds_dwordx4 v[220:221], off
	v_lshl_add_u64 v[220:221], s[18:19], 0, v[144:145]
	s_add_i32 m0, s20, 0x2000
	s_nop 0
	global_load_lds_dwordx4 v[220:221], off
	v_lshl_add_u64 v[220:221], s[60:61], 0, v[150:151]
	s_mov_b32 m0, s4
	s_nop 0
	global_load_lds_dwordx4 v[220:221], off
	s_mov_b32 m0, s5
	s_nop 0
	global_load_lds_dwordx4 v[222:223], off
	s_waitcnt vmcnt(8)
	s_waitcnt lgkmcnt(0)
	s_barrier
	s_setprio 1
	s_waitcnt lgkmcnt(0)
	v_mfma_f32_16x16x32_bf16 v[60:63], v[128:131], v[180:183], 0
	v_mfma_f32_16x16x32_bf16 v[56:59], v[136:139], v[180:183], 0
	v_mfma_f32_16x16x32_bf16 v[48:51], v[128:131], v[188:191], 0
	v_mfma_f32_16x16x32_bf16 v[40:43], v[136:139], v[188:191], 0
	v_mfma_f32_16x16x32_bf16 v[32:35], v[128:131], v[196:199], 0
	v_mfma_f32_16x16x32_bf16 v[24:27], v[136:139], v[196:199], 0
	v_mfma_f32_16x16x32_bf16 v[16:19], v[128:131], v[210:213], 0
	v_mfma_f32_16x16x32_bf16 v[8:11], v[136:139], v[210:213], 0
	v_mfma_f32_16x16x32_bf16 v[60:63], v[132:135], v[184:187], v[60:63]
	v_mfma_f32_16x16x32_bf16 v[56:59], v[140:143], v[184:187], v[56:59]
	v_mfma_f32_16x16x32_bf16 v[48:51], v[132:135], v[192:195], v[48:51]
	v_mfma_f32_16x16x32_bf16 v[40:43], v[140:143], v[192:195], v[40:43]
	v_mfma_f32_16x16x32_bf16 v[32:35], v[132:135], v[206:209], v[32:35]
	v_mfma_f32_16x16x32_bf16 v[24:27], v[140:143], v[206:209], v[24:27]
	v_mfma_f32_16x16x32_bf16 v[16:19], v[132:135], v[214:217], v[16:19]
	v_mfma_f32_16x16x32_bf16 v[8:11], v[140:143], v[214:217], v[8:11]
	s_setprio 0
	s_setprio 1
	v_mfma_f32_16x16x32_bf16 v[52:55], v[156:159], v[180:183], 0
	v_mfma_f32_16x16x32_bf16 v[44:47], v[168:171], v[180:183], 0
	v_mfma_f32_16x16x32_bf16 v[36:39], v[156:159], v[188:191], 0
	v_mfma_f32_16x16x32_bf16 v[28:31], v[168:171], v[188:191], 0
	v_mfma_f32_16x16x32_bf16 v[20:23], v[156:159], v[196:199], 0
	v_mfma_f32_16x16x32_bf16 v[12:15], v[168:171], v[196:199], 0
	v_mfma_f32_16x16x32_bf16 v[4:7], v[156:159], v[210:213], 0
	v_mfma_f32_16x16x32_bf16 v[0:3], v[168:171], v[210:213], 0
	v_mfma_f32_16x16x32_bf16 v[52:55], v[164:167], v[184:187], v[52:55]
	v_mfma_f32_16x16x32_bf16 v[44:47], v[176:179], v[184:187], v[44:47]
	v_mfma_f32_16x16x32_bf16 v[36:39], v[164:167], v[192:195], v[36:39]
	v_mfma_f32_16x16x32_bf16 v[28:31], v[176:179], v[192:195], v[28:31]
	v_mfma_f32_16x16x32_bf16 v[20:23], v[164:167], v[206:209], v[20:23]
	v_mfma_f32_16x16x32_bf16 v[12:15], v[176:179], v[206:209], v[12:15]
	v_mfma_f32_16x16x32_bf16 v[4:7], v[164:167], v[214:217], v[4:7]
	v_mfma_f32_16x16x32_bf16 v[0:3], v[176:179], v[214:217], v[0:3]
	s_setprio 0
	s_barrier
	s_add_i32 s20, 0, 0x18000
	s_add_i32 s21, 0, 0x1c000
	v_add_u32_e32 v140, s20, v174
	v_add_u32_e32 v162, s21, v174
	ds_read_b128 v[128:131], v140
	ds_read_b128 v[132:135], v140 offset:1024
	ds_read_b128 v[136:139], v140 offset:2048
	ds_read_b128 v[140:143], v140 offset:3072
	ds_read_b128 v[156:159], v162
	ds_read_b128 v[164:167], v162 offset:1024
	ds_read_b128 v[168:171], v162 offset:2048
	ds_read_b128 v[176:179], v162 offset:3072
	s_add_u32 s18, s60, 0x40000
	s_addc_u32 s19, s61, 0
	s_mov_b32 m0, s6
	v_lshl_add_u64 v[224:225], s[18:19], 0, v[150:151]
	ds_read_b128 v[180:183], v175 offset:32768
	ds_read_b128 v[184:187], v175 offset:33792
	ds_read_b128 v[188:191], v175 offset:34816
	ds_read_b128 v[192:195], v175 offset:35840
	ds_read_b128 v[196:199], v175 offset:36864
	ds_read_b128 v[206:209], v175 offset:37888
	ds_read_b128 v[210:213], v175 offset:38912
	ds_read_b128 v[214:217], v175 offset:39936
	global_load_lds_dwordx4 v[224:225], off
	v_lshl_add_u64 v[224:225], s[18:19], 0, v[146:147]
	s_mov_b32 m0, s7
	s_nop 0
	global_load_lds_dwordx4 v[224:225], off
	s_waitcnt vmcnt(8)
	s_waitcnt lgkmcnt(0)
	s_barrier
	s_setprio 1
	s_waitcnt lgkmcnt(0)
	v_mfma_f32_16x16x32_bf16 v[124:127], v[128:131], v[180:183], v[124:127]
	v_mfma_f32_16x16x32_bf16 v[120:123], v[136:139], v[180:183], v[120:123]
	v_mfma_f32_16x16x32_bf16 v[112:115], v[128:131], v[188:191], v[112:115]
	v_mfma_f32_16x16x32_bf16 v[104:107], v[136:139], v[188:191], v[104:107]
	v_mfma_f32_16x16x32_bf16 v[96:99], v[128:131], v[196:199], v[96:99]
	v_mfma_f32_16x16x32_bf16 v[88:91], v[136:139], v[196:199], v[88:91]
	v_mfma_f32_16x16x32_bf16 v[80:83], v[128:131], v[210:213], v[80:83]
	v_mfma_f32_16x16x32_bf16 v[72:75], v[136:139], v[210:213], v[72:75]
	v_mfma_f32_16x16x32_bf16 v[124:127], v[132:135], v[184:187], v[124:127]
	v_mfma_f32_16x16x32_bf16 v[120:123], v[140:143], v[184:187], v[120:123]
	v_mfma_f32_16x16x32_bf16 v[112:115], v[132:135], v[192:195], v[112:115]
	v_mfma_f32_16x16x32_bf16 v[104:107], v[140:143], v[192:195], v[104:107]
	v_mfma_f32_16x16x32_bf16 v[96:99], v[132:135], v[206:209], v[96:99]
	v_mfma_f32_16x16x32_bf16 v[88:91], v[140:143], v[206:209], v[88:91]
	v_mfma_f32_16x16x32_bf16 v[80:83], v[132:135], v[214:217], v[80:83]
	v_mfma_f32_16x16x32_bf16 v[72:75], v[140:143], v[214:217], v[72:75]
	s_setprio 0
	s_setprio 1
	v_mfma_f32_16x16x32_bf16 v[116:119], v[156:159], v[180:183], v[116:119]
	v_mfma_f32_16x16x32_bf16 v[108:111], v[168:171], v[180:183], v[108:111]
	v_mfma_f32_16x16x32_bf16 v[100:103], v[156:159], v[188:191], v[100:103]
	v_mfma_f32_16x16x32_bf16 v[92:95], v[168:171], v[188:191], v[92:95]
	v_mfma_f32_16x16x32_bf16 v[84:87], v[156:159], v[196:199], v[84:87]
	v_mfma_f32_16x16x32_bf16 v[76:79], v[168:171], v[196:199], v[76:79]
	v_mfma_f32_16x16x32_bf16 v[68:71], v[156:159], v[210:213], v[68:71]
	v_mfma_f32_16x16x32_bf16 v[64:67], v[168:171], v[210:213], v[64:67]
	v_mfma_f32_16x16x32_bf16 v[116:119], v[164:167], v[184:187], v[116:119]
	v_mfma_f32_16x16x32_bf16 v[108:111], v[176:179], v[184:187], v[108:111]
	v_mfma_f32_16x16x32_bf16 v[100:103], v[164:167], v[192:195], v[100:103]
	v_mfma_f32_16x16x32_bf16 v[92:95], v[176:179], v[192:195], v[92:95]
	v_mfma_f32_16x16x32_bf16 v[84:87], v[164:167], v[206:209], v[84:87]
	v_mfma_f32_16x16x32_bf16 v[76:79], v[176:179], v[206:209], v[76:79]
	v_mfma_f32_16x16x32_bf16 v[68:71], v[164:167], v[214:217], v[68:71]
	v_mfma_f32_16x16x32_bf16 v[64:67], v[176:179], v[214:217], v[64:67]
	s_setprio 0
	s_barrier
	s_add_i32 s18, s20, s46
	v_lshl_add_u64 v[200:201], v[200:201], 0, s[76:77]
	s_mov_b32 m0, s18
	ds_read_b128 v[180:183], v175 offset:49152
	ds_read_b128 v[184:187], v175 offset:50176
	ds_read_b128 v[188:191], v175 offset:51200
	ds_read_b128 v[192:195], v175 offset:52224
	ds_read_b128 v[196:199], v175 offset:53248
	ds_read_b128 v[206:209], v175 offset:54272
	ds_read_b128 v[210:213], v175 offset:55296
	ds_read_b128 v[214:217], v175 offset:56320
	global_load_lds_dwordx4 v[200:201], off
	s_add_i32 m0, s18, 0x2000
	s_add_u32 s18, s50, 0x40080
	v_lshl_add_u64 v[200:201], v[218:219], 0, s[76:77]
	s_addc_u32 s19, s51, 0
	s_add_i32 s20, s21, s46
	global_load_lds_dwordx4 v[200:201], off
	v_lshl_add_u64 v[200:201], s[18:19], 0, v[148:149]
	s_mov_b32 m0, s20
	s_nop 0
	global_load_lds_dwordx4 v[200:201], off
	v_lshl_add_u64 v[200:201], s[18:19], 0, v[144:145]
	s_add_i32 m0, s20, 0x2000
	s_nop 0
	global_load_lds_dwordx4 v[200:201], off
	v_lshl_add_u64 v[200:201], v[220:221], 0, s[76:77]
	s_mov_b32 m0, s9
	s_nop 0
	global_load_lds_dwordx4 v[200:201], off
	v_lshl_add_u64 v[200:201], v[222:223], 0, s[76:77]
	s_mov_b32 m0, s10
	s_nop 0
	global_load_lds_dwordx4 v[200:201], off
	s_waitcnt vmcnt(8)
	s_waitcnt lgkmcnt(0)
	s_barrier
	s_setprio 1
	s_waitcnt lgkmcnt(0)
	v_mfma_f32_16x16x32_bf16 v[60:63], v[128:131], v[180:183], v[60:63]
	v_mfma_f32_16x16x32_bf16 v[56:59], v[136:139], v[180:183], v[56:59]
	v_mfma_f32_16x16x32_bf16 v[48:51], v[128:131], v[188:191], v[48:51]
	v_mfma_f32_16x16x32_bf16 v[40:43], v[136:139], v[188:191], v[40:43]
	v_mfma_f32_16x16x32_bf16 v[32:35], v[128:131], v[196:199], v[32:35]
	v_mfma_f32_16x16x32_bf16 v[24:27], v[136:139], v[196:199], v[24:27]
	v_mfma_f32_16x16x32_bf16 v[16:19], v[128:131], v[210:213], v[16:19]
	v_mfma_f32_16x16x32_bf16 v[8:11], v[136:139], v[210:213], v[8:11]
	v_mfma_f32_16x16x32_bf16 v[60:63], v[132:135], v[184:187], v[60:63]
	v_mfma_f32_16x16x32_bf16 v[56:59], v[140:143], v[184:187], v[56:59]
	v_mfma_f32_16x16x32_bf16 v[48:51], v[132:135], v[192:195], v[48:51]
	v_mfma_f32_16x16x32_bf16 v[40:43], v[140:143], v[192:195], v[40:43]
	v_mfma_f32_16x16x32_bf16 v[32:35], v[132:135], v[206:209], v[32:35]
	v_mfma_f32_16x16x32_bf16 v[24:27], v[140:143], v[206:209], v[24:27]
	v_mfma_f32_16x16x32_bf16 v[16:19], v[132:135], v[214:217], v[16:19]
	v_mfma_f32_16x16x32_bf16 v[8:11], v[140:143], v[214:217], v[8:11]
	s_setprio 0
	s_setprio 1
	v_mfma_f32_16x16x32_bf16 v[52:55], v[156:159], v[180:183], v[52:55]
	v_mfma_f32_16x16x32_bf16 v[44:47], v[168:171], v[180:183], v[44:47]
	v_mfma_f32_16x16x32_bf16 v[36:39], v[156:159], v[188:191], v[36:39]
	v_mfma_f32_16x16x32_bf16 v[28:31], v[168:171], v[188:191], v[28:31]
	v_mfma_f32_16x16x32_bf16 v[20:23], v[156:159], v[196:199], v[20:23]
	v_mfma_f32_16x16x32_bf16 v[12:15], v[168:171], v[196:199], v[12:15]
	v_mfma_f32_16x16x32_bf16 v[4:7], v[156:159], v[210:213], v[4:7]
	v_mfma_f32_16x16x32_bf16 v[0:3], v[168:171], v[210:213], v[0:3]
	v_mfma_f32_16x16x32_bf16 v[52:55], v[164:167], v[184:187], v[52:55]
	v_mfma_f32_16x16x32_bf16 v[44:47], v[176:179], v[184:187], v[44:47]
	v_mfma_f32_16x16x32_bf16 v[36:39], v[164:167], v[192:195], v[36:39]
	v_mfma_f32_16x16x32_bf16 v[28:31], v[176:179], v[192:195], v[28:31]
	v_mfma_f32_16x16x32_bf16 v[20:23], v[164:167], v[206:209], v[20:23]
	v_mfma_f32_16x16x32_bf16 v[12:15], v[176:179], v[206:209], v[12:15]
	v_mfma_f32_16x16x32_bf16 v[4:7], v[164:167], v[214:217], v[4:7]
	v_mfma_f32_16x16x32_bf16 v[0:3], v[176:179], v[214:217], v[0:3]
	s_setprio 0
	s_barrier
	s_add_i32 s54, s54, 2
	s_add_u32 s58, s58, 0x100
	s_addc_u32 s59, s59, 0
	s_add_u32 s39, s39, 0x100
	s_addc_u32 s47, s47, 0
	s_cmp_gt_u32 s54, 13
	s_cbranch_scc0 .LBB0_983
	s_branch .Lpeel_x_983
	.p2align 6

.LBB0_1004:
	s_ashr_i32 s37, s36, 31
	s_lshl_b64 s[16:17], s[36:37], 19
	s_add_u32 s40, s94, s16
	s_addc_u32 s41, s95, s17
	s_and_b64 s[16:17], s[42:43], exec
	s_cselect_b32 s16, s41, s51
	s_cselect_b32 s17, s40, s50
	s_ashr_i32 s39, s38, 31
	s_lshl_b64 s[18:19], s[38:39], 19
	s_add_u32 s48, s22, s18
	s_addc_u32 s49, s23, s19
	s_and_b64 s[18:19], s[42:43], exec
	s_cselect_b32 s37, s49, s61
	s_cselect_b32 s39, s48, s60
	s_add_u32 s58, s50, 0x40080
	s_addc_u32 s59, s51, 0
	s_add_u32 s46, s60, 0x100
	s_addc_u32 s47, s61, 0
	s_mov_b32 s54, -2
	s_add_u32 s18, s58, 0xfffc0080
	s_addc_u32 s19, s59, -1
	s_add_i32 s20, 0, 0x10000
	s_cmp_eq_u32 s54, 12
	s_cselect_b32 s61, s16, s19
	s_cselect_b32 s60, s17, s18
	s_cselect_b32 s51, s37, s47
	s_cselect_b32 s50, s39, s46
	s_add_i32 s21, 0, 0x14000
	v_add_u32_e32 v140, s20, v170
	v_add_u32_e32 v162, s21, v170
	ds_read_b128 v[128:131], v140
	ds_read_b128 v[132:135], v140 offset:1024
	ds_read_b128 v[136:139], v140 offset:2048
	ds_read_b128 v[140:143], v140 offset:3072
	ds_read_b128 v[144:147], v162
	ds_read_b128 v[148:151], v162 offset:1024
	ds_read_b128 v[172:175], v162 offset:2048
	ds_read_b128 v[176:179], v162 offset:3072
	v_lshl_add_u64 v[200:201], s[58:59], 0, v[164:165]
	s_add_i32 m0, s5, 0xc000
	ds_read_b128 v[180:183], v171
	ds_read_b128 v[184:187], v171 offset:1024
	ds_read_b128 v[188:191], v171 offset:2048
	ds_read_b128 v[192:195], v171 offset:3072
	ds_read_b128 v[196:199], v171 offset:4096
	ds_read_b128 v[206:209], v171 offset:5120
	ds_read_b128 v[210:213], v171 offset:6144
	ds_read_b128 v[214:217], v171 offset:7168
	global_load_lds_dwordx4 v[200:201], off
	v_lshl_add_u64 v[200:201], s[58:59], 0, v[166:167]
	s_add_i32 m0, s5, 0xe000
	s_nop 0
	global_load_lds_dwordx4 v[200:201], off
	s_waitcnt vmcnt(8)
	s_waitcnt lgkmcnt(0)
	s_barrier
	s_setprio 1
	s_waitcnt lgkmcnt(0)
	v_mfma_f32_16x16x32_bf16 v[124:127], v[128:131], v[180:183], 0
	v_mfma_f32_16x16x32_bf16 v[120:123], v[136:139], v[180:183], 0
	v_mfma_f32_16x16x32_bf16 v[116:119], v[128:131], v[188:191], 0
	v_mfma_f32_16x16x32_bf16 v[112:115], v[136:139], v[188:191], 0
	v_mfma_f32_16x16x32_bf16 v[104:107], v[128:131], v[196:199], 0
	v_mfma_f32_16x16x32_bf16 v[96:99], v[136:139], v[196:199], 0
	v_mfma_f32_16x16x32_bf16 v[80:83], v[128:131], v[210:213], 0
	v_mfma_f32_16x16x32_bf16 v[72:75], v[136:139], v[210:213], 0
	v_mfma_f32_16x16x32_bf16 v[124:127], v[132:135], v[184:187], v[124:127]
	v_mfma_f32_16x16x32_bf16 v[120:123], v[140:143], v[184:187], v[120:123]
	v_mfma_f32_16x16x32_bf16 v[116:119], v[132:135], v[192:195], v[116:119]
	v_mfma_f32_16x16x32_bf16 v[112:115], v[140:143], v[192:195], v[112:115]
	v_mfma_f32_16x16x32_bf16 v[104:107], v[132:135], v[206:209], v[104:107]
	v_mfma_f32_16x16x32_bf16 v[96:99], v[140:143], v[206:209], v[96:99]
	v_mfma_f32_16x16x32_bf16 v[80:83], v[132:135], v[214:217], v[80:83]
	v_mfma_f32_16x16x32_bf16 v[72:75], v[140:143], v[214:217], v[72:75]
	s_setprio 0
	s_setprio 1
	v_mfma_f32_16x16x32_bf16 v[108:111], v[144:147], v[180:183], 0
	v_mfma_f32_16x16x32_bf16 v[100:103], v[172:175], v[180:183], 0
	v_mfma_f32_16x16x32_bf16 v[92:95], v[144:147], v[188:191], 0
	v_mfma_f32_16x16x32_bf16 v[88:91], v[172:175], v[188:191], 0
	v_mfma_f32_16x16x32_bf16 v[84:87], v[144:147], v[196:199], 0
	v_mfma_f32_16x16x32_bf16 v[76:79], v[172:175], v[196:199], 0
	v_mfma_f32_16x16x32_bf16 v[68:71], v[144:147], v[210:213], 0
	v_mfma_f32_16x16x32_bf16 v[64:67], v[172:175], v[210:213], 0
	v_mfma_f32_16x16x32_bf16 v[108:111], v[148:151], v[184:187], v[108:111]
	v_mfma_f32_16x16x32_bf16 v[100:103], v[176:179], v[184:187], v[100:103]
	v_mfma_f32_16x16x32_bf16 v[92:95], v[148:151], v[192:195], v[92:95]
	v_mfma_f32_16x16x32_bf16 v[88:91], v[176:179], v[192:195], v[88:91]
	v_mfma_f32_16x16x32_bf16 v[84:87], v[148:151], v[206:209], v[84:87]
	v_mfma_f32_16x16x32_bf16 v[76:79], v[176:179], v[206:209], v[76:79]
	v_mfma_f32_16x16x32_bf16 v[68:71], v[148:151], v[214:217], v[68:71]
	v_mfma_f32_16x16x32_bf16 v[64:67], v[176:179], v[214:217], v[64:67]
	s_setprio 0
	s_barrier
	s_add_i32 s18, s20, s4
	v_lshl_add_u64 v[200:201], s[50:51], 0, v[156:157]
	s_mov_b32 m0, s18
	ds_read_b128 v[180:183], v171 offset:16384
	ds_read_b128 v[184:187], v171 offset:17408
	ds_read_b128 v[188:191], v171 offset:18432
	ds_read_b128 v[192:195], v171 offset:19456
	ds_read_b128 v[196:199], v171 offset:20480
	ds_read_b128 v[206:209], v171 offset:21504
	ds_read_b128 v[210:213], v171 offset:22528
	ds_read_b128 v[214:217], v171 offset:23552
	global_load_lds_dwordx4 v[200:201], off
	s_add_i32 m0, s18, 0x2000
	s_add_u32 s18, s50, 0x40000
	v_lshl_add_u64 v[218:219], s[50:51], 0, v[152:153]
	s_addc_u32 s19, s51, 0
	s_add_i32 s20, s21, s4
	global_load_lds_dwordx4 v[218:219], off
	v_lshl_add_u64 v[220:221], s[18:19], 0, v[156:157]
	s_mov_b32 m0, s20
	v_lshl_add_u64 v[222:223], s[60:61], 0, v[154:155]
	global_load_lds_dwordx4 v[220:221], off
	v_lshl_add_u64 v[220:221], s[18:19], 0, v[152:153]
	s_add_i32 m0, s20, 0x2000
	s_nop 0
	global_load_lds_dwordx4 v[220:221], off
	v_lshl_add_u64 v[220:221], s[60:61], 0, v[158:159]
	s_mov_b32 m0, s5
	s_nop 0
	global_load_lds_dwordx4 v[220:221], off
	s_mov_b32 m0, s6
	s_nop 0
	global_load_lds_dwordx4 v[222:223], off
	s_waitcnt vmcnt(8)
	s_waitcnt lgkmcnt(0)
	s_barrier
	s_setprio 1
	s_waitcnt lgkmcnt(0)
	v_mfma_f32_16x16x32_bf16 v[60:63], v[128:131], v[180:183], 0
	v_mfma_f32_16x16x32_bf16 v[56:59], v[136:139], v[180:183], 0
	v_mfma_f32_16x16x32_bf16 v[52:55], v[128:131], v[188:191], 0
	v_mfma_f32_16x16x32_bf16 v[48:51], v[136:139], v[188:191], 0
	v_mfma_f32_16x16x32_bf16 v[28:31], v[128:131], v[196:199], 0
	v_mfma_f32_16x16x32_bf16 v[24:27], v[136:139], v[196:199], 0
	v_mfma_f32_16x16x32_bf16 v[16:19], v[128:131], v[210:213], 0
	v_mfma_f32_16x16x32_bf16 v[8:11], v[136:139], v[210:213], 0
	v_mfma_f32_16x16x32_bf16 v[60:63], v[132:135], v[184:187], v[60:63]
	v_mfma_f32_16x16x32_bf16 v[56:59], v[140:143], v[184:187], v[56:59]
	v_mfma_f32_16x16x32_bf16 v[52:55], v[132:135], v[192:195], v[52:55]
	v_mfma_f32_16x16x32_bf16 v[48:51], v[140:143], v[192:195], v[48:51]
	v_mfma_f32_16x16x32_bf16 v[28:31], v[132:135], v[206:209], v[28:31]
	v_mfma_f32_16x16x32_bf16 v[24:27], v[140:143], v[206:209], v[24:27]
	v_mfma_f32_16x16x32_bf16 v[16:19], v[132:135], v[214:217], v[16:19]
	v_mfma_f32_16x16x32_bf16 v[8:11], v[140:143], v[214:217], v[8:11]
	s_setprio 0
	s_setprio 1
	v_mfma_f32_16x16x32_bf16 v[44:47], v[144:147], v[180:183], 0
	v_mfma_f32_16x16x32_bf16 v[40:43], v[172:175], v[180:183], 0
	v_mfma_f32_16x16x32_bf16 v[36:39], v[144:147], v[188:191], 0
	v_mfma_f32_16x16x32_bf16 v[32:35], v[172:175], v[188:191], 0
	v_mfma_f32_16x16x32_bf16 v[20:23], v[144:147], v[196:199], 0
	v_mfma_f32_16x16x32_bf16 v[12:15], v[172:175], v[196:199], 0
	v_mfma_f32_16x16x32_bf16 v[4:7], v[144:147], v[210:213], 0
	v_mfma_f32_16x16x32_bf16 v[0:3], v[172:175], v[210:213], 0
	v_mfma_f32_16x16x32_bf16 v[44:47], v[148:151], v[184:187], v[44:47]
	v_mfma_f32_16x16x32_bf16 v[40:43], v[176:179], v[184:187], v[40:43]
	v_mfma_f32_16x16x32_bf16 v[36:39], v[148:151], v[192:195], v[36:39]
	v_mfma_f32_16x16x32_bf16 v[32:35], v[176:179], v[192:195], v[32:35]
	v_mfma_f32_16x16x32_bf16 v[20:23], v[148:151], v[206:209], v[20:23]
	v_mfma_f32_16x16x32_bf16 v[12:15], v[176:179], v[206:209], v[12:15]
	v_mfma_f32_16x16x32_bf16 v[4:7], v[148:151], v[214:217], v[4:7]
	v_mfma_f32_16x16x32_bf16 v[0:3], v[176:179], v[214:217], v[0:3]
	s_setprio 0
	s_barrier
	s_add_i32 s20, 0, 0x18000
	s_add_i32 s21, 0, 0x1c000
	v_add_u32_e32 v140, s20, v170
	v_add_u32_e32 v162, s21, v170
	ds_read_b128 v[128:131], v140
	ds_read_b128 v[132:135], v140 offset:1024
	ds_read_b128 v[136:139], v140 offset:2048
	ds_read_b128 v[140:143], v140 offset:3072
	ds_read_b128 v[144:147], v162
	ds_read_b128 v[148:151], v162 offset:1024
	ds_read_b128 v[172:175], v162 offset:2048
	ds_read_b128 v[176:179], v162 offset:3072
	s_add_u32 s18, s60, 0x40000
	s_addc_u32 s19, s61, 0
	s_mov_b32 m0, s7
	v_lshl_add_u64 v[224:225], s[18:19], 0, v[158:159]
	ds_read_b128 v[180:183], v171 offset:32768
	ds_read_b128 v[184:187], v171 offset:33792
	ds_read_b128 v[188:191], v171 offset:34816
	ds_read_b128 v[192:195], v171 offset:35840
	ds_read_b128 v[196:199], v171 offset:36864
	ds_read_b128 v[206:209], v171 offset:37888
	ds_read_b128 v[210:213], v171 offset:38912
	ds_read_b128 v[214:217], v171 offset:39936
	global_load_lds_dwordx4 v[224:225], off
	v_lshl_add_u64 v[224:225], s[18:19], 0, v[154:155]
	s_mov_b32 m0, s8
	s_nop 0
	global_load_lds_dwordx4 v[224:225], off
	s_waitcnt vmcnt(8)
	s_waitcnt lgkmcnt(0)
	s_barrier
	s_setprio 1
	s_waitcnt lgkmcnt(0)
	v_mfma_f32_16x16x32_bf16 v[124:127], v[128:131], v[180:183], v[124:127]
	v_mfma_f32_16x16x32_bf16 v[120:123], v[136:139], v[180:183], v[120:123]
	v_mfma_f32_16x16x32_bf16 v[116:119], v[128:131], v[188:191], v[116:119]
	v_mfma_f32_16x16x32_bf16 v[112:115], v[136:139], v[188:191], v[112:115]
	v_mfma_f32_16x16x32_bf16 v[104:107], v[128:131], v[196:199], v[104:107]
	v_mfma_f32_16x16x32_bf16 v[96:99], v[136:139], v[196:199], v[96:99]
	v_mfma_f32_16x16x32_bf16 v[80:83], v[128:131], v[210:213], v[80:83]
	v_mfma_f32_16x16x32_bf16 v[72:75], v[136:139], v[210:213], v[72:75]
	v_mfma_f32_16x16x32_bf16 v[124:127], v[132:135], v[184:187], v[124:127]
	v_mfma_f32_16x16x32_bf16 v[120:123], v[140:143], v[184:187], v[120:123]
	v_mfma_f32_16x16x32_bf16 v[116:119], v[132:135], v[192:195], v[116:119]
	v_mfma_f32_16x16x32_bf16 v[112:115], v[140:143], v[192:195], v[112:115]
	v_mfma_f32_16x16x32_bf16 v[104:107], v[132:135], v[206:209], v[104:107]
	v_mfma_f32_16x16x32_bf16 v[96:99], v[140:143], v[206:209], v[96:99]
	v_mfma_f32_16x16x32_bf16 v[80:83], v[132:135], v[214:217], v[80:83]
	v_mfma_f32_16x16x32_bf16 v[72:75], v[140:143], v[214:217], v[72:75]
	s_setprio 0
	s_setprio 1
	v_mfma_f32_16x16x32_bf16 v[108:111], v[144:147], v[180:183], v[108:111]
	v_mfma_f32_16x16x32_bf16 v[100:103], v[172:175], v[180:183], v[100:103]
	v_mfma_f32_16x16x32_bf16 v[92:95], v[144:147], v[188:191], v[92:95]
	v_mfma_f32_16x16x32_bf16 v[88:91], v[172:175], v[188:191], v[88:91]
	v_mfma_f32_16x16x32_bf16 v[84:87], v[144:147], v[196:199], v[84:87]
	v_mfma_f32_16x16x32_bf16 v[76:79], v[172:175], v[196:199], v[76:79]
	v_mfma_f32_16x16x32_bf16 v[68:71], v[144:147], v[210:213], v[68:71]
	v_mfma_f32_16x16x32_bf16 v[64:67], v[172:175], v[210:213], v[64:67]
	v_mfma_f32_16x16x32_bf16 v[108:111], v[148:151], v[184:187], v[108:111]
	v_mfma_f32_16x16x32_bf16 v[100:103], v[176:179], v[184:187], v[100:103]
	v_mfma_f32_16x16x32_bf16 v[92:95], v[148:151], v[192:195], v[92:95]
	v_mfma_f32_16x16x32_bf16 v[88:91], v[176:179], v[192:195], v[88:91]
	v_mfma_f32_16x16x32_bf16 v[84:87], v[148:151], v[206:209], v[84:87]
	v_mfma_f32_16x16x32_bf16 v[76:79], v[176:179], v[206:209], v[76:79]
	v_mfma_f32_16x16x32_bf16 v[68:71], v[148:151], v[214:217], v[68:71]
	v_mfma_f32_16x16x32_bf16 v[64:67], v[176:179], v[214:217], v[64:67]
	s_setprio 0
	s_barrier
	s_add_i32 s18, s20, s4
	v_lshl_add_u64 v[200:201], v[200:201], 0, s[76:77]
	s_mov_b32 m0, s18
	ds_read_b128 v[180:183], v171 offset:49152
	ds_read_b128 v[184:187], v171 offset:50176
	ds_read_b128 v[188:191], v171 offset:51200
	ds_read_b128 v[192:195], v171 offset:52224
	ds_read_b128 v[196:199], v171 offset:53248
	ds_read_b128 v[206:209], v171 offset:54272
	ds_read_b128 v[210:213], v171 offset:55296
	ds_read_b128 v[214:217], v171 offset:56320
	global_load_lds_dwordx4 v[200:201], off
	s_add_i32 m0, s18, 0x2000
	s_add_u32 s18, s50, 0x40080
	v_lshl_add_u64 v[200:201], v[218:219], 0, s[76:77]
	s_addc_u32 s19, s51, 0
	s_add_i32 s20, s21, s4
	global_load_lds_dwordx4 v[200:201], off
	v_lshl_add_u64 v[200:201], s[18:19], 0, v[156:157]
	s_mov_b32 m0, s20
	s_nop 0
	global_load_lds_dwordx4 v[200:201], off
	v_lshl_add_u64 v[200:201], s[18:19], 0, v[152:153]
	s_add_i32 m0, s20, 0x2000
	s_nop 0
	global_load_lds_dwordx4 v[200:201], off
	v_lshl_add_u64 v[200:201], v[220:221], 0, s[76:77]
	s_mov_b32 m0, s10
	s_nop 0
	global_load_lds_dwordx4 v[200:201], off
	v_lshl_add_u64 v[200:201], v[222:223], 0, s[76:77]
	s_mov_b32 m0, s11
	s_nop 0
	global_load_lds_dwordx4 v[200:201], off
	s_waitcnt vmcnt(8)
	s_waitcnt lgkmcnt(0)
	s_barrier
	s_setprio 1
	s_waitcnt lgkmcnt(0)
	v_mfma_f32_16x16x32_bf16 v[60:63], v[128:131], v[180:183], v[60:63]
	v_mfma_f32_16x16x32_bf16 v[56:59], v[136:139], v[180:183], v[56:59]
	v_mfma_f32_16x16x32_bf16 v[52:55], v[128:131], v[188:191], v[52:55]
	v_mfma_f32_16x16x32_bf16 v[48:51], v[136:139], v[188:191], v[48:51]
	v_mfma_f32_16x16x32_bf16 v[28:31], v[128:131], v[196:199], v[28:31]
	v_mfma_f32_16x16x32_bf16 v[24:27], v[136:139], v[196:199], v[24:27]
	v_mfma_f32_16x16x32_bf16 v[16:19], v[128:131], v[210:213], v[16:19]
	v_mfma_f32_16x16x32_bf16 v[8:11], v[136:139], v[210:213], v[8:11]
	v_mfma_f32_16x16x32_bf16 v[60:63], v[132:135], v[184:187], v[60:63]
	v_mfma_f32_16x16x32_bf16 v[56:59], v[140:143], v[184:187], v[56:59]
	v_mfma_f32_16x16x32_bf16 v[52:55], v[132:135], v[192:195], v[52:55]
	v_mfma_f32_16x16x32_bf16 v[48:51], v[140:143], v[192:195], v[48:51]
	v_mfma_f32_16x16x32_bf16 v[28:31], v[132:135], v[206:209], v[28:31]
	v_mfma_f32_16x16x32_bf16 v[24:27], v[140:143], v[206:209], v[24:27]
	v_mfma_f32_16x16x32_bf16 v[16:19], v[132:135], v[214:217], v[16:19]
	v_mfma_f32_16x16x32_bf16 v[8:11], v[140:143], v[214:217], v[8:11]
	s_setprio 0
	s_setprio 1
	v_mfma_f32_16x16x32_bf16 v[44:47], v[144:147], v[180:183], v[44:47]
	v_mfma_f32_16x16x32_bf16 v[40:43], v[172:175], v[180:183], v[40:43]
	v_mfma_f32_16x16x32_bf16 v[36:39], v[144:147], v[188:191], v[36:39]
	v_mfma_f32_16x16x32_bf16 v[32:35], v[172:175], v[188:191], v[32:35]
	v_mfma_f32_16x16x32_bf16 v[20:23], v[144:147], v[196:199], v[20:23]
	v_mfma_f32_16x16x32_bf16 v[12:15], v[172:175], v[196:199], v[12:15]
	v_mfma_f32_16x16x32_bf16 v[4:7], v[144:147], v[210:213], v[4:7]
	v_mfma_f32_16x16x32_bf16 v[0:3], v[172:175], v[210:213], v[0:3]
	v_mfma_f32_16x16x32_bf16 v[44:47], v[148:151], v[184:187], v[44:47]
	v_mfma_f32_16x16x32_bf16 v[40:43], v[176:179], v[184:187], v[40:43]
	v_mfma_f32_16x16x32_bf16 v[36:39], v[148:151], v[192:195], v[36:39]
	v_mfma_f32_16x16x32_bf16 v[32:35], v[176:179], v[192:195], v[32:35]
	v_mfma_f32_16x16x32_bf16 v[20:23], v[148:151], v[206:209], v[20:23]
	v_mfma_f32_16x16x32_bf16 v[12:15], v[176:179], v[206:209], v[12:15]
	v_mfma_f32_16x16x32_bf16 v[4:7], v[148:151], v[214:217], v[4:7]
	v_mfma_f32_16x16x32_bf16 v[0:3], v[176:179], v[214:217], v[0:3]
	s_setprio 0
	s_barrier
	s_add_i32 s54, s54, 2
	s_add_u32 s58, s58, 0x100
	s_addc_u32 s59, s59, 0
	s_add_u32 s46, s46, 0x100
	s_addc_u32 s47, s47, 0
	s_cmp_gt_u32 s54, 13
	s_cbranch_scc0 .LBB0_1005
	s_branch .Lpeel_x_1005
	.p2align 6

.LBB0_1137:
	s_ashr_i32 s37, s36, 31
	s_lshl_b64 s[18:19], s[36:37], 19
	s_add_u32 s40, s96, s18
	s_addc_u32 s41, s97, s19
	s_and_b64 s[18:19], s[42:43], exec
	s_cselect_b32 s17, s41, s59
	s_cselect_b32 s37, s40, s58
	s_ashr_i32 s39, s38, 31
	s_lshl_b64 s[18:19], s[38:39], 19
	s_add_u32 s48, s5, s18
	s_addc_u32 s49, s6, s19
	s_and_b64 s[18:19], s[42:43], exec
	s_cselect_b32 s39, s49, s51
	s_cselect_b32 s46, s48, s50
	s_add_u32 s58, s58, 0x40080
	s_addc_u32 s59, s59, 0
	s_add_u32 s47, s50, 0x100
	s_addc_u32 s62, s51, 0
	s_mov_b32 s63, -2
	s_add_u32 s18, s58, 0xfffc0080
	s_addc_u32 s19, s59, -1
	s_add_i32 s20, 0, 0x10000
	s_cmp_eq_u32 s63, 12
	s_cselect_b32 s61, s17, s19
	s_cselect_b32 s60, s37, s18
	v_add_u32_e32 v140, s20, v143
	s_cselect_b32 s51, s39, s62
	s_cselect_b32 s50, s46, s47
	s_add_i32 s21, 0, 0x14000
	ds_read_b128 v[146:149], v140
	ds_read_b128 v[150:153], v140 offset:1024
	ds_read_b128 v[154:157], v140 offset:2048
	ds_read_b128 v[164:167], v140 offset:3072
	v_add_u32_e32 v140, s21, v143
	ds_read_b128 v[168:171], v140
	ds_read_b128 v[172:175], v140 offset:1024
	ds_read_b128 v[176:179], v140 offset:2048
	ds_read_b128 v[180:183], v140 offset:3072
	v_lshl_add_u64 v[140:141], s[58:59], 0, v[136:137]
	s_add_i32 m0, s8, 0xc000
	ds_read_b128 v[184:187], v144
	ds_read_b128 v[188:191], v144 offset:1024
	ds_read_b128 v[192:195], v144 offset:2048
	ds_read_b128 v[196:199], v144 offset:3072
	ds_read_b128 v[206:209], v144 offset:4096
	ds_read_b128 v[210:213], v144 offset:5120
	ds_read_b128 v[214:217], v144 offset:6144
	ds_read_b128 v[218:221], v144 offset:7168
	global_load_lds_dwordx4 v[140:141], off
	v_lshl_add_u64 v[140:141], s[58:59], 0, v[138:139]
	s_add_i32 m0, s8, 0xe000
	s_nop 0
	global_load_lds_dwordx4 v[140:141], off
	s_waitcnt vmcnt(8)
	s_waitcnt lgkmcnt(0)
	s_barrier
	s_setprio 1
	s_waitcnt lgkmcnt(0)
	v_mfma_f32_16x16x32_bf16 v[124:127], v[146:149], v[184:187], 0
	v_mfma_f32_16x16x32_bf16 v[120:123], v[154:157], v[184:187], 0
	v_mfma_f32_16x16x32_bf16 v[108:111], v[146:149], v[192:195], 0
	v_mfma_f32_16x16x32_bf16 v[104:107], v[154:157], v[192:195], 0
	v_mfma_f32_16x16x32_bf16 v[92:95], v[146:149], v[206:209], 0
	v_mfma_f32_16x16x32_bf16 v[88:91], v[154:157], v[206:209], 0
	v_mfma_f32_16x16x32_bf16 v[76:79], v[146:149], v[214:217], 0
	v_mfma_f32_16x16x32_bf16 v[72:75], v[154:157], v[214:217], 0
	v_mfma_f32_16x16x32_bf16 v[124:127], v[150:153], v[188:191], v[124:127]
	v_mfma_f32_16x16x32_bf16 v[120:123], v[164:167], v[188:191], v[120:123]
	v_mfma_f32_16x16x32_bf16 v[108:111], v[150:153], v[196:199], v[108:111]
	v_mfma_f32_16x16x32_bf16 v[104:107], v[164:167], v[196:199], v[104:107]
	v_mfma_f32_16x16x32_bf16 v[92:95], v[150:153], v[210:213], v[92:95]
	v_mfma_f32_16x16x32_bf16 v[88:91], v[164:167], v[210:213], v[88:91]
	v_mfma_f32_16x16x32_bf16 v[76:79], v[150:153], v[218:221], v[76:79]
	v_mfma_f32_16x16x32_bf16 v[72:75], v[164:167], v[218:221], v[72:75]
	s_setprio 0
	s_setprio 1
	v_mfma_f32_16x16x32_bf16 v[116:119], v[168:171], v[184:187], 0
	v_mfma_f32_16x16x32_bf16 v[112:115], v[176:179], v[184:187], 0
	v_mfma_f32_16x16x32_bf16 v[100:103], v[168:171], v[192:195], 0
	v_mfma_f32_16x16x32_bf16 v[96:99], v[176:179], v[192:195], 0
	v_mfma_f32_16x16x32_bf16 v[84:87], v[168:171], v[206:209], 0
	v_mfma_f32_16x16x32_bf16 v[80:83], v[176:179], v[206:209], 0
	v_mfma_f32_16x16x32_bf16 v[68:71], v[168:171], v[214:217], 0
	v_mfma_f32_16x16x32_bf16 v[64:67], v[176:179], v[214:217], 0
	v_mfma_f32_16x16x32_bf16 v[116:119], v[172:175], v[188:191], v[116:119]
	v_mfma_f32_16x16x32_bf16 v[112:115], v[180:183], v[188:191], v[112:115]
	v_mfma_f32_16x16x32_bf16 v[100:103], v[172:175], v[196:199], v[100:103]
	v_mfma_f32_16x16x32_bf16 v[96:99], v[180:183], v[196:199], v[96:99]
	v_mfma_f32_16x16x32_bf16 v[84:87], v[172:175], v[210:213], v[84:87]
	v_mfma_f32_16x16x32_bf16 v[80:83], v[180:183], v[210:213], v[80:83]
	v_mfma_f32_16x16x32_bf16 v[68:71], v[172:175], v[218:221], v[68:71]
	v_mfma_f32_16x16x32_bf16 v[64:67], v[180:183], v[218:221], v[64:67]
	s_setprio 0
	s_barrier
	s_add_i32 s18, s20, s7
	v_lshl_add_u64 v[140:141], s[50:51], 0, v[132:133]
	s_mov_b32 m0, s18
	ds_read_b128 v[184:187], v144 offset:16384
	ds_read_b128 v[188:191], v144 offset:17408
	ds_read_b128 v[192:195], v144 offset:18432
	ds_read_b128 v[196:199], v144 offset:19456
	ds_read_b128 v[206:209], v144 offset:20480
	ds_read_b128 v[210:213], v144 offset:21504
	ds_read_b128 v[214:217], v144 offset:22528
	ds_read_b128 v[218:221], v144 offset:23552
	global_load_lds_dwordx4 v[140:141], off
	s_add_i32 m0, s18, 0x2000
	s_add_u32 s18, s50, 0x40000
	v_lshl_add_u64 v[158:159], s[50:51], 0, v[128:129]
	s_addc_u32 s19, s51, 0
	s_add_i32 s20, s21, s7
	global_load_lds_dwordx4 v[158:159], off
	v_lshl_add_u64 v[200:201], s[18:19], 0, v[132:133]
	s_mov_b32 m0, s20
	v_lshl_add_u64 v[222:223], s[60:61], 0, v[130:131]
	global_load_lds_dwordx4 v[200:201], off
	v_lshl_add_u64 v[200:201], s[18:19], 0, v[128:129]
	s_add_i32 m0, s20, 0x2000
	s_nop 0
	global_load_lds_dwordx4 v[200:201], off
	v_lshl_add_u64 v[200:201], s[60:61], 0, v[134:135]
	s_mov_b32 m0, s8
	s_nop 0
	global_load_lds_dwordx4 v[200:201], off
	s_mov_b32 m0, s9
	s_nop 0
	global_load_lds_dwordx4 v[222:223], off
	s_waitcnt vmcnt(8)
	s_waitcnt lgkmcnt(0)
	s_barrier
	s_setprio 1
	s_waitcnt lgkmcnt(0)
	v_mfma_f32_16x16x32_bf16 v[60:63], v[146:149], v[184:187], 0
	v_mfma_f32_16x16x32_bf16 v[56:59], v[154:157], v[184:187], 0
	v_mfma_f32_16x16x32_bf16 v[44:47], v[146:149], v[192:195], 0
	v_mfma_f32_16x16x32_bf16 v[40:43], v[154:157], v[192:195], 0
	v_mfma_f32_16x16x32_bf16 v[28:31], v[146:149], v[206:209], 0
	v_mfma_f32_16x16x32_bf16 v[24:27], v[154:157], v[206:209], 0
	v_mfma_f32_16x16x32_bf16 v[12:15], v[146:149], v[214:217], 0
	v_mfma_f32_16x16x32_bf16 v[8:11], v[154:157], v[214:217], 0
	v_mfma_f32_16x16x32_bf16 v[60:63], v[150:153], v[188:191], v[60:63]
	v_mfma_f32_16x16x32_bf16 v[56:59], v[164:167], v[188:191], v[56:59]
	v_mfma_f32_16x16x32_bf16 v[44:47], v[150:153], v[196:199], v[44:47]
	v_mfma_f32_16x16x32_bf16 v[40:43], v[164:167], v[196:199], v[40:43]
	v_mfma_f32_16x16x32_bf16 v[28:31], v[150:153], v[210:213], v[28:31]
	v_mfma_f32_16x16x32_bf16 v[24:27], v[164:167], v[210:213], v[24:27]
	v_mfma_f32_16x16x32_bf16 v[12:15], v[150:153], v[218:221], v[12:15]
	v_mfma_f32_16x16x32_bf16 v[8:11], v[164:167], v[218:221], v[8:11]
	s_setprio 0
	s_setprio 1
	v_mfma_f32_16x16x32_bf16 v[52:55], v[168:171], v[184:187], 0
	v_mfma_f32_16x16x32_bf16 v[48:51], v[176:179], v[184:187], 0
	v_mfma_f32_16x16x32_bf16 v[36:39], v[168:171], v[192:195], 0
	v_mfma_f32_16x16x32_bf16 v[32:35], v[176:179], v[192:195], 0
	v_mfma_f32_16x16x32_bf16 v[20:23], v[168:171], v[206:209], 0
	v_mfma_f32_16x16x32_bf16 v[16:19], v[176:179], v[206:209], 0
	v_mfma_f32_16x16x32_bf16 v[4:7], v[168:171], v[214:217], 0
	v_mfma_f32_16x16x32_bf16 v[0:3], v[176:179], v[214:217], 0
	v_mfma_f32_16x16x32_bf16 v[52:55], v[172:175], v[188:191], v[52:55]
	v_mfma_f32_16x16x32_bf16 v[48:51], v[180:183], v[188:191], v[48:51]
	v_mfma_f32_16x16x32_bf16 v[36:39], v[172:175], v[196:199], v[36:39]
	v_mfma_f32_16x16x32_bf16 v[32:35], v[180:183], v[196:199], v[32:35]
	v_mfma_f32_16x16x32_bf16 v[20:23], v[172:175], v[210:213], v[20:23]
	v_mfma_f32_16x16x32_bf16 v[16:19], v[180:183], v[210:213], v[16:19]
	v_mfma_f32_16x16x32_bf16 v[4:7], v[172:175], v[218:221], v[4:7]
	v_mfma_f32_16x16x32_bf16 v[0:3], v[180:183], v[218:221], v[0:3]
	s_setprio 0
	s_barrier
	s_add_i32 s20, 0, 0x18000
	v_add_u32_e32 v145, s20, v143
	s_add_i32 s21, 0, 0x1c000
	ds_read_b128 v[146:149], v145
	ds_read_b128 v[150:153], v145 offset:1024
	ds_read_b128 v[154:157], v145 offset:2048
	ds_read_b128 v[164:167], v145 offset:3072
	v_add_u32_e32 v145, s21, v143
	ds_read_b128 v[168:171], v145
	ds_read_b128 v[172:175], v145 offset:1024
	ds_read_b128 v[176:179], v145 offset:2048
	ds_read_b128 v[180:183], v145 offset:3072
	s_add_u32 s18, s60, 0x40000
	s_addc_u32 s19, s61, 0
	s_mov_b32 m0, s10
	v_lshl_add_u64 v[224:225], s[18:19], 0, v[134:135]
	ds_read_b128 v[184:187], v144 offset:32768
	ds_read_b128 v[188:191], v144 offset:33792
	ds_read_b128 v[192:195], v144 offset:34816
	ds_read_b128 v[196:199], v144 offset:35840
	ds_read_b128 v[206:209], v144 offset:36864
	ds_read_b128 v[210:213], v144 offset:37888
	ds_read_b128 v[214:217], v144 offset:38912
	ds_read_b128 v[218:221], v144 offset:39936
	global_load_lds_dwordx4 v[224:225], off
	v_lshl_add_u64 v[224:225], s[18:19], 0, v[130:131]
	s_mov_b32 m0, s11
	s_nop 0
	global_load_lds_dwordx4 v[224:225], off
	s_waitcnt vmcnt(8)
	s_waitcnt lgkmcnt(0)
	s_barrier
	s_setprio 1
	s_waitcnt lgkmcnt(0)
	v_mfma_f32_16x16x32_bf16 v[124:127], v[146:149], v[184:187], v[124:127]
	v_mfma_f32_16x16x32_bf16 v[120:123], v[154:157], v[184:187], v[120:123]
	v_mfma_f32_16x16x32_bf16 v[108:111], v[146:149], v[192:195], v[108:111]
	v_mfma_f32_16x16x32_bf16 v[104:107], v[154:157], v[192:195], v[104:107]
	v_mfma_f32_16x16x32_bf16 v[92:95], v[146:149], v[206:209], v[92:95]
	v_mfma_f32_16x16x32_bf16 v[88:91], v[154:157], v[206:209], v[88:91]
	v_mfma_f32_16x16x32_bf16 v[76:79], v[146:149], v[214:217], v[76:79]
	v_mfma_f32_16x16x32_bf16 v[72:75], v[154:157], v[214:217], v[72:75]
	v_mfma_f32_16x16x32_bf16 v[124:127], v[150:153], v[188:191], v[124:127]
	v_mfma_f32_16x16x32_bf16 v[120:123], v[164:167], v[188:191], v[120:123]
	v_mfma_f32_16x16x32_bf16 v[108:111], v[150:153], v[196:199], v[108:111]
	v_mfma_f32_16x16x32_bf16 v[104:107], v[164:167], v[196:199], v[104:107]
	v_mfma_f32_16x16x32_bf16 v[92:95], v[150:153], v[210:213], v[92:95]
	v_mfma_f32_16x16x32_bf16 v[88:91], v[164:167], v[210:213], v[88:91]
	v_mfma_f32_16x16x32_bf16 v[76:79], v[150:153], v[218:221], v[76:79]
	v_mfma_f32_16x16x32_bf16 v[72:75], v[164:167], v[218:221], v[72:75]
	s_setprio 0
	s_setprio 1
	v_mfma_f32_16x16x32_bf16 v[116:119], v[168:171], v[184:187], v[116:119]
	v_mfma_f32_16x16x32_bf16 v[112:115], v[176:179], v[184:187], v[112:115]
	v_mfma_f32_16x16x32_bf16 v[100:103], v[168:171], v[192:195], v[100:103]
	v_mfma_f32_16x16x32_bf16 v[96:99], v[176:179], v[192:195], v[96:99]
	v_mfma_f32_16x16x32_bf16 v[84:87], v[168:171], v[206:209], v[84:87]
	v_mfma_f32_16x16x32_bf16 v[80:83], v[176:179], v[206:209], v[80:83]
	v_mfma_f32_16x16x32_bf16 v[68:71], v[168:171], v[214:217], v[68:71]
	v_mfma_f32_16x16x32_bf16 v[64:67], v[176:179], v[214:217], v[64:67]
	v_mfma_f32_16x16x32_bf16 v[116:119], v[172:175], v[188:191], v[116:119]
	v_mfma_f32_16x16x32_bf16 v[112:115], v[180:183], v[188:191], v[112:115]
	v_mfma_f32_16x16x32_bf16 v[100:103], v[172:175], v[196:199], v[100:103]
	v_mfma_f32_16x16x32_bf16 v[96:99], v[180:183], v[196:199], v[96:99]
	v_mfma_f32_16x16x32_bf16 v[84:87], v[172:175], v[210:213], v[84:87]
	v_mfma_f32_16x16x32_bf16 v[80:83], v[180:183], v[210:213], v[80:83]
	v_mfma_f32_16x16x32_bf16 v[68:71], v[172:175], v[218:221], v[68:71]
	v_mfma_f32_16x16x32_bf16 v[64:67], v[180:183], v[218:221], v[64:67]
	s_setprio 0
	s_barrier
	s_add_i32 s18, s20, s7
	v_lshl_add_u64 v[140:141], v[140:141], 0, s[76:77]
	s_mov_b32 m0, s18
	ds_read_b128 v[184:187], v144 offset:49152
	ds_read_b128 v[188:191], v144 offset:50176
	ds_read_b128 v[192:195], v144 offset:51200
	ds_read_b128 v[196:199], v144 offset:52224
	ds_read_b128 v[206:209], v144 offset:53248
	ds_read_b128 v[210:213], v144 offset:54272
	ds_read_b128 v[214:217], v144 offset:55296
	ds_read_b128 v[218:221], v144 offset:56320
	global_load_lds_dwordx4 v[140:141], off
	s_add_i32 m0, s18, 0x2000
	s_add_u32 s18, s50, 0x40080
	v_lshl_add_u64 v[140:141], v[158:159], 0, s[76:77]
	s_addc_u32 s19, s51, 0
	s_add_i32 s20, s21, s7
	global_load_lds_dwordx4 v[140:141], off
	v_lshl_add_u64 v[140:141], s[18:19], 0, v[132:133]
	s_mov_b32 m0, s20
	s_nop 0
	global_load_lds_dwordx4 v[140:141], off
	v_lshl_add_u64 v[140:141], s[18:19], 0, v[128:129]
	s_add_i32 m0, s20, 0x2000
	s_nop 0
	global_load_lds_dwordx4 v[140:141], off
	v_lshl_add_u64 v[140:141], v[200:201], 0, s[76:77]
	s_mov_b32 m0, s12
	s_nop 0
	global_load_lds_dwordx4 v[140:141], off
	v_lshl_add_u64 v[140:141], v[222:223], 0, s[76:77]
	s_mov_b32 m0, s13
	s_nop 0
	global_load_lds_dwordx4 v[140:141], off
	s_waitcnt vmcnt(8)
	s_waitcnt lgkmcnt(0)
	s_barrier
	s_setprio 1
	s_waitcnt lgkmcnt(0)
	v_mfma_f32_16x16x32_bf16 v[60:63], v[146:149], v[184:187], v[60:63]
	v_mfma_f32_16x16x32_bf16 v[56:59], v[154:157], v[184:187], v[56:59]
	v_mfma_f32_16x16x32_bf16 v[44:47], v[146:149], v[192:195], v[44:47]
	v_mfma_f32_16x16x32_bf16 v[40:43], v[154:157], v[192:195], v[40:43]
	v_mfma_f32_16x16x32_bf16 v[28:31], v[146:149], v[206:209], v[28:31]
	v_mfma_f32_16x16x32_bf16 v[24:27], v[154:157], v[206:209], v[24:27]
	v_mfma_f32_16x16x32_bf16 v[12:15], v[146:149], v[214:217], v[12:15]
	v_mfma_f32_16x16x32_bf16 v[8:11], v[154:157], v[214:217], v[8:11]
	v_mfma_f32_16x16x32_bf16 v[60:63], v[150:153], v[188:191], v[60:63]
	v_mfma_f32_16x16x32_bf16 v[56:59], v[164:167], v[188:191], v[56:59]
	v_mfma_f32_16x16x32_bf16 v[44:47], v[150:153], v[196:199], v[44:47]
	v_mfma_f32_16x16x32_bf16 v[40:43], v[164:167], v[196:199], v[40:43]
	v_mfma_f32_16x16x32_bf16 v[28:31], v[150:153], v[210:213], v[28:31]
	v_mfma_f32_16x16x32_bf16 v[24:27], v[164:167], v[210:213], v[24:27]
	v_mfma_f32_16x16x32_bf16 v[12:15], v[150:153], v[218:221], v[12:15]
	v_mfma_f32_16x16x32_bf16 v[8:11], v[164:167], v[218:221], v[8:11]
	s_setprio 0
	s_setprio 1
	v_mfma_f32_16x16x32_bf16 v[52:55], v[168:171], v[184:187], v[52:55]
	v_mfma_f32_16x16x32_bf16 v[48:51], v[176:179], v[184:187], v[48:51]
	v_mfma_f32_16x16x32_bf16 v[36:39], v[168:171], v[192:195], v[36:39]
	v_mfma_f32_16x16x32_bf16 v[32:35], v[176:179], v[192:195], v[32:35]
	v_mfma_f32_16x16x32_bf16 v[20:23], v[168:171], v[206:209], v[20:23]
	v_mfma_f32_16x16x32_bf16 v[16:19], v[176:179], v[206:209], v[16:19]
	v_mfma_f32_16x16x32_bf16 v[4:7], v[168:171], v[214:217], v[4:7]
	v_mfma_f32_16x16x32_bf16 v[0:3], v[176:179], v[214:217], v[0:3]
	v_mfma_f32_16x16x32_bf16 v[52:55], v[172:175], v[188:191], v[52:55]
	v_mfma_f32_16x16x32_bf16 v[48:51], v[180:183], v[188:191], v[48:51]
	v_mfma_f32_16x16x32_bf16 v[36:39], v[172:175], v[196:199], v[36:39]
	v_mfma_f32_16x16x32_bf16 v[32:35], v[180:183], v[196:199], v[32:35]
	v_mfma_f32_16x16x32_bf16 v[20:23], v[172:175], v[210:213], v[20:23]
	v_mfma_f32_16x16x32_bf16 v[16:19], v[180:183], v[210:213], v[16:19]
	v_mfma_f32_16x16x32_bf16 v[4:7], v[172:175], v[218:221], v[4:7]
	v_mfma_f32_16x16x32_bf16 v[0:3], v[180:183], v[218:221], v[0:3]
	s_setprio 0
	s_barrier
	s_add_i32 s63, s63, 2
	s_add_u32 s58, s58, 0x100
	s_addc_u32 s59, s59, 0
	s_add_u32 s47, s47, 0x100
	s_addc_u32 s62, s62, 0
	s_cmp_gt_u32 s63, 13
	s_cbranch_scc0 .LBB0_1138
	s_branch .Lpeel_x_1138
	.p2align 6

.LBB0_1209:
	s_add_u32 s54, s48, 0x100
	s_addc_u32 s60, s49, 0
	s_mov_b32 s61, -2
	s_add_u32 s48, s42, 0x100
	s_addc_u32 s49, s43, 0
	s_add_i32 s18, 0, 0x10000
	s_cmp_eq_u32 s61, 40
	s_cselect_b32 s59, s39, s49
	s_cselect_b32 s58, s38, s48
	s_cselect_b32 s51, s41, s60
	s_cselect_b32 s50, s40, s54
	s_add_i32 s20, 0, 0x14000
	v_add_u32_e32 v140, s18, v174
	v_add_u32_e32 v162, s20, v174
	ds_read_b128 v[128:131], v140
	ds_read_b128 v[132:135], v140 offset:1024
	ds_read_b128 v[136:139], v140 offset:2048
	ds_read_b128 v[140:143], v140 offset:3072
	ds_read_b128 v[156:159], v162
	ds_read_b128 v[164:167], v162 offset:1024
	ds_read_b128 v[168:171], v162 offset:2048
	ds_read_b128 v[176:179], v162 offset:3072
	v_lshl_add_u64 v[200:201], s[42:43], 0, v[152:153]
	s_add_i32 m0, s4, 0xc000
	ds_read_b128 v[180:183], v175
	ds_read_b128 v[184:187], v175 offset:1024
	ds_read_b128 v[188:191], v175 offset:2048
	ds_read_b128 v[192:195], v175 offset:3072
	ds_read_b128 v[196:199], v175 offset:4096
	ds_read_b128 v[206:209], v175 offset:5120
	ds_read_b128 v[210:213], v175 offset:6144
	ds_read_b128 v[214:217], v175 offset:7168
	global_load_lds_dwordx4 v[200:201], off
	v_lshl_add_u64 v[200:201], s[42:43], 0, v[154:155]
	s_add_i32 m0, s4, 0xe000
	s_nop 0
	global_load_lds_dwordx4 v[200:201], off
	s_waitcnt vmcnt(8)
	s_waitcnt lgkmcnt(0)
	s_barrier
	s_setprio 1
	s_waitcnt lgkmcnt(0)
	v_mfma_f32_16x16x32_bf16 v[124:127], v[128:131], v[180:183], 0
	v_mfma_f32_16x16x32_bf16 v[120:123], v[136:139], v[180:183], 0
	v_mfma_f32_16x16x32_bf16 v[112:115], v[128:131], v[188:191], 0
	v_mfma_f32_16x16x32_bf16 v[104:107], v[136:139], v[188:191], 0
	v_mfma_f32_16x16x32_bf16 v[96:99], v[128:131], v[196:199], 0
	v_mfma_f32_16x16x32_bf16 v[88:91], v[136:139], v[196:199], 0
	v_mfma_f32_16x16x32_bf16 v[80:83], v[128:131], v[210:213], 0
	v_mfma_f32_16x16x32_bf16 v[72:75], v[136:139], v[210:213], 0
	v_mfma_f32_16x16x32_bf16 v[124:127], v[132:135], v[184:187], v[124:127]
	v_mfma_f32_16x16x32_bf16 v[120:123], v[140:143], v[184:187], v[120:123]
	v_mfma_f32_16x16x32_bf16 v[112:115], v[132:135], v[192:195], v[112:115]
	v_mfma_f32_16x16x32_bf16 v[104:107], v[140:143], v[192:195], v[104:107]
	v_mfma_f32_16x16x32_bf16 v[96:99], v[132:135], v[206:209], v[96:99]
	v_mfma_f32_16x16x32_bf16 v[88:91], v[140:143], v[206:209], v[88:91]
	v_mfma_f32_16x16x32_bf16 v[80:83], v[132:135], v[214:217], v[80:83]
	v_mfma_f32_16x16x32_bf16 v[72:75], v[140:143], v[214:217], v[72:75]
	s_setprio 0
	s_setprio 1
	v_mfma_f32_16x16x32_bf16 v[116:119], v[156:159], v[180:183], 0
	v_mfma_f32_16x16x32_bf16 v[108:111], v[168:171], v[180:183], 0
	v_mfma_f32_16x16x32_bf16 v[100:103], v[156:159], v[188:191], 0
	v_mfma_f32_16x16x32_bf16 v[92:95], v[168:171], v[188:191], 0
	v_mfma_f32_16x16x32_bf16 v[84:87], v[156:159], v[196:199], 0
	v_mfma_f32_16x16x32_bf16 v[76:79], v[168:171], v[196:199], 0
	v_mfma_f32_16x16x32_bf16 v[68:71], v[156:159], v[210:213], 0
	v_mfma_f32_16x16x32_bf16 v[64:67], v[168:171], v[210:213], 0
	v_mfma_f32_16x16x32_bf16 v[116:119], v[164:167], v[184:187], v[116:119]
	v_mfma_f32_16x16x32_bf16 v[108:111], v[176:179], v[184:187], v[108:111]
	v_mfma_f32_16x16x32_bf16 v[100:103], v[164:167], v[192:195], v[100:103]
	v_mfma_f32_16x16x32_bf16 v[92:95], v[176:179], v[192:195], v[92:95]
	v_mfma_f32_16x16x32_bf16 v[84:87], v[164:167], v[206:209], v[84:87]
	v_mfma_f32_16x16x32_bf16 v[76:79], v[176:179], v[206:209], v[76:79]
	v_mfma_f32_16x16x32_bf16 v[68:71], v[164:167], v[214:217], v[68:71]
	v_mfma_f32_16x16x32_bf16 v[64:67], v[176:179], v[214:217], v[64:67]
	s_setprio 0
	s_barrier
	s_add_i32 s18, s18, s46
	v_lshl_add_u64 v[200:201], s[50:51], 0, v[148:149]
	s_mov_b32 m0, s18
	ds_read_b128 v[180:183], v175 offset:16384
	ds_read_b128 v[184:187], v175 offset:17408
	ds_read_b128 v[188:191], v175 offset:18432
	ds_read_b128 v[192:195], v175 offset:19456
	ds_read_b128 v[196:199], v175 offset:20480
	ds_read_b128 v[206:209], v175 offset:21504
	ds_read_b128 v[210:213], v175 offset:22528
	ds_read_b128 v[214:217], v175 offset:23552
	global_load_lds_dwordx4 v[200:201], off
	s_add_i32 m0, s18, 0x2000
	s_add_u32 s18, s50, 0xb0000
	v_lshl_add_u64 v[218:219], s[50:51], 0, v[144:145]
	s_addc_u32 s19, s51, 0
	s_add_i32 s20, s20, s46
	global_load_lds_dwordx4 v[218:219], off
	v_lshl_add_u64 v[220:221], s[18:19], 0, v[148:149]
	s_mov_b32 m0, s20
	v_lshl_add_u64 v[222:223], s[58:59], 0, v[146:147]
	global_load_lds_dwordx4 v[220:221], off
	v_lshl_add_u64 v[220:221], s[18:19], 0, v[144:145]
	s_add_i32 m0, s20, 0x2000
	s_nop 0
	global_load_lds_dwordx4 v[220:221], off
	v_lshl_add_u64 v[220:221], s[58:59], 0, v[150:151]
	s_mov_b32 m0, s4
	s_nop 0
	global_load_lds_dwordx4 v[220:221], off
	s_mov_b32 m0, s5
	s_nop 0
	global_load_lds_dwordx4 v[222:223], off
	s_waitcnt vmcnt(8)
	s_waitcnt lgkmcnt(0)
	s_barrier
	s_setprio 1
	s_waitcnt lgkmcnt(0)
	v_mfma_f32_16x16x32_bf16 v[60:63], v[128:131], v[180:183], 0
	v_mfma_f32_16x16x32_bf16 v[56:59], v[136:139], v[180:183], 0
	v_mfma_f32_16x16x32_bf16 v[48:51], v[128:131], v[188:191], 0
	v_mfma_f32_16x16x32_bf16 v[40:43], v[136:139], v[188:191], 0
	v_mfma_f32_16x16x32_bf16 v[32:35], v[128:131], v[196:199], 0
	v_mfma_f32_16x16x32_bf16 v[24:27], v[136:139], v[196:199], 0
	v_mfma_f32_16x16x32_bf16 v[16:19], v[128:131], v[210:213], 0
	v_mfma_f32_16x16x32_bf16 v[8:11], v[136:139], v[210:213], 0
	v_mfma_f32_16x16x32_bf16 v[60:63], v[132:135], v[184:187], v[60:63]
	v_mfma_f32_16x16x32_bf16 v[56:59], v[140:143], v[184:187], v[56:59]
	v_mfma_f32_16x16x32_bf16 v[48:51], v[132:135], v[192:195], v[48:51]
	v_mfma_f32_16x16x32_bf16 v[40:43], v[140:143], v[192:195], v[40:43]
	v_mfma_f32_16x16x32_bf16 v[32:35], v[132:135], v[206:209], v[32:35]
	v_mfma_f32_16x16x32_bf16 v[24:27], v[140:143], v[206:209], v[24:27]
	v_mfma_f32_16x16x32_bf16 v[16:19], v[132:135], v[214:217], v[16:19]
	v_mfma_f32_16x16x32_bf16 v[8:11], v[140:143], v[214:217], v[8:11]
	s_setprio 0
	s_setprio 1
	v_mfma_f32_16x16x32_bf16 v[52:55], v[156:159], v[180:183], 0
	v_mfma_f32_16x16x32_bf16 v[44:47], v[168:171], v[180:183], 0
	v_mfma_f32_16x16x32_bf16 v[36:39], v[156:159], v[188:191], 0
	v_mfma_f32_16x16x32_bf16 v[28:31], v[168:171], v[188:191], 0
	v_mfma_f32_16x16x32_bf16 v[20:23], v[156:159], v[196:199], 0
	v_mfma_f32_16x16x32_bf16 v[12:15], v[168:171], v[196:199], 0
	v_mfma_f32_16x16x32_bf16 v[4:7], v[156:159], v[210:213], 0
	v_mfma_f32_16x16x32_bf16 v[0:3], v[168:171], v[210:213], 0
	v_mfma_f32_16x16x32_bf16 v[52:55], v[164:167], v[184:187], v[52:55]
	v_mfma_f32_16x16x32_bf16 v[44:47], v[176:179], v[184:187], v[44:47]
	v_mfma_f32_16x16x32_bf16 v[36:39], v[164:167], v[192:195], v[36:39]
	v_mfma_f32_16x16x32_bf16 v[28:31], v[176:179], v[192:195], v[28:31]
	v_mfma_f32_16x16x32_bf16 v[20:23], v[164:167], v[206:209], v[20:23]
	v_mfma_f32_16x16x32_bf16 v[12:15], v[176:179], v[206:209], v[12:15]
	v_mfma_f32_16x16x32_bf16 v[4:7], v[164:167], v[214:217], v[4:7]
	v_mfma_f32_16x16x32_bf16 v[0:3], v[176:179], v[214:217], v[0:3]
	s_setprio 0
	s_barrier
	s_add_i32 s20, 0, 0x18000
	s_add_i32 s21, 0, 0x1c000
	v_add_u32_e32 v140, s20, v174
	v_add_u32_e32 v162, s21, v174
	ds_read_b128 v[128:131], v140
	ds_read_b128 v[132:135], v140 offset:1024
	ds_read_b128 v[136:139], v140 offset:2048
	ds_read_b128 v[140:143], v140 offset:3072
	ds_read_b128 v[156:159], v162
	ds_read_b128 v[164:167], v162 offset:1024
	ds_read_b128 v[168:171], v162 offset:2048
	ds_read_b128 v[176:179], v162 offset:3072
	s_add_u32 s18, s58, 0xb0000
	s_addc_u32 s19, s59, 0
	s_mov_b32 m0, s6
	v_lshl_add_u64 v[224:225], s[18:19], 0, v[150:151]
	ds_read_b128 v[180:183], v175 offset:32768
	ds_read_b128 v[184:187], v175 offset:33792
	ds_read_b128 v[188:191], v175 offset:34816
	ds_read_b128 v[192:195], v175 offset:35840
	ds_read_b128 v[196:199], v175 offset:36864
	ds_read_b128 v[206:209], v175 offset:37888
	ds_read_b128 v[210:213], v175 offset:38912
	ds_read_b128 v[214:217], v175 offset:39936
	global_load_lds_dwordx4 v[224:225], off
	v_lshl_add_u64 v[224:225], s[18:19], 0, v[146:147]
	s_mov_b32 m0, s7
	s_nop 0
	global_load_lds_dwordx4 v[224:225], off
	s_waitcnt vmcnt(8)
	s_waitcnt lgkmcnt(0)
	s_barrier
	s_setprio 1
	s_waitcnt lgkmcnt(0)
	v_mfma_f32_16x16x32_bf16 v[124:127], v[128:131], v[180:183], v[124:127]
	v_mfma_f32_16x16x32_bf16 v[120:123], v[136:139], v[180:183], v[120:123]
	v_mfma_f32_16x16x32_bf16 v[112:115], v[128:131], v[188:191], v[112:115]
	v_mfma_f32_16x16x32_bf16 v[104:107], v[136:139], v[188:191], v[104:107]
	v_mfma_f32_16x16x32_bf16 v[96:99], v[128:131], v[196:199], v[96:99]
	v_mfma_f32_16x16x32_bf16 v[88:91], v[136:139], v[196:199], v[88:91]
	v_mfma_f32_16x16x32_bf16 v[80:83], v[128:131], v[210:213], v[80:83]
	v_mfma_f32_16x16x32_bf16 v[72:75], v[136:139], v[210:213], v[72:75]
	v_mfma_f32_16x16x32_bf16 v[124:127], v[132:135], v[184:187], v[124:127]
	v_mfma_f32_16x16x32_bf16 v[120:123], v[140:143], v[184:187], v[120:123]
	v_mfma_f32_16x16x32_bf16 v[112:115], v[132:135], v[192:195], v[112:115]
	v_mfma_f32_16x16x32_bf16 v[104:107], v[140:143], v[192:195], v[104:107]
	v_mfma_f32_16x16x32_bf16 v[96:99], v[132:135], v[206:209], v[96:99]
	v_mfma_f32_16x16x32_bf16 v[88:91], v[140:143], v[206:209], v[88:91]
	v_mfma_f32_16x16x32_bf16 v[80:83], v[132:135], v[214:217], v[80:83]
	v_mfma_f32_16x16x32_bf16 v[72:75], v[140:143], v[214:217], v[72:75]
	s_setprio 0
	s_setprio 1
	v_mfma_f32_16x16x32_bf16 v[116:119], v[156:159], v[180:183], v[116:119]
	v_mfma_f32_16x16x32_bf16 v[108:111], v[168:171], v[180:183], v[108:111]
	v_mfma_f32_16x16x32_bf16 v[100:103], v[156:159], v[188:191], v[100:103]
	v_mfma_f32_16x16x32_bf16 v[92:95], v[168:171], v[188:191], v[92:95]
	v_mfma_f32_16x16x32_bf16 v[84:87], v[156:159], v[196:199], v[84:87]
	v_mfma_f32_16x16x32_bf16 v[76:79], v[168:171], v[196:199], v[76:79]
	v_mfma_f32_16x16x32_bf16 v[68:71], v[156:159], v[210:213], v[68:71]
	v_mfma_f32_16x16x32_bf16 v[64:67], v[168:171], v[210:213], v[64:67]
	v_mfma_f32_16x16x32_bf16 v[116:119], v[164:167], v[184:187], v[116:119]
	v_mfma_f32_16x16x32_bf16 v[108:111], v[176:179], v[184:187], v[108:111]
	v_mfma_f32_16x16x32_bf16 v[100:103], v[164:167], v[192:195], v[100:103]
	v_mfma_f32_16x16x32_bf16 v[92:95], v[176:179], v[192:195], v[92:95]
	v_mfma_f32_16x16x32_bf16 v[84:87], v[164:167], v[206:209], v[84:87]
	v_mfma_f32_16x16x32_bf16 v[76:79], v[176:179], v[206:209], v[76:79]
	v_mfma_f32_16x16x32_bf16 v[68:71], v[164:167], v[214:217], v[68:71]
	v_mfma_f32_16x16x32_bf16 v[64:67], v[176:179], v[214:217], v[64:67]
	s_setprio 0
	s_barrier
	s_add_i32 s18, s20, s46
	v_lshl_add_u64 v[200:201], v[200:201], 0, s[76:77]
	s_mov_b32 m0, s18
	ds_read_b128 v[180:183], v175 offset:49152
	ds_read_b128 v[184:187], v175 offset:50176
	ds_read_b128 v[188:191], v175 offset:51200
	ds_read_b128 v[192:195], v175 offset:52224
	ds_read_b128 v[196:199], v175 offset:53248
	ds_read_b128 v[206:209], v175 offset:54272
	ds_read_b128 v[210:213], v175 offset:55296
	ds_read_b128 v[214:217], v175 offset:56320
	global_load_lds_dwordx4 v[200:201], off
	s_add_i32 m0, s18, 0x2000
	s_add_u32 s18, s50, 0xb0080
	v_lshl_add_u64 v[200:201], v[218:219], 0, s[76:77]
	s_addc_u32 s19, s51, 0
	s_add_i32 s20, s21, s46
	global_load_lds_dwordx4 v[200:201], off
	v_lshl_add_u64 v[200:201], s[18:19], 0, v[148:149]
	s_mov_b32 m0, s20
	s_nop 0
	global_load_lds_dwordx4 v[200:201], off
	v_lshl_add_u64 v[200:201], s[18:19], 0, v[144:145]
	s_add_i32 m0, s20, 0x2000
	s_nop 0
	global_load_lds_dwordx4 v[200:201], off
	v_lshl_add_u64 v[200:201], v[220:221], 0, s[76:77]
	s_mov_b32 m0, s11
	s_nop 0
	global_load_lds_dwordx4 v[200:201], off
	v_lshl_add_u64 v[200:201], v[222:223], 0, s[76:77]
	s_mov_b32 m0, s12
	s_nop 0
	global_load_lds_dwordx4 v[200:201], off
	s_waitcnt vmcnt(8)
	s_waitcnt lgkmcnt(0)
	s_barrier
	s_setprio 1
	s_waitcnt lgkmcnt(0)
	v_mfma_f32_16x16x32_bf16 v[60:63], v[128:131], v[180:183], v[60:63]
	v_mfma_f32_16x16x32_bf16 v[56:59], v[136:139], v[180:183], v[56:59]
	v_mfma_f32_16x16x32_bf16 v[48:51], v[128:131], v[188:191], v[48:51]
	v_mfma_f32_16x16x32_bf16 v[40:43], v[136:139], v[188:191], v[40:43]
	v_mfma_f32_16x16x32_bf16 v[32:35], v[128:131], v[196:199], v[32:35]
	v_mfma_f32_16x16x32_bf16 v[24:27], v[136:139], v[196:199], v[24:27]
	v_mfma_f32_16x16x32_bf16 v[16:19], v[128:131], v[210:213], v[16:19]
	v_mfma_f32_16x16x32_bf16 v[8:11], v[136:139], v[210:213], v[8:11]
	v_mfma_f32_16x16x32_bf16 v[60:63], v[132:135], v[184:187], v[60:63]
	v_mfma_f32_16x16x32_bf16 v[56:59], v[140:143], v[184:187], v[56:59]
	v_mfma_f32_16x16x32_bf16 v[48:51], v[132:135], v[192:195], v[48:51]
	v_mfma_f32_16x16x32_bf16 v[40:43], v[140:143], v[192:195], v[40:43]
	v_mfma_f32_16x16x32_bf16 v[32:35], v[132:135], v[206:209], v[32:35]
	v_mfma_f32_16x16x32_bf16 v[24:27], v[140:143], v[206:209], v[24:27]
	v_mfma_f32_16x16x32_bf16 v[16:19], v[132:135], v[214:217], v[16:19]
	v_mfma_f32_16x16x32_bf16 v[8:11], v[140:143], v[214:217], v[8:11]
	s_setprio 0
	s_setprio 1
	v_mfma_f32_16x16x32_bf16 v[52:55], v[156:159], v[180:183], v[52:55]
	v_mfma_f32_16x16x32_bf16 v[44:47], v[168:171], v[180:183], v[44:47]
	v_mfma_f32_16x16x32_bf16 v[36:39], v[156:159], v[188:191], v[36:39]
	v_mfma_f32_16x16x32_bf16 v[28:31], v[168:171], v[188:191], v[28:31]
	v_mfma_f32_16x16x32_bf16 v[20:23], v[156:159], v[196:199], v[20:23]
	v_mfma_f32_16x16x32_bf16 v[12:15], v[168:171], v[196:199], v[12:15]
	v_mfma_f32_16x16x32_bf16 v[4:7], v[156:159], v[210:213], v[4:7]
	v_mfma_f32_16x16x32_bf16 v[0:3], v[168:171], v[210:213], v[0:3]
	v_mfma_f32_16x16x32_bf16 v[52:55], v[164:167], v[184:187], v[52:55]
	v_mfma_f32_16x16x32_bf16 v[44:47], v[176:179], v[184:187], v[44:47]
	v_mfma_f32_16x16x32_bf16 v[36:39], v[164:167], v[192:195], v[36:39]
	v_mfma_f32_16x16x32_bf16 v[28:31], v[176:179], v[192:195], v[28:31]
	v_mfma_f32_16x16x32_bf16 v[20:23], v[164:167], v[206:209], v[20:23]
	v_mfma_f32_16x16x32_bf16 v[12:15], v[176:179], v[206:209], v[12:15]
	v_mfma_f32_16x16x32_bf16 v[4:7], v[164:167], v[214:217], v[4:7]
	v_mfma_f32_16x16x32_bf16 v[0:3], v[176:179], v[214:217], v[0:3]
	s_setprio 0
	s_barrier
	s_add_i32 s61, s61, 2
	s_add_u32 s54, s54, 0x100
	s_addc_u32 s60, s60, 0
	s_cmp_gt_u32 s61, 41
	s_mov_b64 s[42:43], s[48:49]
	s_cbranch_scc0 .LBB0_1210
	s_branch .Lpeel_x_1210
	.p2align 6

.LBB0_1234:
	s_add_u32 s43, s58, 0x100
	s_addc_u32 s46, s59, 0
	s_mov_b32 s47, -2
	s_add_u32 s58, s48, 0x100
	s_addc_u32 s59, s49, 0
	s_add_i32 s18, 0, 0x10000
	s_cmp_eq_u32 s47, 18
	s_cselect_b32 s61, s39, s59
	s_cselect_b32 s60, s38, s58
	v_add_u32_e32 v158, s18, v152
	s_cselect_b32 s51, s41, s46
	s_cselect_b32 s50, s40, s43
	s_add_i32 s20, 0, 0x14000
	ds_read_b128 v[154:157], v158
	ds_read_b128 v[164:167], v158 offset:1024
	ds_read_b128 v[168:171], v158 offset:2048
	ds_read_b128 v[172:175], v158 offset:3072
	v_add_u32_e32 v158, s20, v152
	ds_read_b128 v[176:179], v158
	ds_read_b128 v[180:183], v158 offset:1024
	ds_read_b128 v[184:187], v158 offset:2048
	ds_read_b128 v[188:191], v158 offset:3072
	v_lshl_add_u64 v[158:159], s[48:49], 0, v[148:149]
	s_add_i32 m0, s5, 0xc000
	ds_read_b128 v[192:195], v153
	ds_read_b128 v[196:199], v153 offset:1024
	ds_read_b128 v[206:209], v153 offset:2048
	ds_read_b128 v[210:213], v153 offset:3072
	ds_read_b128 v[214:217], v153 offset:4096
	ds_read_b128 v[218:221], v153 offset:5120
	ds_read_b128 v[222:225], v153 offset:6144
	ds_read_b128 v[226:229], v153 offset:7168
	global_load_lds_dwordx4 v[158:159], off
	v_lshl_add_u64 v[158:159], s[48:49], 0, v[150:151]
	s_add_i32 m0, s5, 0xe000
	s_nop 0
	global_load_lds_dwordx4 v[158:159], off
	s_waitcnt vmcnt(8)
	s_waitcnt lgkmcnt(0)
	s_barrier
	s_setprio 1
	s_waitcnt lgkmcnt(0)
	v_mfma_f32_16x16x32_bf16 v[124:127], v[154:157], v[192:195], 0
	v_mfma_f32_16x16x32_bf16 v[120:123], v[168:171], v[192:195], 0
	v_mfma_f32_16x16x32_bf16 v[116:119], v[154:157], v[206:209], 0
	v_mfma_f32_16x16x32_bf16 v[112:115], v[168:171], v[206:209], 0
	v_mfma_f32_16x16x32_bf16 v[108:111], v[154:157], v[214:217], 0
	v_mfma_f32_16x16x32_bf16 v[104:107], v[168:171], v[214:217], 0
	v_mfma_f32_16x16x32_bf16 v[96:99], v[154:157], v[222:225], 0
	v_mfma_f32_16x16x32_bf16 v[88:91], v[168:171], v[222:225], 0
	v_mfma_f32_16x16x32_bf16 v[124:127], v[164:167], v[196:199], v[124:127]
	v_mfma_f32_16x16x32_bf16 v[120:123], v[172:175], v[196:199], v[120:123]
	v_mfma_f32_16x16x32_bf16 v[116:119], v[164:167], v[210:213], v[116:119]
	v_mfma_f32_16x16x32_bf16 v[112:115], v[172:175], v[210:213], v[112:115]
	v_mfma_f32_16x16x32_bf16 v[108:111], v[164:167], v[218:221], v[108:111]
	v_mfma_f32_16x16x32_bf16 v[104:107], v[172:175], v[218:221], v[104:107]
	v_mfma_f32_16x16x32_bf16 v[96:99], v[164:167], v[226:229], v[96:99]
	v_mfma_f32_16x16x32_bf16 v[88:91], v[172:175], v[226:229], v[88:91]
	s_setprio 0
	s_setprio 1
	v_mfma_f32_16x16x32_bf16 v[100:103], v[176:179], v[192:195], 0
	v_mfma_f32_16x16x32_bf16 v[92:95], v[184:187], v[192:195], 0
	v_mfma_f32_16x16x32_bf16 v[84:87], v[176:179], v[206:209], 0
	v_mfma_f32_16x16x32_bf16 v[80:83], v[184:187], v[206:209], 0
	v_mfma_f32_16x16x32_bf16 v[76:79], v[176:179], v[214:217], 0
	v_mfma_f32_16x16x32_bf16 v[72:75], v[184:187], v[214:217], 0
	v_mfma_f32_16x16x32_bf16 v[68:71], v[176:179], v[222:225], 0
	v_mfma_f32_16x16x32_bf16 v[64:67], v[184:187], v[222:225], 0
	v_mfma_f32_16x16x32_bf16 v[100:103], v[180:183], v[196:199], v[100:103]
	v_mfma_f32_16x16x32_bf16 v[92:95], v[188:191], v[196:199], v[92:95]
	v_mfma_f32_16x16x32_bf16 v[84:87], v[180:183], v[210:213], v[84:87]
	v_mfma_f32_16x16x32_bf16 v[80:83], v[188:191], v[210:213], v[80:83]
	v_mfma_f32_16x16x32_bf16 v[76:79], v[180:183], v[218:221], v[76:79]
	v_mfma_f32_16x16x32_bf16 v[72:75], v[188:191], v[218:221], v[72:75]
	v_mfma_f32_16x16x32_bf16 v[68:71], v[180:183], v[226:229], v[68:71]
	v_mfma_f32_16x16x32_bf16 v[64:67], v[188:191], v[226:229], v[64:67]
	s_setprio 0
	s_barrier
	s_add_i32 s18, s18, s4
	v_lshl_add_u64 v[158:159], s[50:51], 0, v[130:131]
	s_mov_b32 m0, s18
	ds_read_b128 v[192:195], v153 offset:16384
	ds_read_b128 v[196:199], v153 offset:17408
	ds_read_b128 v[206:209], v153 offset:18432
	ds_read_b128 v[210:213], v153 offset:19456
	ds_read_b128 v[214:217], v153 offset:20480
	ds_read_b128 v[218:221], v153 offset:21504
	ds_read_b128 v[222:225], v153 offset:22528
	ds_read_b128 v[226:229], v153 offset:23552
	global_load_lds_dwordx4 v[158:159], off
	s_add_i32 m0, s18, 0x2000
	s_add_u32 s18, s50, 0xb0000
	v_lshl_add_u64 v[200:201], s[50:51], 0, v[128:129]
	s_addc_u32 s19, s51, 0
	s_add_i32 s20, s20, s4
	global_load_lds_dwordx4 v[200:201], off
	v_lshl_add_u64 v[230:231], s[18:19], 0, v[130:131]
	s_mov_b32 m0, s20
	v_lshl_add_u64 v[232:233], s[60:61], 0, v[128:129]
	global_load_lds_dwordx4 v[230:231], off
	v_lshl_add_u64 v[230:231], s[18:19], 0, v[128:129]
	s_add_i32 m0, s20, 0x2000
	s_nop 0
	global_load_lds_dwordx4 v[230:231], off
	v_lshl_add_u64 v[230:231], s[60:61], 0, v[130:131]
	s_mov_b32 m0, s5
	s_nop 0
	global_load_lds_dwordx4 v[230:231], off
	s_mov_b32 m0, s6
	s_nop 0
	global_load_lds_dwordx4 v[232:233], off
	s_waitcnt vmcnt(8)
	s_waitcnt lgkmcnt(0)
	s_barrier
	s_setprio 1
	s_waitcnt lgkmcnt(0)
	v_mfma_f32_16x16x32_bf16 v[60:63], v[154:157], v[192:195], 0
	v_mfma_f32_16x16x32_bf16 v[56:59], v[168:171], v[192:195], 0
	v_mfma_f32_16x16x32_bf16 v[52:55], v[154:157], v[206:209], 0
	v_mfma_f32_16x16x32_bf16 v[48:51], v[168:171], v[206:209], 0
	v_mfma_f32_16x16x32_bf16 v[44:47], v[154:157], v[214:217], 0
	v_mfma_f32_16x16x32_bf16 v[40:43], v[168:171], v[214:217], 0
	v_mfma_f32_16x16x32_bf16 v[32:35], v[154:157], v[222:225], 0
	v_mfma_f32_16x16x32_bf16 v[24:27], v[168:171], v[222:225], 0
	v_mfma_f32_16x16x32_bf16 v[60:63], v[164:167], v[196:199], v[60:63]
	v_mfma_f32_16x16x32_bf16 v[56:59], v[172:175], v[196:199], v[56:59]
	v_mfma_f32_16x16x32_bf16 v[52:55], v[164:167], v[210:213], v[52:55]
	v_mfma_f32_16x16x32_bf16 v[48:51], v[172:175], v[210:213], v[48:51]
	v_mfma_f32_16x16x32_bf16 v[44:47], v[164:167], v[218:221], v[44:47]
	v_mfma_f32_16x16x32_bf16 v[40:43], v[172:175], v[218:221], v[40:43]
	v_mfma_f32_16x16x32_bf16 v[32:35], v[164:167], v[226:229], v[32:35]
	v_mfma_f32_16x16x32_bf16 v[24:27], v[172:175], v[226:229], v[24:27]
	s_setprio 0
	s_setprio 1
	v_mfma_f32_16x16x32_bf16 v[36:39], v[176:179], v[192:195], 0
	v_mfma_f32_16x16x32_bf16 v[28:31], v[184:187], v[192:195], 0
	v_mfma_f32_16x16x32_bf16 v[20:23], v[176:179], v[206:209], 0
	v_mfma_f32_16x16x32_bf16 v[16:19], v[184:187], v[206:209], 0
	v_mfma_f32_16x16x32_bf16 v[12:15], v[176:179], v[214:217], 0
	v_mfma_f32_16x16x32_bf16 v[8:11], v[184:187], v[214:217], 0
	v_mfma_f32_16x16x32_bf16 v[4:7], v[176:179], v[222:225], 0
	v_mfma_f32_16x16x32_bf16 v[0:3], v[184:187], v[222:225], 0
	v_mfma_f32_16x16x32_bf16 v[36:39], v[180:183], v[196:199], v[36:39]
	v_mfma_f32_16x16x32_bf16 v[28:31], v[188:191], v[196:199], v[28:31]
	v_mfma_f32_16x16x32_bf16 v[20:23], v[180:183], v[210:213], v[20:23]
	v_mfma_f32_16x16x32_bf16 v[16:19], v[188:191], v[210:213], v[16:19]
	v_mfma_f32_16x16x32_bf16 v[12:15], v[180:183], v[218:221], v[12:15]
	v_mfma_f32_16x16x32_bf16 v[8:11], v[188:191], v[218:221], v[8:11]
	v_mfma_f32_16x16x32_bf16 v[4:7], v[180:183], v[226:229], v[4:7]
	v_mfma_f32_16x16x32_bf16 v[0:3], v[188:191], v[226:229], v[0:3]
	s_setprio 0
	s_barrier
	s_add_i32 s20, 0, 0x18000
	s_add_i32 s21, 0, 0x1c000
	v_add_u32_e32 v172, s20, v152
	v_add_u32_e32 v188, s21, v152
	ds_read_b128 v[154:157], v172
	ds_read_b128 v[164:167], v172 offset:1024
	ds_read_b128 v[168:171], v172 offset:2048
	ds_read_b128 v[172:175], v172 offset:3072
	ds_read_b128 v[176:179], v188
	ds_read_b128 v[180:183], v188 offset:1024
	ds_read_b128 v[184:187], v188 offset:2048
	ds_read_b128 v[188:191], v188 offset:3072
	s_add_u32 s18, s60, 0xb0000
	s_addc_u32 s19, s61, 0
	s_mov_b32 m0, s7
	v_lshl_add_u64 v[234:235], s[18:19], 0, v[130:131]
	ds_read_b128 v[192:195], v153 offset:32768
	ds_read_b128 v[196:199], v153 offset:33792
	ds_read_b128 v[206:209], v153 offset:34816
	ds_read_b128 v[210:213], v153 offset:35840
	ds_read_b128 v[214:217], v153 offset:36864
	ds_read_b128 v[218:221], v153 offset:37888
	ds_read_b128 v[222:225], v153 offset:38912
	ds_read_b128 v[226:229], v153 offset:39936
	global_load_lds_dwordx4 v[234:235], off
	v_lshl_add_u64 v[234:235], s[18:19], 0, v[128:129]
	s_mov_b32 m0, s8
	s_nop 0
	global_load_lds_dwordx4 v[234:235], off
	s_waitcnt vmcnt(8)
	s_waitcnt lgkmcnt(0)
	s_barrier
	s_setprio 1
	s_waitcnt lgkmcnt(0)
	v_mfma_f32_16x16x32_bf16 v[124:127], v[154:157], v[192:195], v[124:127]
	v_mfma_f32_16x16x32_bf16 v[120:123], v[168:171], v[192:195], v[120:123]
	v_mfma_f32_16x16x32_bf16 v[116:119], v[154:157], v[206:209], v[116:119]
	v_mfma_f32_16x16x32_bf16 v[112:115], v[168:171], v[206:209], v[112:115]
	v_mfma_f32_16x16x32_bf16 v[108:111], v[154:157], v[214:217], v[108:111]
	v_mfma_f32_16x16x32_bf16 v[104:107], v[168:171], v[214:217], v[104:107]
	v_mfma_f32_16x16x32_bf16 v[96:99], v[154:157], v[222:225], v[96:99]
	v_mfma_f32_16x16x32_bf16 v[88:91], v[168:171], v[222:225], v[88:91]
	v_mfma_f32_16x16x32_bf16 v[124:127], v[164:167], v[196:199], v[124:127]
	v_mfma_f32_16x16x32_bf16 v[120:123], v[172:175], v[196:199], v[120:123]
	v_mfma_f32_16x16x32_bf16 v[116:119], v[164:167], v[210:213], v[116:119]
	v_mfma_f32_16x16x32_bf16 v[112:115], v[172:175], v[210:213], v[112:115]
	v_mfma_f32_16x16x32_bf16 v[108:111], v[164:167], v[218:221], v[108:111]
	v_mfma_f32_16x16x32_bf16 v[104:107], v[172:175], v[218:221], v[104:107]
	v_mfma_f32_16x16x32_bf16 v[96:99], v[164:167], v[226:229], v[96:99]
	v_mfma_f32_16x16x32_bf16 v[88:91], v[172:175], v[226:229], v[88:91]
	s_setprio 0
	s_setprio 1
	v_mfma_f32_16x16x32_bf16 v[100:103], v[176:179], v[192:195], v[100:103]
	v_mfma_f32_16x16x32_bf16 v[92:95], v[184:187], v[192:195], v[92:95]
	v_mfma_f32_16x16x32_bf16 v[84:87], v[176:179], v[206:209], v[84:87]
	v_mfma_f32_16x16x32_bf16 v[80:83], v[184:187], v[206:209], v[80:83]
	v_mfma_f32_16x16x32_bf16 v[76:79], v[176:179], v[214:217], v[76:79]
	v_mfma_f32_16x16x32_bf16 v[72:75], v[184:187], v[214:217], v[72:75]
	v_mfma_f32_16x16x32_bf16 v[68:71], v[176:179], v[222:225], v[68:71]
	v_mfma_f32_16x16x32_bf16 v[64:67], v[184:187], v[222:225], v[64:67]
	v_mfma_f32_16x16x32_bf16 v[100:103], v[180:183], v[196:199], v[100:103]
	v_mfma_f32_16x16x32_bf16 v[92:95], v[188:191], v[196:199], v[92:95]
	v_mfma_f32_16x16x32_bf16 v[84:87], v[180:183], v[210:213], v[84:87]
	v_mfma_f32_16x16x32_bf16 v[80:83], v[188:191], v[210:213], v[80:83]
	v_mfma_f32_16x16x32_bf16 v[76:79], v[180:183], v[218:221], v[76:79]
	v_mfma_f32_16x16x32_bf16 v[72:75], v[188:191], v[218:221], v[72:75]
	v_mfma_f32_16x16x32_bf16 v[68:71], v[180:183], v[226:229], v[68:71]
	v_mfma_f32_16x16x32_bf16 v[64:67], v[188:191], v[226:229], v[64:67]
	s_setprio 0
	s_barrier
	s_add_i32 s18, s20, s4
	v_lshl_add_u64 v[158:159], v[158:159], 0, s[76:77]
	s_mov_b32 m0, s18
	ds_read_b128 v[192:195], v153 offset:49152
	ds_read_b128 v[196:199], v153 offset:50176
	ds_read_b128 v[206:209], v153 offset:51200
	ds_read_b128 v[210:213], v153 offset:52224
	ds_read_b128 v[214:217], v153 offset:53248
	ds_read_b128 v[218:221], v153 offset:54272
	ds_read_b128 v[222:225], v153 offset:55296
	ds_read_b128 v[226:229], v153 offset:56320
	global_load_lds_dwordx4 v[158:159], off
	s_add_i32 m0, s18, 0x2000
	s_add_u32 s18, s50, 0xb0080
	v_lshl_add_u64 v[158:159], v[200:201], 0, s[76:77]
	s_addc_u32 s19, s51, 0
	s_add_i32 s20, s21, s4
	global_load_lds_dwordx4 v[158:159], off
	v_lshl_add_u64 v[158:159], s[18:19], 0, v[130:131]
	s_mov_b32 m0, s20
	s_nop 0
	global_load_lds_dwordx4 v[158:159], off
	v_lshl_add_u64 v[158:159], s[18:19], 0, v[128:129]
	s_add_i32 m0, s20, 0x2000
	s_nop 0
	global_load_lds_dwordx4 v[158:159], off
	v_lshl_add_u64 v[158:159], v[230:231], 0, s[76:77]
	s_mov_b32 m0, s9
	s_nop 0
	global_load_lds_dwordx4 v[158:159], off
	v_lshl_add_u64 v[158:159], v[232:233], 0, s[76:77]
	s_mov_b32 m0, s10
	s_nop 0
	global_load_lds_dwordx4 v[158:159], off
	s_waitcnt vmcnt(8)
	s_waitcnt lgkmcnt(0)
	s_barrier
	s_setprio 1
	s_waitcnt lgkmcnt(0)
	v_mfma_f32_16x16x32_bf16 v[60:63], v[154:157], v[192:195], v[60:63]
	v_mfma_f32_16x16x32_bf16 v[56:59], v[168:171], v[192:195], v[56:59]
	v_mfma_f32_16x16x32_bf16 v[52:55], v[154:157], v[206:209], v[52:55]
	v_mfma_f32_16x16x32_bf16 v[48:51], v[168:171], v[206:209], v[48:51]
	v_mfma_f32_16x16x32_bf16 v[44:47], v[154:157], v[214:217], v[44:47]
	v_mfma_f32_16x16x32_bf16 v[40:43], v[168:171], v[214:217], v[40:43]
	v_mfma_f32_16x16x32_bf16 v[32:35], v[154:157], v[222:225], v[32:35]
	v_mfma_f32_16x16x32_bf16 v[24:27], v[168:171], v[222:225], v[24:27]
	v_mfma_f32_16x16x32_bf16 v[60:63], v[164:167], v[196:199], v[60:63]
	v_mfma_f32_16x16x32_bf16 v[56:59], v[172:175], v[196:199], v[56:59]
	v_mfma_f32_16x16x32_bf16 v[52:55], v[164:167], v[210:213], v[52:55]
	v_mfma_f32_16x16x32_bf16 v[48:51], v[172:175], v[210:213], v[48:51]
	v_mfma_f32_16x16x32_bf16 v[44:47], v[164:167], v[218:221], v[44:47]
	v_mfma_f32_16x16x32_bf16 v[40:43], v[172:175], v[218:221], v[40:43]
	v_mfma_f32_16x16x32_bf16 v[32:35], v[164:167], v[226:229], v[32:35]
	v_mfma_f32_16x16x32_bf16 v[24:27], v[172:175], v[226:229], v[24:27]
	s_setprio 0
	s_setprio 1
	v_mfma_f32_16x16x32_bf16 v[36:39], v[176:179], v[192:195], v[36:39]
	v_mfma_f32_16x16x32_bf16 v[28:31], v[184:187], v[192:195], v[28:31]
	v_mfma_f32_16x16x32_bf16 v[20:23], v[176:179], v[206:209], v[20:23]
	v_mfma_f32_16x16x32_bf16 v[16:19], v[184:187], v[206:209], v[16:19]
	v_mfma_f32_16x16x32_bf16 v[12:15], v[176:179], v[214:217], v[12:15]
	v_mfma_f32_16x16x32_bf16 v[8:11], v[184:187], v[214:217], v[8:11]
	v_mfma_f32_16x16x32_bf16 v[4:7], v[176:179], v[222:225], v[4:7]
	v_mfma_f32_16x16x32_bf16 v[0:3], v[184:187], v[222:225], v[0:3]
	v_mfma_f32_16x16x32_bf16 v[36:39], v[180:183], v[196:199], v[36:39]
	v_mfma_f32_16x16x32_bf16 v[28:31], v[188:191], v[196:199], v[28:31]
	v_mfma_f32_16x16x32_bf16 v[20:23], v[180:183], v[210:213], v[20:23]
	v_mfma_f32_16x16x32_bf16 v[16:19], v[188:191], v[210:213], v[16:19]
	v_mfma_f32_16x16x32_bf16 v[12:15], v[180:183], v[218:221], v[12:15]
	v_mfma_f32_16x16x32_bf16 v[8:11], v[188:191], v[218:221], v[8:11]
	v_mfma_f32_16x16x32_bf16 v[4:7], v[180:183], v[226:229], v[4:7]
	v_mfma_f32_16x16x32_bf16 v[0:3], v[188:191], v[226:229], v[0:3]
	s_setprio 0
	s_barrier
	s_add_i32 s47, s47, 2
	s_add_u32 s43, s43, 0x100
	s_addc_u32 s46, s46, 0
	s_cmp_gt_u32 s47, 19
	s_mov_b64 s[48:49], s[58:59]
	s_cbranch_scc0 .LBB0_1235
	s_branch .Lpeel_x_1235
	.p2align 6
